# cache policy: weight-transpose and conv stores nt (GEMM outputs stay write-through); compare with v69/v70
# speedup vs baseline: 1.0155x; 1.0033x over previous
; #define LAS __attribute__((address_space(3)))
; __device__ __forceinline__ void lds_wait() { asm volatile("s_waitcnt lgkmcnt(0)" ::: "memory"); }
; __device__ __forceinline__ void transpose_item(const float* W, int K, int N, bf16_t* WT, int gate, const float* kscale, LAS float* scr, int item, int lane) {
;     const int nblk = N / 64, kb = item / nblk, nb = item % nblk, k0 = 64 * kb, n0 = 64 * nb;
;     const int c4 = (lane & 15) * 4, kr = lane >> 4;
;     f32x4 v[16];
; #pragma unroll
;     for (int i = 0; i < 16; ++i) v[i] = __builtin_nontemporal_load((const f32x4*)(W + (size_t)(k0 + 4 * i + kr) * N + n0 + c4));
; #pragma unroll
;     for (int i = 0; i < 16; ++i) { LAS float* d = scr + (4 * i + kr) * 65 + c4; d[0] = v[i][0]; d[1] = v[i][1]; d[2] = v[i][2]; d[3] = v[i][3]; }
;     lds_wait();
.LBB0_24:
	s_mul_hi_i32 s5, s4, 0x2aaaaaab
	s_lshr_b32 s6, s5, 31
	s_ashr_i32 s5, s5, 4
	s_add_i32 s5, s5, s6
	s_lshl_b32 s6, s5, 6
	s_mulk_i32 s5, 0xe800
	s_add_i32 s8, s0, s5
	v_add_u32_e32 v52, s6, v21
	s_ashr_i32 s9, s8, 31
	s_ashr_i32 s7, s6, 31
	v_add_u32_e32 v54, 4, v52
	v_add_u32_e32 v56, 8, v52
	v_add_u32_e32 v58, 12, v52
	v_add_u32_e32 v59, 16, v52
	v_add_u32_e32 v62, 20, v52
	v_add_u32_e32 v63, 24, v52
	v_add_u32_e32 v66, 28, v52
	v_add_u32_e32 v67, 32, v52
	v_add_u32_e32 v70, 36, v52
	v_add_u32_e32 v71, 40, v52
	v_add_u32_e32 v74, 44, v52
	v_add_u32_e32 v75, 48, v52
	v_add_u32_e32 v78, 52, v52
	v_add_u32_e32 v79, 56, v52
	v_add_u32_e32 v82, 60, v52
	v_add_u32_e32 v48, s8, v6
	v_lshl_add_u64 v[50:51], s[8:9], 2, v[0:1]
	v_lshl_add_u64 v[112:113], s[6:7], 1, v[2:3]
	v_ashrrev_i32_e32 v49, 31, v48
	v_mad_i64_i32 v[52:53], s[6:7], v52, s1, v[50:51]
	v_mad_i64_i32 v[54:55], s[6:7], v54, s1, v[50:51]
	v_mad_i64_i32 v[56:57], s[6:7], v56, s1, v[50:51]
	v_mad_i64_i32 v[60:61], s[6:7], v58, s1, v[50:51]
	v_mad_i64_i32 v[64:65], s[6:7], v59, s1, v[50:51]
	v_mad_i64_i32 v[68:69], s[6:7], v62, s1, v[50:51]
	v_mad_i64_i32 v[72:73], s[6:7], v63, s1, v[50:51]
	v_mad_i64_i32 v[76:77], s[6:7], v66, s1, v[50:51]
	v_mad_i64_i32 v[80:81], s[6:7], v67, s1, v[50:51]
	v_mad_i64_i32 v[84:85], s[6:7], v70, s1, v[50:51]
	v_mad_i64_i32 v[88:89], s[6:7], v71, s1, v[50:51]
	v_mad_i64_i32 v[92:93], s[6:7], v74, s1, v[50:51]
	v_mad_i64_i32 v[96:97], s[6:7], v75, s1, v[50:51]
	v_mad_i64_i32 v[100:101], s[6:7], v78, s1, v[50:51]
	v_mad_i64_i32 v[104:105], s[6:7], v79, s1, v[50:51]
	v_mad_i64_i32 v[108:109], s[6:7], v82, s1, v[50:51]
	v_add_u32_e32 v114, 8, v48
	v_add_u32_e32 v116, 16, v48
	v_add_u32_e32 v118, 24, v48
	v_add_u32_e32 v120, 32, v48
	v_add_u32_e32 v122, 40, v48
	v_add_u32_e32 v124, 48, v48
	v_add_u32_e32 v126, 56, v48
	v_lshlrev_b64 v[128:129], 12, v[48:49]
	global_load_dwordx4 v[48:51], v[52:53], off nt
	s_nop 0
	global_load_dwordx4 v[52:55], v[54:55], off nt
	s_nop 0
	global_load_dwordx4 v[56:59], v[56:57], off nt
	s_nop 0
	global_load_dwordx4 v[60:63], v[60:61], off nt
	s_nop 0
	global_load_dwordx4 v[64:67], v[64:65], off nt
	s_nop 0
	global_load_dwordx4 v[68:71], v[68:69], off nt
	s_nop 0
	global_load_dwordx4 v[72:75], v[72:73], off nt
	s_nop 0
	global_load_dwordx4 v[76:79], v[76:77], off nt
	s_nop 0
	global_load_dwordx4 v[80:83], v[80:81], off nt
	s_nop 0
	global_load_dwordx4 v[84:87], v[84:85], off nt
	s_nop 0
	global_load_dwordx4 v[88:91], v[88:89], off nt
	s_nop 0
	global_load_dwordx4 v[92:95], v[92:93], off nt
	s_nop 0
	global_load_dwordx4 v[96:99], v[96:97], off nt
	s_nop 0
	global_load_dwordx4 v[100:103], v[100:101], off nt
	s_nop 0
	global_load_dwordx4 v[104:107], v[104:105], off nt
	s_nop 0
	global_load_dwordx4 v[108:111], v[108:109], off nt
	v_add_u32_e32 v130, 0x38e8, v11
	v_add_u32_e32 v131, 0x3cf0, v11
	v_add_u32_e32 v132, 0x3cf8, v11
	v_ashrrev_i32_e32 v115, 31, v114
	v_ashrrev_i32_e32 v117, 31, v116
	v_ashrrev_i32_e32 v119, 31, v118
	v_ashrrev_i32_e32 v121, 31, v120
	v_ashrrev_i32_e32 v123, 31, v122
	v_ashrrev_i32_e32 v125, 31, v124
	v_ashrrev_i32_e32 v127, 31, v126
	v_lshlrev_b64 v[114:115], 12, v[114:115]
	v_lshlrev_b64 v[116:117], 12, v[116:117]
	v_lshlrev_b64 v[118:119], 12, v[118:119]
	v_lshlrev_b64 v[120:121], 12, v[120:121]
	v_lshlrev_b64 v[122:123], 12, v[122:123]
	v_lshlrev_b64 v[124:125], 12, v[124:125]
	v_lshlrev_b64 v[126:127], 12, v[126:127]
	v_add_u32_e32 v133, 0x400, v7
	s_waitcnt vmcnt(15)
	ds_write2_b32 v11, v48, v49 offset1:1
	ds_write2_b32 v11, v50, v51 offset0:2 offset1:3
	s_waitcnt vmcnt(14)
	ds_write2_b32 v12, v52, v53 offset1:1
	ds_write2_b32 v13, v54, v55 offset1:1
	s_waitcnt vmcnt(13)
	ds_write2_b32 v14, v56, v57 offset1:1
	ds_write2_b32 v15, v58, v59 offset1:1
	s_waitcnt vmcnt(12)
	ds_write2_b32 v16, v60, v61 offset1:1
	ds_write2_b32 v17, v62, v63 offset1:1
	s_waitcnt vmcnt(11)
	ds_write2_b32 v18, v64, v65 offset1:1
	ds_write2_b32 v19, v66, v67 offset1:1
	s_waitcnt vmcnt(10)
	ds_write2_b32 v29, v68, v69 offset1:1
	ds_write2_b32 v30, v70, v71 offset1:1
	s_waitcnt vmcnt(9)
	ds_write2_b32 v31, v72, v73 offset1:1
	ds_write2_b32 v32, v74, v75 offset1:1
	s_waitcnt vmcnt(8)
	ds_write2_b32 v33, v76, v77 offset1:1
	ds_write2_b32 v34, v78, v79 offset1:1
	s_waitcnt vmcnt(7)
	ds_write2_b32 v35, v80, v81 offset1:1
	ds_write2_b32 v36, v82, v83 offset1:1
	s_waitcnt vmcnt(6)
	ds_write2_b32 v37, v84, v85 offset1:1
	ds_write2_b32 v38, v86, v87 offset1:1
	s_waitcnt vmcnt(5)
; #define LAS __attribute__((address_space(3)))
; __device__ __forceinline__ void transpose_item(const float* W, int K, int N, bf16_t* WT, int gate, const float* kscale, LAS float* scr, int item, int lane) {
;     ...
;     const int c = lane & 7;
;     f32x4 k0v = {1.f, 1.f, 1.f, 1.f}, k1v = k0v;
;     if (kscale) { k0v = *(const f32x4*)(kscale + k0 + 8 * c); k1v = *(const f32x4*)(kscale + k0 + 8 * c + 4); }
; #pragma unroll
;     for (int j = 0; j < 8; ++j) { const int n = (lane >> 3) + 8 * j; const LAS float* s = scr + (8 * c) * 65 + n;
;         u32x4 o; o.x = pk2(s[0 * 65] * k0v[0], s[1 * 65] * k0v[1]); o.y = pk2(s[2 * 65] * k0v[2], s[3 * 65] * k0v[3]); o.z = pk2(s[4 * 65] * k1v[0], s[5 * 65] * k1v[1]); o.w = pk2(s[6 * 65] * k1v[2], s[7 * 65] * k1v[3]);
;         const int nn = n0 + n; const int row = gate < 0 ? nn : (256 * (nn >> 7) + 128 * gate + (nn & 127));
;         *(u32x4*)(WT + (size_t)row * K + k0 + 8 * c) = o; }
	ds_write2_b32 v39, v88, v89 offset1:1
	ds_write2_b32 v40, v90, v91 offset1:1
	s_waitcnt vmcnt(4)
	ds_write2_b32 v41, v92, v93 offset1:1
	ds_write2_b32 v42, v94, v95 offset1:1
	s_waitcnt vmcnt(3)
	ds_write2_b32 v43, v96, v97 offset1:1
	ds_write2_b32 v44, v98, v99 offset1:1
	s_waitcnt vmcnt(2)
	ds_write2_b32 v45, v100, v101 offset1:1
	ds_write2_b32 v46, v102, v103 offset1:1
	s_waitcnt vmcnt(1)
	ds_write2_b32 v47, v104, v105 offset1:1
	ds_write2_b32 v130, v106, v107 offset1:1
	s_waitcnt vmcnt(0)
	ds_write2_b32 v131, v108, v109 offset1:1
	ds_write2_b32 v132, v110, v111 offset1:1
	s_waitcnt lgkmcnt(0)
	v_lshl_add_u64 v[128:129], v[112:113], 0, v[128:129]
	v_lshl_add_u64 v[114:115], v[112:113], 0, v[114:115]
	v_lshl_add_u64 v[116:117], v[112:113], 0, v[116:117]
	v_lshl_add_u64 v[118:119], v[112:113], 0, v[118:119]
	v_lshl_add_u64 v[120:121], v[112:113], 0, v[120:121]
	v_lshl_add_u64 v[122:123], v[112:113], 0, v[122:123]
	v_lshl_add_u64 v[124:125], v[112:113], 0, v[124:125]
	v_lshl_add_u64 v[112:113], v[112:113], 0, v[126:127]
	ds_read2_b32 v[52:53], v7 offset0:65 offset1:73
	ds_read2_b32 v[54:55], v7 offset1:8
	ds_read2_b32 v[56:57], v7 offset0:130 offset1:138
	ds_read2_b32 v[58:59], v7 offset0:195 offset1:203
	ds_read2_b32 v[60:61], v133 offset0:4 offset1:12
	ds_read2_b32 v[62:63], v133 offset0:69 offset1:77
	ds_read2_b32 v[64:65], v133 offset0:134 offset1:142
	ds_read2_b32 v[66:67], v133 offset0:199 offset1:207
	ds_read2_b32 v[68:69], v7 offset0:81 offset1:89
	ds_read2_b32 v[70:71], v7 offset0:16 offset1:24
	ds_read2_b32 v[72:73], v7 offset0:146 offset1:154
	ds_read2_b32 v[74:75], v7 offset0:211 offset1:219
	ds_read2_b32 v[76:77], v133 offset0:20 offset1:28
	ds_read2_b32 v[78:79], v133 offset0:85 offset1:93
	ds_read2_b32 v[80:81], v133 offset0:150 offset1:158
	ds_read2_b32 v[82:83], v133 offset0:215 offset1:223
	ds_read2_b32 v[84:85], v7 offset0:32 offset1:40
	ds_read2_b32 v[86:87], v7 offset0:97 offset1:105
	ds_read2_b32 v[88:89], v7 offset0:162 offset1:170
	ds_read2_b32 v[90:91], v7 offset0:227 offset1:235
	ds_read2_b32 v[92:93], v133 offset0:36 offset1:44
	ds_read2_b32 v[94:95], v133 offset0:101 offset1:109
	ds_read2_b32 v[96:97], v133 offset0:166 offset1:174
	ds_read2_b32 v[98:99], v133 offset0:231 offset1:239
	ds_read2_b32 v[100:101], v7 offset0:48 offset1:56
	ds_read2_b32 v[102:103], v7 offset0:113 offset1:121
	ds_read2_b32 v[104:105], v7 offset0:178 offset1:186
	ds_read2_b32 v[106:107], v7 offset0:243 offset1:251
	ds_read2_b32 v[108:109], v133 offset0:52 offset1:60
	ds_read2_b32 v[110:111], v133 offset0:117 offset1:125
	ds_read2_b32 v[126:127], v133 offset0:182 offset1:190
	ds_read2_b32 v[130:131], v133 offset0:247 offset1:255
	s_waitcnt lgkmcnt(14)
	v_cvt_pk_bf16_f32 v48, v54, v52
	v_cvt_pk_bf16_f32 v49, v56, v58
	v_cvt_pk_bf16_f32 v50, v60, v62
	v_cvt_pk_bf16_f32 v51, v64, v66
	v_cvt_pk_bf16_f32 v52, v55, v53
	v_cvt_pk_bf16_f32 v53, v57, v59
	v_cvt_pk_bf16_f32 v54, v61, v63
	v_cvt_pk_bf16_f32 v55, v65, v67
	v_cvt_pk_bf16_f32 v56, v70, v68
	v_cvt_pk_bf16_f32 v57, v72, v74
	v_cvt_pk_bf16_f32 v58, v76, v78
	v_cvt_pk_bf16_f32 v59, v80, v82
	v_cvt_pk_bf16_f32 v60, v71, v69
	v_cvt_pk_bf16_f32 v61, v73, v75
	v_cvt_pk_bf16_f32 v62, v77, v79
	v_cvt_pk_bf16_f32 v63, v81, v83
	v_cvt_pk_bf16_f32 v64, v84, v86
	s_waitcnt lgkmcnt(12)
	v_cvt_pk_bf16_f32 v65, v88, v90
	v_cvt_pk_bf16_f32 v68, v85, v87
	v_cvt_pk_bf16_f32 v69, v89, v91
	s_waitcnt lgkmcnt(10)
	v_cvt_pk_bf16_f32 v66, v92, v94
	v_cvt_pk_bf16_f32 v70, v93, v95
	s_waitcnt lgkmcnt(8)
	v_cvt_pk_bf16_f32 v67, v96, v98
	v_cvt_pk_bf16_f32 v71, v97, v99
	s_waitcnt lgkmcnt(6)
	v_cvt_pk_bf16_f32 v72, v100, v102
	s_waitcnt lgkmcnt(4)
	v_cvt_pk_bf16_f32 v73, v104, v106
	v_cvt_pk_bf16_f32 v76, v101, v103
	v_cvt_pk_bf16_f32 v77, v105, v107
	s_waitcnt lgkmcnt(2)
	v_cvt_pk_bf16_f32 v74, v108, v110
	v_cvt_pk_bf16_f32 v78, v109, v111
	s_waitcnt lgkmcnt(0)
	v_cvt_pk_bf16_f32 v75, v126, v130
	v_cvt_pk_bf16_f32 v79, v127, v131
	global_store_dwordx4 v[128:129], v[48:51], off nt
	global_store_dwordx4 v[114:115], v[52:55], off nt
	global_store_dwordx4 v[116:117], v[56:59], off nt
	global_store_dwordx4 v[118:119], v[60:63], off nt
	global_store_dwordx4 v[120:121], v[64:67], off nt
	global_store_dwordx4 v[122:123], v[68:71], off nt
	global_store_dwordx4 v[124:125], v[72:75], off nt
	global_store_dwordx4 v[112:113], v[76:79], off nt
	s_waitcnt lgkmcnt(0)
	s_add_i32 s4, s4, s92
	s_add_i32 s0, s0, s38
	s_cmpk_lt_i32 s4, 0xc00
	s_cbranch_scc1 .LBB0_24
	v_mov_b32_e32 v29, v6

; #define LAS __attribute__((address_space(3)))
; __device__ __forceinline__ void lds_wait() { asm volatile("s_waitcnt lgkmcnt(0)" ::: "memory"); }
; __device__ __forceinline__ void transpose_item(const float* W, int K, int N, bf16_t* WT, int gate, const float* kscale, LAS float* scr, int item, int lane) {
;     const int nblk = N / 64, kb = item / nblk, nb = item % nblk, k0 = 64 * kb, n0 = 64 * nb;
;     const int c4 = (lane & 15) * 4, kr = lane >> 4;
;     f32x4 v[16];
; #pragma unroll
;     for (int i = 0; i < 16; ++i) v[i] = __builtin_nontemporal_load((const f32x4*)(W + (size_t)(k0 + 4 * i + kr) * N + n0 + c4));
; #pragma unroll
;     for (int i = 0; i < 16; ++i) { LAS float* d = scr + (4 * i + kr) * 65 + c4; d[0] = v[i][0]; d[1] = v[i][1]; d[2] = v[i][2]; d[3] = v[i][3]; }
;     lds_wait();
.LBB0_30:
	s_ashr_i32 s19, s18, 31
	s_lshr_b32 s19, s19, 30
	s_add_i32 s19, s18, s19
	s_ashr_i32 s19, s19, 2
	s_lshl_b32 s20, s19, 6
	s_lshl_b32 s21, s19, 8
	v_add_u32_e32 v78, s20, v21
	s_lshl_b32 s19, s19, 9
	s_sub_i32 s22, s13, s21
	v_add_u32_e32 v80, 4, v78
	v_add_u32_e32 v82, 8, v78
	v_add_u32_e32 v84, 12, v78
	v_add_u32_e32 v86, 16, v78
	v_add_u32_e32 v88, 20, v78
	v_add_u32_e32 v90, 24, v78
	v_add_u32_e32 v92, 28, v78
	v_add_u32_e32 v94, 32, v78
	v_add_u32_e32 v96, 36, v78
	v_add_u32_e32 v98, 40, v78
	v_add_u32_e32 v100, 44, v78
	v_add_u32_e32 v102, 48, v78
	v_add_u32_e32 v104, 52, v78
	v_add_u32_e32 v106, 56, v78
	v_add_u32_e32 v108, 60, v78
	s_sub_i32 s19, s12, s19
	s_ashr_i32 s23, s22, 31
	v_ashrrev_i32_e32 v79, 31, v78
	v_add_u32_e32 v112, s22, v29
	v_add_u32_e32 v113, s22, v22
	v_add_u32_e32 v116, s22, v23
	v_add_u32_e32 v118, s22, v24
	v_add_u32_e32 v120, s22, v25
	v_add_u32_e32 v122, s22, v26
	v_add_u32_e32 v124, s22, v27
	v_add_u32_e32 v126, s22, v28
	v_ashrrev_i32_e32 v81, 31, v80
	v_ashrrev_i32_e32 v83, 31, v82
	v_ashrrev_i32_e32 v85, 31, v84
	v_ashrrev_i32_e32 v87, 31, v86
	v_ashrrev_i32_e32 v89, 31, v88
	v_ashrrev_i32_e32 v91, 31, v90
	v_ashrrev_i32_e32 v93, 31, v92
	v_ashrrev_i32_e32 v95, 31, v94
	v_ashrrev_i32_e32 v97, 31, v96
	v_ashrrev_i32_e32 v99, 31, v98
	v_ashrrev_i32_e32 v101, 31, v100
	v_ashrrev_i32_e32 v103, 31, v102
	v_ashrrev_i32_e32 v105, 31, v104
	v_ashrrev_i32_e32 v107, 31, v106
	v_ashrrev_i32_e32 v109, 31, v108
	v_add_u32_e32 v114, s19, v39
	v_add_u32_e32 v115, s19, v19
	v_add_u32_e32 v117, s19, v18
	v_add_u32_e32 v119, s19, v17
	v_add_u32_e32 v121, s19, v16
	v_add_u32_e32 v123, s19, v15
	v_add_u32_e32 v125, s19, v14
	v_add_u32_e32 v127, s19, v11
	v_lshl_add_u64 v[110:111], s[22:23], 2, v[12:13]
	v_lshlrev_b64 v[78:79], 10, v[78:79]
	v_and_b32_e32 v128, 0x7f, v112
	v_and_b32_e32 v129, 0x7f, v113
	v_and_b32_e32 v116, 0x7f, v116
	v_and_b32_e32 v118, 0x7f, v118
	v_and_b32_e32 v120, 0x7f, v120
	v_and_b32_e32 v122, 0x7f, v122
	v_and_b32_e32 v124, 0x7f, v124
	v_and_b32_e32 v126, 0x7f, v126
	v_lshlrev_b64 v[112:113], 10, v[80:81]
	v_lshlrev_b64 v[82:83], 10, v[82:83]
	v_lshlrev_b64 v[84:85], 10, v[84:85]
	v_lshlrev_b64 v[86:87], 10, v[86:87]
	v_lshlrev_b64 v[88:89], 10, v[88:89]
	v_lshlrev_b64 v[90:91], 10, v[90:91]
	v_lshlrev_b64 v[92:93], 10, v[92:93]
	v_lshlrev_b64 v[94:95], 10, v[94:95]
	v_lshlrev_b64 v[96:97], 10, v[96:97]
	v_lshlrev_b64 v[98:99], 10, v[98:99]
	v_lshlrev_b64 v[100:101], 10, v[100:101]
	v_lshlrev_b64 v[102:103], 10, v[102:103]
	v_lshlrev_b64 v[104:105], 10, v[104:105]
	v_lshlrev_b64 v[106:107], 10, v[106:107]
	v_lshlrev_b64 v[108:109], 10, v[108:109]
	v_lshl_add_u64 v[78:79], v[110:111], 0, v[78:79]
	v_and_or_b32 v144, v114, s10, v128
	v_and_or_b32 v146, v115, s10, v129
	v_and_or_b32 v148, v117, s10, v116
	v_and_or_b32 v150, v119, s10, v118
	v_and_or_b32 v152, v121, s10, v120
	v_and_or_b32 v154, v123, s10, v122
	v_and_or_b32 v156, v125, s10, v124
	v_and_or_b32 v158, v127, s10, v126
	v_lshl_add_u64 v[112:113], v[110:111], 0, v[112:113]
	v_lshl_add_u64 v[114:115], v[110:111], 0, v[82:83]
	v_lshl_add_u64 v[116:117], v[110:111], 0, v[84:85]
	v_lshl_add_u64 v[118:119], v[110:111], 0, v[86:87]
	v_lshl_add_u64 v[120:121], v[110:111], 0, v[88:89]
	v_lshl_add_u64 v[122:123], v[110:111], 0, v[90:91]
	v_lshl_add_u64 v[124:125], v[110:111], 0, v[92:93]
	v_lshl_add_u64 v[126:127], v[110:111], 0, v[94:95]
	v_lshl_add_u64 v[128:129], v[110:111], 0, v[96:97]
	v_lshl_add_u64 v[130:131], v[110:111], 0, v[98:99]
	v_lshl_add_u64 v[132:133], v[110:111], 0, v[100:101]
	v_lshl_add_u64 v[134:135], v[110:111], 0, v[102:103]
	v_lshl_add_u64 v[136:137], v[110:111], 0, v[104:105]
	v_lshl_add_u64 v[138:139], v[110:111], 0, v[106:107]
	v_lshl_add_u64 v[140:141], v[110:111], 0, v[108:109]
	global_load_dwordx4 v[78:81], v[78:79], off nt
	s_nop 0
	global_load_dwordx4 v[82:85], v[112:113], off nt
	global_load_dwordx4 v[86:89], v[114:115], off nt
	global_load_dwordx4 v[90:93], v[116:117], off nt
	global_load_dwordx4 v[94:97], v[118:119], off nt
	global_load_dwordx4 v[98:101], v[120:121], off nt
	global_load_dwordx4 v[102:105], v[122:123], off nt
	global_load_dwordx4 v[106:109], v[124:125], off nt
	global_load_dwordx4 v[110:113], v[126:127], off nt
	global_load_dwordx4 v[114:117], v[128:129], off nt
	s_nop 0
	global_load_dwordx4 v[118:121], v[130:131], off nt
	global_load_dwordx4 v[122:125], v[132:133], off nt
	global_load_dwordx4 v[126:129], v[134:135], off nt
	s_nop 0
	global_load_dwordx4 v[130:133], v[136:137], off nt
	s_nop 0
	global_load_dwordx4 v[134:137], v[138:139], off nt
	s_nop 0
	global_load_dwordx4 v[138:141], v[140:141], off nt
	v_add_u32_e32 v64, 0x34d0, v30
	v_add_u32_e32 v65, 0x34d8, v30
	v_add_u32_e32 v66, 0x38e0, v30
	v_add_u32_e32 v67, 0x38e8, v30
	v_add_u32_e32 v68, 0x3cf0, v30
	v_add_u32_e32 v69, 0x3cf8, v30
	s_waitcnt vmcnt(15)
	ds_write2_b32 v30, v78, v79 offset1:1
	ds_write2_b32 v30, v80, v81 offset0:2 offset1:3
	s_waitcnt vmcnt(14)
	ds_write2_b32 v40, v82, v83 offset1:1
	ds_write2_b32 v41, v84, v85 offset1:1
	s_waitcnt vmcnt(13)
	ds_write2_b32 v42, v86, v87 offset1:1
	ds_write2_b32 v43, v88, v89 offset1:1
	s_waitcnt vmcnt(12)
	ds_write2_b32 v44, v90, v91 offset1:1
	ds_write2_b32 v45, v92, v93 offset1:1
	s_waitcnt vmcnt(11)
	ds_write2_b32 v46, v94, v95 offset1:1
	ds_write2_b32 v47, v96, v97 offset1:1
	s_waitcnt vmcnt(10)
	ds_write2_b32 v48, v98, v99 offset1:1
	ds_write2_b32 v49, v100, v101 offset1:1
	s_waitcnt vmcnt(9)
	ds_write2_b32 v50, v102, v103 offset1:1
	ds_write2_b32 v51, v104, v105 offset1:1
	s_waitcnt vmcnt(8)
	ds_write2_b32 v52, v106, v107 offset1:1
	ds_write2_b32 v53, v108, v109 offset1:1
	s_waitcnt vmcnt(7)
; #define LAS __attribute__((address_space(3)))
; __device__ __forceinline__ void transpose_item(const float* W, int K, int N, bf16_t* WT, int gate, const float* kscale, LAS float* scr, int item, int lane) {
;     ...
;     const int c = lane & 7;
;     f32x4 k0v = {1.f, 1.f, 1.f, 1.f}, k1v = k0v;
;     if (kscale) { k0v = *(const f32x4*)(kscale + k0 + 8 * c); k1v = *(const f32x4*)(kscale + k0 + 8 * c + 4); }
; #pragma unroll
;     for (int j = 0; j < 8; ++j) { const int n = (lane >> 3) + 8 * j; const LAS float* s = scr + (8 * c) * 65 + n;
;         u32x4 o; o.x = pk2(s[0 * 65] * k0v[0], s[1 * 65] * k0v[1]); o.y = pk2(s[2 * 65] * k0v[2], s[3 * 65] * k0v[3]); o.z = pk2(s[4 * 65] * k1v[0], s[5 * 65] * k1v[1]); o.w = pk2(s[6 * 65] * k1v[2], s[7 * 65] * k1v[3]);
;         const int nn = n0 + n; const int row = gate < 0 ? nn : (256 * (nn >> 7) + 128 * gate + (nn & 127));
;         *(u32x4*)(WT + (size_t)row * K + k0 + 8 * c) = o; }
	ds_write2_b32 v54, v110, v111 offset1:1
	ds_write2_b32 v55, v112, v113 offset1:1
	s_waitcnt vmcnt(6)
	ds_write2_b32 v56, v114, v115 offset1:1
	ds_write2_b32 v57, v116, v117 offset1:1
	s_waitcnt vmcnt(5)
	ds_write2_b32 v58, v118, v119 offset1:1
	ds_write2_b32 v59, v120, v121 offset1:1
	s_waitcnt vmcnt(4)
	ds_write2_b32 v60, v122, v123 offset1:1
	ds_write2_b32 v61, v124, v125 offset1:1
	s_waitcnt vmcnt(3)
	ds_write2_b32 v62, v126, v127 offset1:1
	ds_write2_b32 v63, v128, v129 offset1:1
	s_waitcnt vmcnt(2)
	ds_write2_b32 v64, v130, v131 offset1:1
	ds_write2_b32 v65, v132, v133 offset1:1
	s_waitcnt vmcnt(1)
	ds_write2_b32 v66, v134, v135 offset1:1
	ds_write2_b32 v67, v136, v137 offset1:1
	s_waitcnt vmcnt(0)
	ds_write2_b32 v68, v138, v139 offset1:1
	ds_write2_b32 v69, v140, v141 offset1:1
	s_waitcnt lgkmcnt(0)
	v_add_u32_e32 v70, 0x400, v31
	v_add_u32_e32 v71, 0x400, v32
	v_add_u32_e32 v72, 0x400, v33
	v_add_u32_e32 v73, 0x400, v34
	v_add_u32_e32 v74, 0x400, v35
	v_add_u32_e32 v75, 0x400, v36
	v_add_u32_e32 v76, 0x400, v37
	v_add_u32_e32 v77, 0x400, v38
	ds_read2_b32 v[78:79], v31 offset1:65
	ds_read2_b32 v[80:81], v31 offset0:130 offset1:195
	ds_read2_b32 v[82:83], v70 offset0:4 offset1:69
	ds_read2_b32 v[84:85], v70 offset0:134 offset1:199
	ds_read2_b32 v[86:87], v32 offset1:65
	ds_read2_b32 v[88:89], v32 offset0:130 offset1:195
	ds_read2_b32 v[90:91], v71 offset0:4 offset1:69
	ds_read2_b32 v[92:93], v71 offset0:134 offset1:199
	ds_read2_b32 v[94:95], v33 offset1:65
	ds_read2_b32 v[96:97], v33 offset0:130 offset1:195
	ds_read2_b32 v[98:99], v72 offset0:4 offset1:69
	ds_read2_b32 v[100:101], v72 offset0:134 offset1:199
	ds_read2_b32 v[102:103], v34 offset1:65
	ds_read2_b32 v[104:105], v34 offset0:130 offset1:195
	ds_read2_b32 v[106:107], v73 offset0:4 offset1:69
	ds_read2_b32 v[108:109], v73 offset0:134 offset1:199
	ds_read2_b32 v[110:111], v35 offset1:65
	ds_read2_b32 v[112:113], v35 offset0:130 offset1:195
	ds_read2_b32 v[114:115], v74 offset0:4 offset1:69
	ds_read2_b32 v[116:117], v74 offset0:134 offset1:199
	ds_read2_b32 v[118:119], v36 offset1:65
	ds_read2_b32 v[120:121], v36 offset0:130 offset1:195
	ds_read2_b32 v[122:123], v75 offset0:4 offset1:69
	ds_read2_b32 v[124:125], v75 offset0:134 offset1:199
	ds_read2_b32 v[126:127], v37 offset1:65
	ds_read2_b32 v[128:129], v37 offset0:130 offset1:195
	ds_read2_b32 v[130:131], v76 offset0:4 offset1:69
	ds_read2_b32 v[132:133], v76 offset0:134 offset1:199
	ds_read2_b32 v[134:135], v38 offset1:65
	ds_read2_b32 v[136:137], v38 offset0:130 offset1:195
	ds_read2_b32 v[138:139], v77 offset0:4 offset1:69
	ds_read2_b32 v[140:141], v77 offset0:134 offset1:199
	s_ashr_i32 s21, s20, 31
	v_ashrrev_i32_e32 v145, 31, v144
	v_lshl_add_u64 v[142:143], s[20:21], 1, v[6:7]
	v_ashrrev_i32_e32 v147, 31, v146
	v_ashrrev_i32_e32 v149, 31, v148
	v_ashrrev_i32_e32 v151, 31, v150
	v_ashrrev_i32_e32 v153, 31, v152
	v_ashrrev_i32_e32 v155, 31, v154
	v_ashrrev_i32_e32 v157, 31, v156
	v_ashrrev_i32_e32 v159, 31, v158
	v_lshlrev_b64 v[144:145], 9, v[144:145]
	v_lshlrev_b64 v[146:147], 9, v[146:147]
	v_lshlrev_b64 v[148:149], 9, v[148:149]
	v_lshlrev_b64 v[150:151], 9, v[150:151]
	v_lshlrev_b64 v[152:153], 9, v[152:153]
	v_lshlrev_b64 v[154:155], 9, v[154:155]
	v_lshlrev_b64 v[156:157], 9, v[156:157]
	v_lshlrev_b64 v[158:159], 9, v[158:159]
	v_lshl_add_u64 v[144:145], v[142:143], 0, v[144:145]
	s_waitcnt lgkmcnt(14)
	v_cvt_pk_bf16_f32 v78, v78, v79
	v_cvt_pk_bf16_f32 v79, v80, v81
	v_cvt_pk_bf16_f32 v80, v82, v83
	v_cvt_pk_bf16_f32 v81, v84, v85
	v_lshl_add_u64 v[146:147], v[142:143], 0, v[146:147]
	v_lshl_add_u64 v[148:149], v[142:143], 0, v[148:149]
	v_lshl_add_u64 v[150:151], v[142:143], 0, v[150:151]
	v_lshl_add_u64 v[152:153], v[142:143], 0, v[152:153]
	v_lshl_add_u64 v[154:155], v[142:143], 0, v[154:155]
	v_lshl_add_u64 v[156:157], v[142:143], 0, v[156:157]
	v_lshl_add_u64 v[142:143], v[142:143], 0, v[158:159]
	v_cvt_pk_bf16_f32 v82, v86, v87
	v_cvt_pk_bf16_f32 v83, v88, v89
	v_cvt_pk_bf16_f32 v84, v90, v91
	v_cvt_pk_bf16_f32 v85, v92, v93
	v_cvt_pk_bf16_f32 v86, v94, v95
	v_cvt_pk_bf16_f32 v87, v96, v97
	v_cvt_pk_bf16_f32 v88, v98, v99
	v_cvt_pk_bf16_f32 v89, v100, v101
	v_cvt_pk_bf16_f32 v90, v102, v103
	v_cvt_pk_bf16_f32 v91, v104, v105
	v_cvt_pk_bf16_f32 v92, v106, v107
	v_cvt_pk_bf16_f32 v93, v108, v109
	v_cvt_pk_bf16_f32 v94, v110, v111
	v_cvt_pk_bf16_f32 v95, v112, v113
	s_waitcnt lgkmcnt(13)
	v_cvt_pk_bf16_f32 v96, v114, v115
	s_waitcnt lgkmcnt(12)
	v_cvt_pk_bf16_f32 v97, v116, v117
	s_waitcnt lgkmcnt(11)
	v_cvt_pk_bf16_f32 v98, v118, v119
	s_waitcnt lgkmcnt(10)
	v_cvt_pk_bf16_f32 v99, v120, v121
	s_waitcnt lgkmcnt(9)
	v_cvt_pk_bf16_f32 v100, v122, v123
	s_waitcnt lgkmcnt(8)
	v_cvt_pk_bf16_f32 v101, v124, v125
	s_waitcnt lgkmcnt(7)
	v_cvt_pk_bf16_f32 v102, v126, v127
	s_waitcnt lgkmcnt(6)
	v_cvt_pk_bf16_f32 v103, v128, v129
	s_waitcnt lgkmcnt(5)
	v_cvt_pk_bf16_f32 v104, v130, v131
	s_waitcnt lgkmcnt(4)
	v_cvt_pk_bf16_f32 v105, v132, v133
	s_waitcnt lgkmcnt(3)
	v_cvt_pk_bf16_f32 v106, v134, v135
	s_waitcnt lgkmcnt(2)
	v_cvt_pk_bf16_f32 v107, v136, v137
	s_waitcnt lgkmcnt(1)
	v_cvt_pk_bf16_f32 v108, v138, v139
	s_waitcnt lgkmcnt(0)
	v_cvt_pk_bf16_f32 v109, v140, v141
	global_store_dwordx4 v[144:145], v[78:81], off nt
	global_store_dwordx4 v[146:147], v[82:85], off nt
	global_store_dwordx4 v[148:149], v[86:89], off nt
	global_store_dwordx4 v[150:151], v[90:93], off nt
	global_store_dwordx4 v[152:153], v[94:97], off nt
	global_store_dwordx4 v[154:155], v[98:101], off nt
	global_store_dwordx4 v[156:157], v[102:105], off nt
	global_store_dwordx4 v[142:143], v[106:109], off nt
	s_waitcnt lgkmcnt(0)
	s_add_i32 s18, s18, s92
	s_add_i32 s13, s13, s38
	s_add_i32 s12, s12, s3
	s_cmp_lt_i32 s18, 16
	s_cbranch_scc1 .LBB0_30
	v_lshl_add_u64 v[12:13], s[6:7], 2, v[2:3]
	s_mov_b32 s6, s9
	s_mov_b32 s7, s8
	s_mov_b32 s12, s54
; #define LAS __attribute__((address_space(3)))
; __device__ __forceinline__ void lds_wait() { asm volatile("s_waitcnt lgkmcnt(0)" ::: "memory"); }
; __device__ __forceinline__ void transpose_item(const float* W, int K, int N, bf16_t* WT, int gate, const float* kscale, LAS float* scr, int item, int lane) {
;     const int nblk = N / 64, kb = item / nblk, nb = item % nblk, k0 = 64 * kb, n0 = 64 * nb;
;     const int c4 = (lane & 15) * 4, kr = lane >> 4;
;     f32x4 v[16];
; #pragma unroll
;     for (int i = 0; i < 16; ++i) v[i] = __builtin_nontemporal_load((const f32x4*)(W + (size_t)(k0 + 4 * i + kr) * N + n0 + c4));
; #pragma unroll
;     for (int i = 0; i < 16; ++i) { LAS float* d = scr + (4 * i + kr) * 65 + c4; d[0] = v[i][0]; d[1] = v[i][1]; d[2] = v[i][2]; d[3] = v[i][3]; }
;     lds_wait();
.LBB0_32:
	s_ashr_i32 s13, s12, 31
	s_lshr_b32 s13, s13, 30
	s_add_i32 s13, s12, s13
	s_ashr_i32 s13, s13, 2
	s_lshl_b32 s18, s13, 6
	s_lshl_b32 s19, s13, 8
	s_lshl_b32 s13, s13, 9
	v_add_u32_e32 v78, s18, v21
	s_sub_i32 s20, s7, s19
	s_sub_i32 s13, s6, s13
	v_add_u32_e32 v80, 4, v78
	v_add_u32_e32 v82, 8, v78
	v_add_u32_e32 v84, 12, v78
	v_add_u32_e32 v86, 16, v78
	v_add_u32_e32 v88, 20, v78
	v_add_u32_e32 v90, 24, v78
	v_add_u32_e32 v92, 28, v78
	v_add_u32_e32 v94, 32, v78
	v_add_u32_e32 v96, 36, v78
	v_add_u32_e32 v98, 40, v78
	v_add_u32_e32 v100, 44, v78
	v_add_u32_e32 v102, 48, v78
	v_add_u32_e32 v104, 52, v78
	v_add_u32_e32 v106, 56, v78
	v_add_u32_e32 v108, 60, v78
	s_ashr_i32 s21, s20, 31
	v_ashrrev_i32_e32 v79, 31, v78
	v_add_u32_e32 v112, s20, v29
	v_add_u32_e32 v113, s13, v39
	v_add_u32_e32 v114, s20, v22
	v_add_u32_e32 v115, s13, v19
	v_add_u32_e32 v116, s20, v23
	v_add_u32_e32 v117, s13, v18
	v_add_u32_e32 v118, s20, v24
	v_add_u32_e32 v119, s13, v17
	v_add_u32_e32 v120, s20, v25
	v_add_u32_e32 v121, s13, v16
	v_add_u32_e32 v122, s20, v26
	v_add_u32_e32 v123, s13, v15
	v_add_u32_e32 v124, s20, v27
	v_add_u32_e32 v125, s13, v14
	v_add_u32_e32 v126, s20, v28
	v_add_u32_e32 v127, s13, v11
	v_ashrrev_i32_e32 v81, 31, v80
	v_ashrrev_i32_e32 v83, 31, v82
	v_ashrrev_i32_e32 v85, 31, v84
	v_ashrrev_i32_e32 v87, 31, v86
	v_ashrrev_i32_e32 v89, 31, v88
	v_ashrrev_i32_e32 v91, 31, v90
	v_ashrrev_i32_e32 v93, 31, v92
	v_ashrrev_i32_e32 v95, 31, v94
	v_ashrrev_i32_e32 v97, 31, v96
	v_ashrrev_i32_e32 v99, 31, v98
	v_ashrrev_i32_e32 v101, 31, v100
	v_ashrrev_i32_e32 v103, 31, v102
	v_ashrrev_i32_e32 v105, 31, v104
	v_ashrrev_i32_e32 v107, 31, v106
	v_ashrrev_i32_e32 v109, 31, v108
	v_lshl_add_u64 v[110:111], s[20:21], 2, v[12:13]
	v_lshlrev_b64 v[78:79], 10, v[78:79]
	v_and_b32_e32 v128, 0xffffff00, v113
	v_and_b32_e32 v129, 0x7f, v112
	v_and_b32_e32 v115, 0xffffff00, v115
	v_and_b32_e32 v114, 0x7f, v114
	v_and_b32_e32 v117, 0xffffff00, v117
	v_and_b32_e32 v116, 0x7f, v116
	v_and_b32_e32 v119, 0xffffff00, v119
	v_and_b32_e32 v118, 0x7f, v118
	v_and_b32_e32 v121, 0xffffff00, v121
	v_and_b32_e32 v120, 0x7f, v120
	v_and_b32_e32 v123, 0xffffff00, v123
	v_and_b32_e32 v122, 0x7f, v122
	v_and_b32_e32 v125, 0xffffff00, v125
	v_and_b32_e32 v124, 0x7f, v124
	v_and_b32_e32 v127, 0xffffff00, v127
	v_and_b32_e32 v126, 0x7f, v126
	v_lshlrev_b64 v[112:113], 10, v[80:81]
	v_lshlrev_b64 v[82:83], 10, v[82:83]
	v_lshlrev_b64 v[84:85], 10, v[84:85]
	v_lshlrev_b64 v[86:87], 10, v[86:87]
	v_lshlrev_b64 v[88:89], 10, v[88:89]
	v_lshlrev_b64 v[90:91], 10, v[90:91]
	v_lshlrev_b64 v[92:93], 10, v[92:93]
	v_lshlrev_b64 v[94:95], 10, v[94:95]
	v_lshlrev_b64 v[96:97], 10, v[96:97]
	v_lshlrev_b64 v[98:99], 10, v[98:99]
	v_lshlrev_b64 v[100:101], 10, v[100:101]
	v_lshlrev_b64 v[102:103], 10, v[102:103]
	v_lshlrev_b64 v[104:105], 10, v[104:105]
	v_lshlrev_b64 v[106:107], 10, v[106:107]
	v_lshlrev_b64 v[108:109], 10, v[108:109]
	v_lshl_add_u64 v[78:79], v[110:111], 0, v[78:79]
	v_or3_b32 v144, v129, v128, s11
	v_or3_b32 v146, v114, v115, s11
	v_or3_b32 v148, v116, v117, s11
	v_or3_b32 v150, v118, v119, s11
	v_or3_b32 v152, v120, v121, s11
	v_or3_b32 v154, v122, v123, s11
	v_or3_b32 v156, v124, v125, s11
	v_or3_b32 v158, v126, v127, s11
	v_lshl_add_u64 v[112:113], v[110:111], 0, v[112:113]
	v_lshl_add_u64 v[114:115], v[110:111], 0, v[82:83]
	v_lshl_add_u64 v[116:117], v[110:111], 0, v[84:85]
	v_lshl_add_u64 v[118:119], v[110:111], 0, v[86:87]
	v_lshl_add_u64 v[120:121], v[110:111], 0, v[88:89]
	v_lshl_add_u64 v[122:123], v[110:111], 0, v[90:91]
	v_lshl_add_u64 v[124:125], v[110:111], 0, v[92:93]
	v_lshl_add_u64 v[126:127], v[110:111], 0, v[94:95]
	v_lshl_add_u64 v[128:129], v[110:111], 0, v[96:97]
	v_lshl_add_u64 v[130:131], v[110:111], 0, v[98:99]
	v_lshl_add_u64 v[132:133], v[110:111], 0, v[100:101]
	v_lshl_add_u64 v[134:135], v[110:111], 0, v[102:103]
	v_lshl_add_u64 v[136:137], v[110:111], 0, v[104:105]
	v_lshl_add_u64 v[138:139], v[110:111], 0, v[106:107]
	v_lshl_add_u64 v[140:141], v[110:111], 0, v[108:109]
	global_load_dwordx4 v[78:81], v[78:79], off nt
	s_nop 0
	global_load_dwordx4 v[82:85], v[112:113], off nt
	global_load_dwordx4 v[86:89], v[114:115], off nt
	global_load_dwordx4 v[90:93], v[116:117], off nt
	global_load_dwordx4 v[94:97], v[118:119], off nt
	global_load_dwordx4 v[98:101], v[120:121], off nt
	global_load_dwordx4 v[102:105], v[122:123], off nt
	global_load_dwordx4 v[106:109], v[124:125], off nt
	global_load_dwordx4 v[110:113], v[126:127], off nt
	global_load_dwordx4 v[114:117], v[128:129], off nt
	s_nop 0
	global_load_dwordx4 v[118:121], v[130:131], off nt
	global_load_dwordx4 v[122:125], v[132:133], off nt
	global_load_dwordx4 v[126:129], v[134:135], off nt
	s_nop 0
	global_load_dwordx4 v[130:133], v[136:137], off nt
	s_nop 0
	global_load_dwordx4 v[134:137], v[138:139], off nt
	s_nop 0
	global_load_dwordx4 v[138:141], v[140:141], off nt
	s_waitcnt vmcnt(15)
	ds_write2_b32 v30, v78, v79 offset1:1
	ds_write2_b32 v30, v80, v81 offset0:2 offset1:3
	s_waitcnt vmcnt(14)
	ds_write2_b32 v40, v82, v83 offset1:1
	ds_write2_b32 v41, v84, v85 offset1:1
	s_waitcnt vmcnt(13)
	ds_write2_b32 v42, v86, v87 offset1:1
	ds_write2_b32 v43, v88, v89 offset1:1
	s_waitcnt vmcnt(12)
	ds_write2_b32 v44, v90, v91 offset1:1
	ds_write2_b32 v45, v92, v93 offset1:1
	s_waitcnt vmcnt(11)
	ds_write2_b32 v46, v94, v95 offset1:1
	ds_write2_b32 v47, v96, v97 offset1:1
	s_waitcnt vmcnt(10)
	ds_write2_b32 v48, v98, v99 offset1:1
	ds_write2_b32 v49, v100, v101 offset1:1
	s_waitcnt vmcnt(9)
	ds_write2_b32 v50, v102, v103 offset1:1
	ds_write2_b32 v51, v104, v105 offset1:1
	s_waitcnt vmcnt(8)
; #define LAS __attribute__((address_space(3)))
; __device__ __forceinline__ void transpose_item(const float* W, int K, int N, bf16_t* WT, int gate, const float* kscale, LAS float* scr, int item, int lane) {
;     ...
;     const int c = lane & 7;
;     f32x4 k0v = {1.f, 1.f, 1.f, 1.f}, k1v = k0v;
;     if (kscale) { k0v = *(const f32x4*)(kscale + k0 + 8 * c); k1v = *(const f32x4*)(kscale + k0 + 8 * c + 4); }
; #pragma unroll
;     for (int j = 0; j < 8; ++j) { const int n = (lane >> 3) + 8 * j; const LAS float* s = scr + (8 * c) * 65 + n;
;         u32x4 o; o.x = pk2(s[0 * 65] * k0v[0], s[1 * 65] * k0v[1]); o.y = pk2(s[2 * 65] * k0v[2], s[3 * 65] * k0v[3]); o.z = pk2(s[4 * 65] * k1v[0], s[5 * 65] * k1v[1]); o.w = pk2(s[6 * 65] * k1v[2], s[7 * 65] * k1v[3]);
;         const int nn = n0 + n; const int row = gate < 0 ? nn : (256 * (nn >> 7) + 128 * gate + (nn & 127));
;         *(u32x4*)(WT + (size_t)row * K + k0 + 8 * c) = o; }
	ds_write2_b32 v52, v106, v107 offset1:1
	ds_write2_b32 v53, v108, v109 offset1:1
	s_waitcnt vmcnt(7)
	ds_write2_b32 v54, v110, v111 offset1:1
	ds_write2_b32 v55, v112, v113 offset1:1
	s_waitcnt vmcnt(6)
	ds_write2_b32 v56, v114, v115 offset1:1
	ds_write2_b32 v57, v116, v117 offset1:1
	s_waitcnt vmcnt(5)
	ds_write2_b32 v58, v118, v119 offset1:1
	ds_write2_b32 v59, v120, v121 offset1:1
	s_waitcnt vmcnt(4)
	ds_write2_b32 v60, v122, v123 offset1:1
	ds_write2_b32 v61, v124, v125 offset1:1
	s_waitcnt vmcnt(3)
	ds_write2_b32 v62, v126, v127 offset1:1
	ds_write2_b32 v63, v128, v129 offset1:1
	s_waitcnt vmcnt(2)
	ds_write2_b32 v64, v130, v131 offset1:1
	ds_write2_b32 v65, v132, v133 offset1:1
	s_waitcnt vmcnt(1)
	ds_write2_b32 v66, v134, v135 offset1:1
	ds_write2_b32 v67, v136, v137 offset1:1
	s_waitcnt vmcnt(0)
	ds_write2_b32 v68, v138, v139 offset1:1
	ds_write2_b32 v69, v140, v141 offset1:1
	s_waitcnt lgkmcnt(0)
	ds_read2_b32 v[78:79], v31 offset1:65
	ds_read2_b32 v[80:81], v31 offset0:130 offset1:195
	ds_read2_b32 v[82:83], v70 offset0:4 offset1:69
	ds_read2_b32 v[84:85], v70 offset0:134 offset1:199
	ds_read2_b32 v[86:87], v32 offset1:65
	ds_read2_b32 v[88:89], v32 offset0:130 offset1:195
	ds_read2_b32 v[90:91], v71 offset0:4 offset1:69
	ds_read2_b32 v[92:93], v71 offset0:134 offset1:199
	ds_read2_b32 v[94:95], v33 offset1:65
	ds_read2_b32 v[96:97], v33 offset0:130 offset1:195
	ds_read2_b32 v[98:99], v72 offset0:4 offset1:69
	ds_read2_b32 v[100:101], v72 offset0:134 offset1:199
	ds_read2_b32 v[102:103], v34 offset1:65
	ds_read2_b32 v[104:105], v34 offset0:130 offset1:195
	ds_read2_b32 v[106:107], v73 offset0:4 offset1:69
	ds_read2_b32 v[108:109], v73 offset0:134 offset1:199
	ds_read2_b32 v[110:111], v35 offset1:65
	ds_read2_b32 v[112:113], v35 offset0:130 offset1:195
	ds_read2_b32 v[114:115], v74 offset0:4 offset1:69
	ds_read2_b32 v[116:117], v74 offset0:134 offset1:199
	ds_read2_b32 v[118:119], v36 offset1:65
	ds_read2_b32 v[120:121], v36 offset0:130 offset1:195
	ds_read2_b32 v[122:123], v75 offset0:4 offset1:69
	ds_read2_b32 v[124:125], v75 offset0:134 offset1:199
	ds_read2_b32 v[126:127], v37 offset1:65
	ds_read2_b32 v[128:129], v37 offset0:130 offset1:195
	ds_read2_b32 v[130:131], v76 offset0:4 offset1:69
	ds_read2_b32 v[132:133], v76 offset0:134 offset1:199
	ds_read2_b32 v[134:135], v38 offset1:65
	ds_read2_b32 v[136:137], v38 offset0:130 offset1:195
	ds_read2_b32 v[138:139], v77 offset0:4 offset1:69
	ds_read2_b32 v[140:141], v77 offset0:134 offset1:199
	s_ashr_i32 s19, s18, 31
	v_ashrrev_i32_e32 v145, 31, v144
	v_lshl_add_u64 v[142:143], s[18:19], 1, v[6:7]
	v_ashrrev_i32_e32 v147, 31, v146
	v_ashrrev_i32_e32 v149, 31, v148
	v_ashrrev_i32_e32 v151, 31, v150
	v_ashrrev_i32_e32 v153, 31, v152
	v_ashrrev_i32_e32 v155, 31, v154
	v_ashrrev_i32_e32 v157, 31, v156
	v_ashrrev_i32_e32 v159, 31, v158
	v_lshlrev_b64 v[144:145], 9, v[144:145]
	v_lshlrev_b64 v[146:147], 9, v[146:147]
	v_lshlrev_b64 v[148:149], 9, v[148:149]
	v_lshlrev_b64 v[150:151], 9, v[150:151]
	v_lshlrev_b64 v[152:153], 9, v[152:153]
	v_lshlrev_b64 v[154:155], 9, v[154:155]
	v_lshlrev_b64 v[156:157], 9, v[156:157]
	v_lshlrev_b64 v[158:159], 9, v[158:159]
	v_lshl_add_u64 v[144:145], v[142:143], 0, v[144:145]
	s_waitcnt lgkmcnt(14)
	v_cvt_pk_bf16_f32 v78, v78, v79
	v_cvt_pk_bf16_f32 v79, v80, v81
	v_cvt_pk_bf16_f32 v80, v82, v83
	v_cvt_pk_bf16_f32 v81, v84, v85
	v_lshl_add_u64 v[146:147], v[142:143], 0, v[146:147]
	v_lshl_add_u64 v[148:149], v[142:143], 0, v[148:149]
	v_lshl_add_u64 v[150:151], v[142:143], 0, v[150:151]
	v_lshl_add_u64 v[152:153], v[142:143], 0, v[152:153]
	v_lshl_add_u64 v[154:155], v[142:143], 0, v[154:155]
	v_lshl_add_u64 v[156:157], v[142:143], 0, v[156:157]
	v_lshl_add_u64 v[142:143], v[142:143], 0, v[158:159]
	v_cvt_pk_bf16_f32 v82, v86, v87
	v_cvt_pk_bf16_f32 v83, v88, v89
	v_cvt_pk_bf16_f32 v84, v90, v91
	v_cvt_pk_bf16_f32 v85, v92, v93
	v_cvt_pk_bf16_f32 v86, v94, v95
	v_cvt_pk_bf16_f32 v87, v96, v97
	v_cvt_pk_bf16_f32 v88, v98, v99
	v_cvt_pk_bf16_f32 v89, v100, v101
	v_cvt_pk_bf16_f32 v90, v102, v103
	v_cvt_pk_bf16_f32 v91, v104, v105
	v_cvt_pk_bf16_f32 v92, v106, v107
	v_cvt_pk_bf16_f32 v93, v108, v109
	v_cvt_pk_bf16_f32 v94, v110, v111
	v_cvt_pk_bf16_f32 v95, v112, v113
	s_waitcnt lgkmcnt(13)
	v_cvt_pk_bf16_f32 v96, v114, v115
	s_waitcnt lgkmcnt(12)
	v_cvt_pk_bf16_f32 v97, v116, v117
	s_waitcnt lgkmcnt(11)
	v_cvt_pk_bf16_f32 v98, v118, v119
	s_waitcnt lgkmcnt(10)
	v_cvt_pk_bf16_f32 v99, v120, v121
	s_waitcnt lgkmcnt(9)
	v_cvt_pk_bf16_f32 v100, v122, v123
	s_waitcnt lgkmcnt(8)
	v_cvt_pk_bf16_f32 v101, v124, v125
	s_waitcnt lgkmcnt(7)
	v_cvt_pk_bf16_f32 v102, v126, v127
	s_waitcnt lgkmcnt(6)
	v_cvt_pk_bf16_f32 v103, v128, v129
	s_waitcnt lgkmcnt(5)
	v_cvt_pk_bf16_f32 v104, v130, v131
	s_waitcnt lgkmcnt(4)
	v_cvt_pk_bf16_f32 v105, v132, v133
	s_waitcnt lgkmcnt(3)
	v_cvt_pk_bf16_f32 v106, v134, v135
	s_waitcnt lgkmcnt(2)
	v_cvt_pk_bf16_f32 v107, v136, v137
	s_waitcnt lgkmcnt(1)
	v_cvt_pk_bf16_f32 v108, v138, v139
	s_waitcnt lgkmcnt(0)
	v_cvt_pk_bf16_f32 v109, v140, v141
	global_store_dwordx4 v[144:145], v[78:81], off nt
	global_store_dwordx4 v[146:147], v[82:85], off nt
	global_store_dwordx4 v[148:149], v[86:89], off nt
	global_store_dwordx4 v[150:151], v[90:93], off nt
	global_store_dwordx4 v[152:153], v[94:97], off nt
	global_store_dwordx4 v[154:155], v[98:101], off nt
	global_store_dwordx4 v[156:157], v[102:105], off nt
	global_store_dwordx4 v[142:143], v[106:109], off nt
	s_waitcnt lgkmcnt(0)
	s_add_i32 s12, s12, s92
	s_add_i32 s7, s7, s38
	s_add_i32 s6, s6, s3
	s_cmp_lt_i32 s12, 16
	s_cbranch_scc1 .LBB0_32
	s_branch .LBB0_27

; #define LAS __attribute__((address_space(3)))
; __device__ __forceinline__ void lds_wait() { asm volatile("s_waitcnt lgkmcnt(0)" ::: "memory"); }
; __device__ __forceinline__ void transpose_item(const float* W, int K, int N, bf16_t* WT, int gate, const float* kscale, LAS float* scr, int item, int lane) {
;     const int nblk = N / 64, kb = item / nblk, nb = item % nblk, k0 = 64 * kb, n0 = 64 * nb;
;     const int c4 = (lane & 15) * 4, kr = lane >> 4;
;     f32x4 v[16];
; #pragma unroll
;     for (int i = 0; i < 16; ++i) v[i] = __builtin_nontemporal_load((const f32x4*)(W + (size_t)(k0 + 4 * i + kr) * N + n0 + c4));
; #pragma unroll
;     for (int i = 0; i < 16; ++i) { LAS float* d = scr + (4 * i + kr) * 65 + c4; d[0] = v[i][0]; d[1] = v[i][1]; d[2] = v[i][2]; d[3] = v[i][3]; }
;     lds_wait();
.LBB0_35:
	s_ashr_i32 s3, s1, 31
	s_lshr_b32 s3, s3, 27
	s_add_i32 s3, s1, s3
	s_ashr_i32 s3, s3, 5
	s_lshl_b32 s4, s3, 6
	s_lshl_b32 s3, s3, 11
	v_add_u32_e32 v64, s4, v21
	s_sub_i32 s6, s0, s3
	v_add_u32_e32 v66, 4, v64
	v_add_u32_e32 v68, 8, v64
	v_add_u32_e32 v70, 12, v64
	v_add_u32_e32 v72, 16, v64
	v_add_u32_e32 v74, 20, v64
	v_add_u32_e32 v76, 24, v64
	s_ashr_i32 s7, s6, 31
	v_ashrrev_i32_e32 v65, 31, v64
	v_add_u32_e32 v78, 28, v64
	v_add_u32_e32 v80, 32, v64
	v_add_u32_e32 v82, 36, v64
	v_add_u32_e32 v84, 40, v64
	v_add_u32_e32 v86, 44, v64
	v_add_u32_e32 v88, 48, v64
	v_add_u32_e32 v90, 52, v64
	v_add_u32_e32 v92, 56, v64
	v_add_u32_e32 v94, 60, v64
	v_add_u32_e32 v98, s6, v29
	v_add_u32_e32 v100, s6, v22
	v_add_u32_e32 v102, s6, v23
	v_add_u32_e32 v104, s6, v24
	v_add_u32_e32 v106, s6, v25
	v_add_u32_e32 v108, s6, v26
	v_add_u32_e32 v110, s6, v27
	v_add_u32_e32 v112, s6, v28
	v_ashrrev_i32_e32 v67, 31, v66
	v_ashrrev_i32_e32 v69, 31, v68
	v_ashrrev_i32_e32 v71, 31, v70
	v_ashrrev_i32_e32 v73, 31, v72
	v_ashrrev_i32_e32 v75, 31, v74
	v_ashrrev_i32_e32 v77, 31, v76
	s_ashr_i32 s5, s4, 31
	v_lshl_add_u64 v[114:115], s[6:7], 2, v[0:1]
	v_lshlrev_b64 v[64:65], 13, v[64:65]
	v_ashrrev_i32_e32 v79, 31, v78
	v_ashrrev_i32_e32 v81, 31, v80
	v_ashrrev_i32_e32 v83, 31, v82
	v_ashrrev_i32_e32 v85, 31, v84
	v_ashrrev_i32_e32 v87, 31, v86
	v_ashrrev_i32_e32 v89, 31, v88
	v_ashrrev_i32_e32 v91, 31, v90
	v_ashrrev_i32_e32 v93, 31, v92
	v_ashrrev_i32_e32 v95, 31, v94
	v_ashrrev_i32_e32 v99, 31, v98
	v_ashrrev_i32_e32 v101, 31, v100
	v_ashrrev_i32_e32 v103, 31, v102
	v_ashrrev_i32_e32 v105, 31, v104
	v_ashrrev_i32_e32 v107, 31, v106
	v_ashrrev_i32_e32 v109, 31, v108
	v_ashrrev_i32_e32 v111, 31, v110
	v_ashrrev_i32_e32 v113, 31, v112
	v_lshlrev_b64 v[116:117], 13, v[66:67]
	v_lshlrev_b64 v[68:69], 13, v[68:69]
	v_lshlrev_b64 v[70:71], 13, v[70:71]
	v_lshlrev_b64 v[72:73], 13, v[72:73]
	v_lshlrev_b64 v[74:75], 13, v[74:75]
	v_lshlrev_b64 v[76:77], 13, v[76:77]
	v_lshl_add_u64 v[96:97], s[4:5], 1, v[2:3]
	v_lshl_add_u64 v[64:65], v[114:115], 0, v[64:65]
	v_lshlrev_b64 v[78:79], 13, v[78:79]
	v_lshlrev_b64 v[80:81], 13, v[80:81]
	v_lshlrev_b64 v[82:83], 13, v[82:83]
	v_lshlrev_b64 v[84:85], 13, v[84:85]
	v_lshlrev_b64 v[86:87], 13, v[86:87]
	v_lshlrev_b64 v[88:89], 13, v[88:89]
	v_lshlrev_b64 v[90:91], 13, v[90:91]
	v_lshlrev_b64 v[92:93], 13, v[92:93]
	v_lshlrev_b64 v[94:95], 13, v[94:95]
	v_lshlrev_b64 v[98:99], 12, v[98:99]
	v_lshlrev_b64 v[100:101], 12, v[100:101]
	v_lshlrev_b64 v[102:103], 12, v[102:103]
	v_lshlrev_b64 v[104:105], 12, v[104:105]
	v_lshlrev_b64 v[106:107], 12, v[106:107]
	v_lshlrev_b64 v[108:109], 12, v[108:109]
	v_lshlrev_b64 v[110:111], 12, v[110:111]
	v_lshlrev_b64 v[112:113], 12, v[112:113]
	v_lshl_add_u64 v[116:117], v[114:115], 0, v[116:117]
	v_lshl_add_u64 v[118:119], v[114:115], 0, v[68:69]
	v_lshl_add_u64 v[120:121], v[114:115], 0, v[70:71]
	v_lshl_add_u64 v[122:123], v[114:115], 0, v[72:73]
	v_lshl_add_u64 v[124:125], v[114:115], 0, v[74:75]
	v_lshl_add_u64 v[126:127], v[114:115], 0, v[76:77]
	global_load_dwordx4 v[64:67], v[64:65], off nt
	v_lshl_add_u64 v[128:129], v[114:115], 0, v[78:79]
	v_lshl_add_u64 v[130:131], v[114:115], 0, v[80:81]
	v_lshl_add_u64 v[132:133], v[114:115], 0, v[82:83]
	v_lshl_add_u64 v[134:135], v[114:115], 0, v[84:85]
	v_lshl_add_u64 v[136:137], v[114:115], 0, v[86:87]
	v_lshl_add_u64 v[138:139], v[114:115], 0, v[88:89]
	v_lshl_add_u64 v[140:141], v[114:115], 0, v[90:91]
	v_lshl_add_u64 v[142:143], v[114:115], 0, v[92:93]
	v_lshl_add_u64 v[144:145], v[114:115], 0, v[94:95]
	v_lshl_add_u64 v[146:147], v[96:97], 0, v[98:99]
	v_lshl_add_u64 v[148:149], v[96:97], 0, v[100:101]
	v_lshl_add_u64 v[150:151], v[96:97], 0, v[102:103]
	v_lshl_add_u64 v[152:153], v[96:97], 0, v[104:105]
	v_lshl_add_u64 v[154:155], v[96:97], 0, v[106:107]
	v_lshl_add_u64 v[156:157], v[96:97], 0, v[108:109]
	v_lshl_add_u64 v[158:159], v[96:97], 0, v[110:111]
	v_lshl_add_u64 v[160:161], v[96:97], 0, v[112:113]
	global_load_dwordx4 v[68:71], v[116:117], off nt
	global_load_dwordx4 v[72:75], v[118:119], off nt
	global_load_dwordx4 v[76:79], v[120:121], off nt
	global_load_dwordx4 v[80:83], v[122:123], off nt
	global_load_dwordx4 v[84:87], v[124:125], off nt
	global_load_dwordx4 v[88:91], v[126:127], off nt
	global_load_dwordx4 v[92:95], v[128:129], off nt
	global_load_dwordx4 v[96:99], v[130:131], off nt
	global_load_dwordx4 v[100:103], v[132:133], off nt
	global_load_dwordx4 v[104:107], v[134:135], off nt
	global_load_dwordx4 v[108:111], v[136:137], off nt
	global_load_dwordx4 v[112:115], v[138:139], off nt
	global_load_dwordx4 v[116:119], v[140:141], off nt
	global_load_dwordx4 v[120:123], v[142:143], off nt
	global_load_dwordx4 v[124:127], v[144:145], off nt
	s_waitcnt vmcnt(15)
	ds_write2_b32 v30, v64, v65 offset1:1
	ds_write2_b32 v30, v66, v67 offset0:2 offset1:3
	s_waitcnt vmcnt(14)
	ds_write2_b32 v4, v68, v69 offset1:1
	ds_write2_b32 v5, v70, v71 offset1:1
	s_waitcnt vmcnt(13)
; #define LAS __attribute__((address_space(3)))
; __device__ __forceinline__ void transpose_item(const float* W, int K, int N, bf16_t* WT, int gate, const float* kscale, LAS float* scr, int item, int lane) {
;     ...
;     const int c = lane & 7;
;     f32x4 k0v = {1.f, 1.f, 1.f, 1.f}, k1v = k0v;
;     if (kscale) { k0v = *(const f32x4*)(kscale + k0 + 8 * c); k1v = *(const f32x4*)(kscale + k0 + 8 * c + 4); }
; #pragma unroll
;     for (int j = 0; j < 8; ++j) { const int n = (lane >> 3) + 8 * j; const LAS float* s = scr + (8 * c) * 65 + n;
;         u32x4 o; o.x = pk2(s[0 * 65] * k0v[0], s[1 * 65] * k0v[1]); o.y = pk2(s[2 * 65] * k0v[2], s[3 * 65] * k0v[3]); o.z = pk2(s[4 * 65] * k1v[0], s[5 * 65] * k1v[1]); o.w = pk2(s[6 * 65] * k1v[2], s[7 * 65] * k1v[3]);
;         const int nn = n0 + n; const int row = gate < 0 ? nn : (256 * (nn >> 7) + 128 * gate + (nn & 127));
;         *(u32x4*)(WT + (size_t)row * K + k0 + 8 * c) = o; }
	ds_write2_b32 v6, v72, v73 offset1:1
	ds_write2_b32 v7, v74, v75 offset1:1
	s_waitcnt vmcnt(12)
	ds_write2_b32 v11, v76, v77 offset1:1
	ds_write2_b32 v12, v78, v79 offset1:1
	s_waitcnt vmcnt(11)
	ds_write2_b32 v13, v80, v81 offset1:1
	ds_write2_b32 v14, v82, v83 offset1:1
	s_waitcnt vmcnt(10)
	ds_write2_b32 v15, v84, v85 offset1:1
	ds_write2_b32 v16, v86, v87 offset1:1
	s_waitcnt vmcnt(9)
	ds_write2_b32 v17, v88, v89 offset1:1
	ds_write2_b32 v18, v90, v91 offset1:1
	s_waitcnt vmcnt(8)
	ds_write2_b32 v19, v92, v93 offset1:1
	ds_write2_b32 v39, v94, v95 offset1:1
	s_waitcnt vmcnt(7)
	ds_write2_b32 v40, v96, v97 offset1:1
	ds_write2_b32 v41, v98, v99 offset1:1
	s_waitcnt vmcnt(6)
	ds_write2_b32 v42, v100, v101 offset1:1
	ds_write2_b32 v43, v102, v103 offset1:1
	s_waitcnt vmcnt(5)
	ds_write2_b32 v44, v104, v105 offset1:1
	ds_write2_b32 v45, v106, v107 offset1:1
	s_waitcnt vmcnt(4)
	ds_write2_b32 v46, v108, v109 offset1:1
	ds_write2_b32 v47, v110, v111 offset1:1
	s_waitcnt vmcnt(3)
	ds_write2_b32 v48, v112, v113 offset1:1
	ds_write2_b32 v49, v114, v115 offset1:1
	s_waitcnt vmcnt(2)
	ds_write2_b32 v50, v116, v117 offset1:1
	ds_write2_b32 v51, v118, v119 offset1:1
	s_waitcnt vmcnt(1)
	ds_write2_b32 v52, v120, v121 offset1:1
	ds_write2_b32 v53, v122, v123 offset1:1
	s_waitcnt vmcnt(0)
	ds_write2_b32 v54, v124, v125 offset1:1
	ds_write2_b32 v55, v126, v127 offset1:1
	s_waitcnt lgkmcnt(0)
	ds_read2_b32 v[64:65], v31 offset1:65
	ds_read2_b32 v[66:67], v31 offset0:130 offset1:195
	ds_read2_b32 v[68:69], v56 offset0:4 offset1:69
	ds_read2_b32 v[70:71], v56 offset0:134 offset1:199
	ds_read2_b32 v[72:73], v32 offset1:65
	ds_read2_b32 v[74:75], v32 offset0:130 offset1:195
	ds_read2_b32 v[76:77], v57 offset0:4 offset1:69
	ds_read2_b32 v[78:79], v57 offset0:134 offset1:199
	ds_read2_b32 v[80:81], v33 offset1:65
	ds_read2_b32 v[82:83], v33 offset0:130 offset1:195
	ds_read2_b32 v[84:85], v58 offset0:4 offset1:69
	ds_read2_b32 v[86:87], v58 offset0:134 offset1:199
	ds_read2_b32 v[88:89], v34 offset1:65
	ds_read2_b32 v[90:91], v34 offset0:130 offset1:195
	ds_read2_b32 v[92:93], v59 offset0:4 offset1:69
	ds_read2_b32 v[94:95], v59 offset0:134 offset1:199
	ds_read2_b32 v[96:97], v35 offset1:65
	ds_read2_b32 v[98:99], v35 offset0:130 offset1:195
	ds_read2_b32 v[100:101], v60 offset0:4 offset1:69
	ds_read2_b32 v[102:103], v60 offset0:134 offset1:199
	ds_read2_b32 v[104:105], v36 offset1:65
	ds_read2_b32 v[106:107], v36 offset0:130 offset1:195
	ds_read2_b32 v[108:109], v61 offset0:4 offset1:69
	ds_read2_b32 v[110:111], v61 offset0:134 offset1:199
	ds_read2_b32 v[112:113], v37 offset1:65
	ds_read2_b32 v[114:115], v37 offset0:130 offset1:195
	ds_read2_b32 v[116:117], v62 offset0:4 offset1:69
	ds_read2_b32 v[118:119], v62 offset0:134 offset1:199
	ds_read2_b32 v[120:121], v38 offset1:65
	ds_read2_b32 v[122:123], v38 offset0:130 offset1:195
	ds_read2_b32 v[124:125], v63 offset0:4 offset1:69
	ds_read2_b32 v[126:127], v63 offset0:134 offset1:199
	s_waitcnt lgkmcnt(14)
	v_cvt_pk_bf16_f32 v64, v64, v65
	v_cvt_pk_bf16_f32 v65, v66, v67
	v_cvt_pk_bf16_f32 v66, v68, v69
	v_cvt_pk_bf16_f32 v67, v70, v71
	v_cvt_pk_bf16_f32 v68, v72, v73
	v_cvt_pk_bf16_f32 v69, v74, v75
	v_cvt_pk_bf16_f32 v70, v76, v77
	v_cvt_pk_bf16_f32 v71, v78, v79
	v_cvt_pk_bf16_f32 v72, v80, v81
	v_cvt_pk_bf16_f32 v73, v82, v83
	v_cvt_pk_bf16_f32 v74, v84, v85
	v_cvt_pk_bf16_f32 v75, v86, v87
	v_cvt_pk_bf16_f32 v76, v88, v89
	v_cvt_pk_bf16_f32 v77, v90, v91
	v_cvt_pk_bf16_f32 v78, v92, v93
	v_cvt_pk_bf16_f32 v79, v94, v95
	v_cvt_pk_bf16_f32 v80, v96, v97
	v_cvt_pk_bf16_f32 v81, v98, v99
	s_waitcnt lgkmcnt(13)
	v_cvt_pk_bf16_f32 v82, v100, v101
	s_waitcnt lgkmcnt(12)
	v_cvt_pk_bf16_f32 v83, v102, v103
	s_waitcnt lgkmcnt(11)
	v_cvt_pk_bf16_f32 v84, v104, v105
	s_waitcnt lgkmcnt(10)
	v_cvt_pk_bf16_f32 v85, v106, v107
	s_waitcnt lgkmcnt(9)
	v_cvt_pk_bf16_f32 v86, v108, v109
	s_waitcnt lgkmcnt(8)
	v_cvt_pk_bf16_f32 v87, v110, v111
	s_waitcnt lgkmcnt(7)
	v_cvt_pk_bf16_f32 v88, v112, v113
	s_waitcnt lgkmcnt(6)
	v_cvt_pk_bf16_f32 v89, v114, v115
	s_waitcnt lgkmcnt(5)
	v_cvt_pk_bf16_f32 v90, v116, v117
	s_waitcnt lgkmcnt(4)
	v_cvt_pk_bf16_f32 v91, v118, v119
	s_waitcnt lgkmcnt(3)
	v_cvt_pk_bf16_f32 v92, v120, v121
	s_waitcnt lgkmcnt(2)
	v_cvt_pk_bf16_f32 v93, v122, v123
	s_waitcnt lgkmcnt(1)
	v_cvt_pk_bf16_f32 v94, v124, v125
	s_waitcnt lgkmcnt(0)
	v_cvt_pk_bf16_f32 v95, v126, v127
	global_store_dwordx4 v[146:147], v[64:67], off nt
	global_store_dwordx4 v[148:149], v[68:71], off nt
	global_store_dwordx4 v[150:151], v[72:75], off nt
	global_store_dwordx4 v[152:153], v[76:79], off nt
	global_store_dwordx4 v[154:155], v[80:83], off nt
	global_store_dwordx4 v[156:157], v[84:87], off nt
	global_store_dwordx4 v[158:159], v[88:91], off nt
	global_store_dwordx4 v[160:161], v[92:95], off nt
	s_waitcnt lgkmcnt(0)
	s_add_i32 s1, s1, s92
	s_add_i32 s0, s0, s38
	s_cmpk_lt_i32 s1, 0x400
	s_cbranch_scc1 .LBB0_35

; #define LAS __attribute__((address_space(3)))
; __device__ __forceinline__ void transpose_item(const float* W, int K, int N, bf16_t* WT, int gate, const float* kscale, LAS float* scr, int item, int lane) {
;     ...
;     const int c = lane & 7;
;     f32x4 k0v = {1.f, 1.f, 1.f, 1.f}, k1v = k0v;
;     if (kscale) { k0v = *(const f32x4*)(kscale + k0 + 8 * c); k1v = *(const f32x4*)(kscale + k0 + 8 * c + 4); }
; #pragma unroll
;     for (int j = 0; j < 8; ++j) { const int n = (lane >> 3) + 8 * j; const LAS float* s = scr + (8 * c) * 65 + n;
;         u32x4 o; o.x = pk2(s[0 * 65] * k0v[0], s[1 * 65] * k0v[1]); o.y = pk2(s[2 * 65] * k0v[2], s[3 * 65] * k0v[3]); o.z = pk2(s[4 * 65] * k1v[0], s[5 * 65] * k1v[1]); o.w = pk2(s[6 * 65] * k1v[2], s[7 * 65] * k1v[3]);
;         const int nn = n0 + n; const int row = gate < 0 ? nn : (256 * (nn >> 7) + 128 * gate + (nn & 127));
;         *(u32x4*)(WT + (size_t)row * K + k0 + 8 * c) = o; }
.LBB0_39:
	ds_read2_b32 v[68:69], v31 offset1:65
	ds_read2_b32 v[70:71], v31 offset0:130 offset1:195
	s_sub_i32 s27, 0, s27
	v_lshl_add_u64 v[18:19], s[4:5], 1, v[16:17]
	s_add_i32 s4, s27, s25
	s_waitcnt vmcnt(0) lgkmcnt(1)
	v_mul_f32_e32 v68, v4, v68
	v_mul_f32_e32 v69, v5, v69
	v_cvt_pk_bf16_f32 v68, v68, v69
	v_add_u32_e32 v69, 0x400, v31
	ds_read2_b32 v[72:73], v69 offset0:4 offset1:69
	ds_read2_b32 v[74:75], v69 offset0:134 offset1:199
	s_waitcnt lgkmcnt(2)
	v_mul_f32_e32 v70, v6, v70
	v_mul_f32_e32 v71, v7, v71
	v_cvt_pk_bf16_f32 v69, v70, v71
	s_waitcnt lgkmcnt(1)
	v_mul_f32_e32 v70, v0, v72
	v_mul_f32_e32 v71, v1, v73
	v_cvt_pk_bf16_f32 v70, v70, v71
	s_waitcnt lgkmcnt(0)
	v_mul_f32_e32 v71, v2, v74
	v_mul_f32_e32 v72, v3, v75
	ds_read2_b32 v[74:75], v32 offset1:65
	v_cvt_pk_bf16_f32 v71, v71, v72
	v_add_u32_e32 v72, s4, v29
	v_ashrrev_i32_e32 v73, 31, v72
	v_lshlrev_b64 v[72:73], 12, v[72:73]
	v_lshl_add_u64 v[72:73], v[18:19], 0, v[72:73]
	global_store_dwordx4 v[72:73], v[68:71], off nt
	ds_read2_b32 v[70:71], v32 offset0:130 offset1:195
	s_add_i32 s26, s26, s92
	s_waitcnt lgkmcnt(1)
	v_mul_f32_e32 v68, v4, v74
	v_mul_f32_e32 v69, v5, v75
	v_cvt_pk_bf16_f32 v68, v68, v69
	v_add_u32_e32 v69, 0x400, v32
	ds_read2_b32 v[72:73], v69 offset0:4 offset1:69
	ds_read2_b32 v[74:75], v69 offset0:134 offset1:199
	s_waitcnt lgkmcnt(2)
	v_mul_f32_e32 v70, v6, v70
	v_mul_f32_e32 v71, v7, v71
	v_cvt_pk_bf16_f32 v69, v70, v71
	s_waitcnt lgkmcnt(1)
	v_mul_f32_e32 v70, v0, v72
	v_mul_f32_e32 v71, v1, v73
	v_cvt_pk_bf16_f32 v70, v70, v71
	s_waitcnt lgkmcnt(0)
	v_mul_f32_e32 v71, v2, v74
	v_mul_f32_e32 v72, v3, v75
	ds_read2_b32 v[74:75], v33 offset1:65
	v_cvt_pk_bf16_f32 v71, v71, v72
	v_add_u32_e32 v72, s4, v22
	v_ashrrev_i32_e32 v73, 31, v72
	v_lshlrev_b64 v[72:73], 12, v[72:73]
	v_lshl_add_u64 v[72:73], v[18:19], 0, v[72:73]
	global_store_dwordx4 v[72:73], v[68:71], off nt
	ds_read2_b32 v[70:71], v33 offset0:130 offset1:195
	s_add_i32 s25, s25, s38
	s_waitcnt lgkmcnt(1)
	v_mul_f32_e32 v68, v4, v74
	v_mul_f32_e32 v69, v5, v75
	v_cvt_pk_bf16_f32 v68, v68, v69
	v_add_u32_e32 v69, 0x400, v33
	ds_read2_b32 v[72:73], v69 offset0:4 offset1:69
	ds_read2_b32 v[74:75], v69 offset0:134 offset1:199
	s_waitcnt lgkmcnt(2)
	v_mul_f32_e32 v70, v6, v70
	v_mul_f32_e32 v71, v7, v71
	v_cvt_pk_bf16_f32 v69, v70, v71
	s_waitcnt lgkmcnt(1)
	v_mul_f32_e32 v70, v0, v72
	v_mul_f32_e32 v71, v1, v73
	v_cvt_pk_bf16_f32 v70, v70, v71
	s_waitcnt lgkmcnt(0)
	v_mul_f32_e32 v71, v2, v74
	v_mul_f32_e32 v72, v3, v75
	ds_read2_b32 v[74:75], v34 offset1:65
	v_cvt_pk_bf16_f32 v71, v71, v72
	v_add_u32_e32 v72, s4, v23
	v_ashrrev_i32_e32 v73, 31, v72
	v_lshlrev_b64 v[72:73], 12, v[72:73]
	v_lshl_add_u64 v[72:73], v[18:19], 0, v[72:73]
	global_store_dwordx4 v[72:73], v[68:71], off nt
	ds_read2_b32 v[70:71], v34 offset0:130 offset1:195
	s_cmpk_lt_i32 s26, 0x1000
	s_waitcnt lgkmcnt(1)
	v_mul_f32_e32 v68, v4, v74
	v_mul_f32_e32 v69, v5, v75
	v_cvt_pk_bf16_f32 v68, v68, v69
	v_add_u32_e32 v69, 0x400, v34
	ds_read2_b32 v[72:73], v69 offset0:4 offset1:69
	ds_read2_b32 v[74:75], v69 offset0:134 offset1:199
	s_waitcnt lgkmcnt(2)
	v_mul_f32_e32 v70, v6, v70
	v_mul_f32_e32 v71, v7, v71
	v_cvt_pk_bf16_f32 v69, v70, v71
	s_waitcnt lgkmcnt(1)
	v_mul_f32_e32 v70, v0, v72
	v_mul_f32_e32 v71, v1, v73
	v_cvt_pk_bf16_f32 v70, v70, v71
	s_waitcnt lgkmcnt(0)
; #define LAS __attribute__((address_space(3)))
; __device__ __forceinline__ void transpose_item(const float* W, int K, int N, bf16_t* WT, int gate, const float* kscale, LAS float* scr, int item, int lane) {
;     ...
;     const int c = lane & 7;
;     f32x4 k0v = {1.f, 1.f, 1.f, 1.f}, k1v = k0v;
;     if (kscale) { k0v = *(const f32x4*)(kscale + k0 + 8 * c); k1v = *(const f32x4*)(kscale + k0 + 8 * c + 4); }
; #pragma unroll
;     for (int j = 0; j < 8; ++j) { const int n = (lane >> 3) + 8 * j; const LAS float* s = scr + (8 * c) * 65 + n;
;         u32x4 o; o.x = pk2(s[0 * 65] * k0v[0], s[1 * 65] * k0v[1]); o.y = pk2(s[2 * 65] * k0v[2], s[3 * 65] * k0v[3]); o.z = pk2(s[4 * 65] * k1v[0], s[5 * 65] * k1v[1]); o.w = pk2(s[6 * 65] * k1v[2], s[7 * 65] * k1v[3]);
;         const int nn = n0 + n; const int row = gate < 0 ? nn : (256 * (nn >> 7) + 128 * gate + (nn & 127));
;         *(u32x4*)(WT + (size_t)row * K + k0 + 8 * c) = o; }
	v_mul_f32_e32 v71, v2, v74
	v_mul_f32_e32 v72, v3, v75
	ds_read2_b32 v[74:75], v35 offset1:65
	v_cvt_pk_bf16_f32 v71, v71, v72
	v_add_u32_e32 v72, s4, v24
	v_ashrrev_i32_e32 v73, 31, v72
	v_lshlrev_b64 v[72:73], 12, v[72:73]
	v_lshl_add_u64 v[72:73], v[18:19], 0, v[72:73]
	global_store_dwordx4 v[72:73], v[68:71], off nt
	ds_read2_b32 v[70:71], v35 offset0:130 offset1:195
	s_waitcnt lgkmcnt(1)
	v_mul_f32_e32 v68, v4, v74
	v_mul_f32_e32 v69, v5, v75
	v_cvt_pk_bf16_f32 v68, v68, v69
	v_add_u32_e32 v69, 0x400, v35
	ds_read2_b32 v[72:73], v69 offset0:4 offset1:69
	ds_read2_b32 v[74:75], v69 offset0:134 offset1:199
	s_waitcnt lgkmcnt(2)
	v_mul_f32_e32 v70, v6, v70
	v_mul_f32_e32 v71, v7, v71
	v_cvt_pk_bf16_f32 v69, v70, v71
	s_waitcnt lgkmcnt(1)
	v_mul_f32_e32 v70, v0, v72
	v_mul_f32_e32 v71, v1, v73
	v_cvt_pk_bf16_f32 v70, v70, v71
	s_waitcnt lgkmcnt(0)
	v_mul_f32_e32 v71, v2, v74
	v_mul_f32_e32 v72, v3, v75
	ds_read2_b32 v[74:75], v36 offset1:65
	v_cvt_pk_bf16_f32 v71, v71, v72
	v_add_u32_e32 v72, s4, v25
	v_ashrrev_i32_e32 v73, 31, v72
	v_lshlrev_b64 v[72:73], 12, v[72:73]
	v_lshl_add_u64 v[72:73], v[18:19], 0, v[72:73]
	global_store_dwordx4 v[72:73], v[68:71], off nt
	ds_read2_b32 v[70:71], v36 offset0:130 offset1:195
	s_waitcnt lgkmcnt(1)
	v_mul_f32_e32 v68, v4, v74
	v_mul_f32_e32 v69, v5, v75
	v_cvt_pk_bf16_f32 v68, v68, v69
	v_add_u32_e32 v69, 0x400, v36
	ds_read2_b32 v[72:73], v69 offset0:4 offset1:69
	ds_read2_b32 v[74:75], v69 offset0:134 offset1:199
	s_waitcnt lgkmcnt(2)
	v_mul_f32_e32 v70, v6, v70
	v_mul_f32_e32 v71, v7, v71
	v_cvt_pk_bf16_f32 v69, v70, v71
	s_waitcnt lgkmcnt(1)
	v_mul_f32_e32 v70, v0, v72
	v_mul_f32_e32 v71, v1, v73
	v_cvt_pk_bf16_f32 v70, v70, v71
	s_waitcnt lgkmcnt(0)
	v_mul_f32_e32 v71, v2, v74
	v_mul_f32_e32 v72, v3, v75
	ds_read2_b32 v[74:75], v37 offset1:65
	v_cvt_pk_bf16_f32 v71, v71, v72
	v_add_u32_e32 v72, s4, v26
	v_ashrrev_i32_e32 v73, 31, v72
	v_lshlrev_b64 v[72:73], 12, v[72:73]
	v_lshl_add_u64 v[72:73], v[18:19], 0, v[72:73]
	global_store_dwordx4 v[72:73], v[68:71], off nt
	ds_read2_b32 v[70:71], v37 offset0:130 offset1:195
	s_waitcnt lgkmcnt(1)
	v_mul_f32_e32 v68, v4, v74
	v_mul_f32_e32 v69, v5, v75
	v_cvt_pk_bf16_f32 v68, v68, v69
	v_add_u32_e32 v69, 0x400, v37
	ds_read2_b32 v[72:73], v69 offset0:4 offset1:69
	ds_read2_b32 v[74:75], v69 offset0:134 offset1:199
	s_waitcnt lgkmcnt(2)
	v_mul_f32_e32 v70, v6, v70
	v_mul_f32_e32 v71, v7, v71
	v_cvt_pk_bf16_f32 v69, v70, v71
	s_waitcnt lgkmcnt(1)
	v_mul_f32_e32 v70, v0, v72
	v_mul_f32_e32 v71, v1, v73
	v_cvt_pk_bf16_f32 v70, v70, v71
	s_waitcnt lgkmcnt(0)
	v_mul_f32_e32 v71, v2, v74
	v_mul_f32_e32 v72, v3, v75
	v_cvt_pk_bf16_f32 v71, v71, v72
	v_add_u32_e32 v72, s4, v27
	ds_read2_b32 v[74:75], v38 offset1:65
	v_ashrrev_i32_e32 v73, 31, v72
	v_lshlrev_b64 v[72:73], 12, v[72:73]
	v_lshl_add_u64 v[72:73], v[18:19], 0, v[72:73]
	global_store_dwordx4 v[72:73], v[68:71], off nt
	ds_read2_b32 v[68:69], v38 offset0:130 offset1:195
	s_waitcnt lgkmcnt(1)
	v_mul_f32_e32 v4, v4, v74
	v_mul_f32_e32 v5, v5, v75
	v_cvt_pk_bf16_f32 v4, v4, v5
	v_add_u32_e32 v5, 0x400, v38
	ds_read2_b32 v[70:71], v5 offset0:4 offset1:69
	s_waitcnt lgkmcnt(1)
	v_mul_f32_e32 v6, v6, v68
	v_mul_f32_e32 v7, v7, v69
	ds_read2_b32 v[68:69], v5 offset0:134 offset1:199
	v_cvt_pk_bf16_f32 v5, v6, v7
	s_waitcnt lgkmcnt(1)
	v_mul_f32_e32 v0, v0, v70
	v_mul_f32_e32 v1, v1, v71
	v_cvt_pk_bf16_f32 v6, v0, v1
	s_waitcnt lgkmcnt(0)
	v_mul_f32_e32 v0, v2, v68
	v_mul_f32_e32 v1, v3, v69
	v_cvt_pk_bf16_f32 v7, v0, v1
	v_add_u32_e32 v0, s4, v28
	v_ashrrev_i32_e32 v1, 31, v0
	v_lshlrev_b64 v[0:1], 12, v[0:1]
	v_lshl_add_u64 v[0:1], v[18:19], 0, v[0:1]
	global_store_dwordx4 v[0:1], v[4:7], off nt
	s_waitcnt lgkmcnt(0)
	s_cbranch_scc0 .LBB0_42

; #define LAS __attribute__((address_space(3)))
; __device__ __forceinline__ void lds_wait() { asm volatile("s_waitcnt lgkmcnt(0)" ::: "memory"); }
; __device__ __forceinline__ void transpose_item(const float* W, int K, int N, bf16_t* WT, int gate, const float* kscale, LAS float* scr, int item, int lane) {
;     const int nblk = N / 64, kb = item / nblk, nb = item % nblk, k0 = 64 * kb, n0 = 64 * nb;
;     const int c4 = (lane & 15) * 4, kr = lane >> 4;
;     f32x4 v[16];
; #pragma unroll
;     for (int i = 0; i < 16; ++i) v[i] = __builtin_nontemporal_load((const f32x4*)(W + (size_t)(k0 + 4 * i + kr) * N + n0 + c4));
; #pragma unroll
;     for (int i = 0; i < 16; ++i) { LAS float* d = scr + (4 * i + kr) * 65 + c4; d[0] = v[i][0]; d[1] = v[i][1]; d[2] = v[i][2]; d[3] = v[i][3]; }
;     lds_wait();
.LBB0_43:
	s_ashr_i32 s1, s0, 31
	s_lshr_b32 s1, s1, 27
	s_add_i32 s1, s0, s1
	s_ashr_i32 s1, s1, 5
	s_lshl_b32 s4, s1, 6
	s_lshl_b32 s1, s1, 11
	v_add_u32_e32 v4, s4, v21
	s_sub_i32 s6, s3, s1
	v_add_u32_e32 v6, 4, v4
	v_add_u32_e32 v8, 8, v4
	v_add_u32_e32 v10, 12, v4
	v_add_u32_e32 v12, 16, v4
	v_add_u32_e32 v14, 20, v4
	v_add_u32_e32 v16, 24, v4
	s_ashr_i32 s7, s6, 31
	v_ashrrev_i32_e32 v5, 31, v4
	v_add_u32_e32 v18, 28, v4
	v_add_u32_e32 v40, 32, v4
	v_add_u32_e32 v42, 36, v4
	v_add_u32_e32 v44, 40, v4
	v_add_u32_e32 v46, 44, v4
	v_add_u32_e32 v48, 48, v4
	v_add_u32_e32 v50, 52, v4
	v_add_u32_e32 v52, 56, v4
	v_add_u32_e32 v54, 60, v4
	v_add_u32_e32 v58, s6, v29
	v_add_u32_e32 v60, s6, v22
	v_add_u32_e32 v62, s6, v23
	v_add_u32_e32 v64, s6, v24
	v_add_u32_e32 v66, s6, v25
	v_add_u32_e32 v68, s6, v26
	v_add_u32_e32 v70, s6, v27
	v_add_u32_e32 v72, s6, v28
	v_ashrrev_i32_e32 v7, 31, v6
	v_ashrrev_i32_e32 v9, 31, v8
	v_ashrrev_i32_e32 v11, 31, v10
	v_ashrrev_i32_e32 v13, 31, v12
	v_ashrrev_i32_e32 v15, 31, v14
	v_ashrrev_i32_e32 v17, 31, v16
	s_ashr_i32 s5, s4, 31
	v_lshl_add_u64 v[74:75], s[6:7], 2, v[0:1]
	v_lshlrev_b64 v[4:5], 13, v[4:5]
	v_ashrrev_i32_e32 v19, 31, v18
	v_ashrrev_i32_e32 v41, 31, v40
	v_ashrrev_i32_e32 v43, 31, v42
	v_ashrrev_i32_e32 v45, 31, v44
	v_ashrrev_i32_e32 v47, 31, v46
	v_ashrrev_i32_e32 v49, 31, v48
	v_ashrrev_i32_e32 v51, 31, v50
	v_ashrrev_i32_e32 v53, 31, v52
	v_ashrrev_i32_e32 v55, 31, v54
	v_ashrrev_i32_e32 v59, 31, v58
	v_ashrrev_i32_e32 v61, 31, v60
	v_ashrrev_i32_e32 v63, 31, v62
	v_ashrrev_i32_e32 v65, 31, v64
	v_ashrrev_i32_e32 v67, 31, v66
	v_ashrrev_i32_e32 v69, 31, v68
	v_ashrrev_i32_e32 v71, 31, v70
	v_ashrrev_i32_e32 v73, 31, v72
	v_lshlrev_b64 v[6:7], 13, v[6:7]
	v_lshlrev_b64 v[8:9], 13, v[8:9]
	v_lshlrev_b64 v[10:11], 13, v[10:11]
	v_lshlrev_b64 v[12:13], 13, v[12:13]
	v_lshlrev_b64 v[14:15], 13, v[14:15]
	v_lshlrev_b64 v[16:17], 13, v[16:17]
	v_lshl_add_u64 v[56:57], s[4:5], 1, v[2:3]
	v_lshl_add_u64 v[4:5], v[74:75], 0, v[4:5]
	v_lshlrev_b64 v[18:19], 13, v[18:19]
	v_lshlrev_b64 v[40:41], 13, v[40:41]
	v_lshlrev_b64 v[42:43], 13, v[42:43]
	v_lshlrev_b64 v[44:45], 13, v[44:45]
	v_lshlrev_b64 v[46:47], 13, v[46:47]
	v_lshlrev_b64 v[48:49], 13, v[48:49]
	v_lshlrev_b64 v[50:51], 13, v[50:51]
	v_lshlrev_b64 v[52:53], 13, v[52:53]
	v_lshlrev_b64 v[54:55], 13, v[54:55]
	v_lshlrev_b64 v[58:59], 14, v[58:59]
	v_lshlrev_b64 v[60:61], 14, v[60:61]
	v_lshlrev_b64 v[62:63], 14, v[62:63]
	v_lshlrev_b64 v[64:65], 14, v[64:65]
	v_lshlrev_b64 v[66:67], 14, v[66:67]
	v_lshlrev_b64 v[68:69], 14, v[68:69]
	v_lshlrev_b64 v[70:71], 14, v[70:71]
	v_lshlrev_b64 v[72:73], 14, v[72:73]
	v_lshl_add_u64 v[76:77], v[74:75], 0, v[6:7]
	v_lshl_add_u64 v[78:79], v[74:75], 0, v[8:9]
	v_lshl_add_u64 v[80:81], v[74:75], 0, v[10:11]
	v_lshl_add_u64 v[82:83], v[74:75], 0, v[12:13]
	v_lshl_add_u64 v[84:85], v[74:75], 0, v[14:15]
	v_lshl_add_u64 v[86:87], v[74:75], 0, v[16:17]
	v_lshl_add_u64 v[88:89], v[74:75], 0, v[18:19]
	v_lshl_add_u64 v[90:91], v[74:75], 0, v[40:41]
	v_lshl_add_u64 v[92:93], v[74:75], 0, v[42:43]
	v_lshl_add_u64 v[94:95], v[74:75], 0, v[44:45]
	v_lshl_add_u64 v[96:97], v[74:75], 0, v[46:47]
	v_lshl_add_u64 v[98:99], v[74:75], 0, v[48:49]
	v_lshl_add_u64 v[100:101], v[74:75], 0, v[50:51]
	v_lshl_add_u64 v[102:103], v[74:75], 0, v[52:53]
	v_lshl_add_u64 v[104:105], v[74:75], 0, v[54:55]
	v_lshl_add_u64 v[106:107], v[56:57], 0, v[58:59]
	v_lshl_add_u64 v[108:109], v[56:57], 0, v[60:61]
	v_lshl_add_u64 v[110:111], v[56:57], 0, v[62:63]
	v_lshl_add_u64 v[112:113], v[56:57], 0, v[64:65]
	v_lshl_add_u64 v[114:115], v[56:57], 0, v[66:67]
	v_lshl_add_u64 v[116:117], v[56:57], 0, v[68:69]
	v_lshl_add_u64 v[118:119], v[56:57], 0, v[70:71]
	global_load_dwordx4 v[4:7], v[4:5], off nt
	v_lshl_add_u64 v[120:121], v[56:57], 0, v[72:73]
	global_load_dwordx4 v[8:11], v[76:77], off nt
	global_load_dwordx4 v[12:15], v[78:79], off nt
	global_load_dwordx4 v[16:19], v[80:81], off nt
	global_load_dwordx4 v[40:43], v[82:83], off nt
	global_load_dwordx4 v[44:47], v[84:85], off nt
	global_load_dwordx4 v[48:51], v[86:87], off nt
	global_load_dwordx4 v[52:55], v[88:89], off nt
	global_load_dwordx4 v[56:59], v[90:91], off nt
	global_load_dwordx4 v[60:63], v[92:93], off nt
	global_load_dwordx4 v[64:67], v[94:95], off nt
	global_load_dwordx4 v[68:71], v[96:97], off nt
	global_load_dwordx4 v[72:75], v[98:99], off nt
	global_load_dwordx4 v[76:79], v[100:101], off nt
	global_load_dwordx4 v[80:83], v[102:103], off nt
	global_load_dwordx4 v[84:87], v[104:105], off nt
	v_add_u32_e32 v39, 0x410, v30
	v_add_u32_e32 v122, 0x418, v30
	v_add_u32_e32 v123, 0x820, v30
	v_add_u32_e32 v124, 0x828, v30
	v_add_u32_e32 v125, 0xc30, v30
	v_add_u32_e32 v126, 0xc38, v30
	v_add_u32_e32 v127, 0x1040, v30
	v_add_u32_e32 v128, 0x1048, v30
	v_add_u32_e32 v129, 0x1450, v30
	v_add_u32_e32 v130, 0x1458, v30
	v_add_u32_e32 v131, 0x1860, v30
	v_add_u32_e32 v132, 0x1868, v30
	v_add_u32_e32 v133, 0x1c70, v30
	v_add_u32_e32 v134, 0x1c78, v30
	v_add_u32_e32 v135, 0x2080, v30
	v_add_u32_e32 v136, 0x2088, v30
	v_add_u32_e32 v137, 0x2490, v30
	v_add_u32_e32 v138, 0x2498, v30
	v_add_u32_e32 v139, 0x28a0, v30
	v_add_u32_e32 v140, 0x28a8, v30
	v_add_u32_e32 v141, 0x2cb0, v30
	v_add_u32_e32 v142, 0x2cb8, v30
	v_add_u32_e32 v143, 0x30c0, v30
	v_add_u32_e32 v144, 0x30c8, v30
	v_add_u32_e32 v145, 0x34d0, v30
	v_add_u32_e32 v146, 0x34d8, v30
	v_add_u32_e32 v147, 0x38e0, v30
	v_add_u32_e32 v148, 0x38e8, v30
	v_add_u32_e32 v149, 0x3cf0, v30
	v_add_u32_e32 v150, 0x3cf8, v30
	s_waitcnt vmcnt(15)
; #define LAS __attribute__((address_space(3)))
; __device__ __forceinline__ void transpose_item(const float* W, int K, int N, bf16_t* WT, int gate, const float* kscale, LAS float* scr, int item, int lane) {
;     ...
;     const int c = lane & 7;
;     f32x4 k0v = {1.f, 1.f, 1.f, 1.f}, k1v = k0v;
;     if (kscale) { k0v = *(const f32x4*)(kscale + k0 + 8 * c); k1v = *(const f32x4*)(kscale + k0 + 8 * c + 4); }
; #pragma unroll
;     for (int j = 0; j < 8; ++j) { const int n = (lane >> 3) + 8 * j; const LAS float* s = scr + (8 * c) * 65 + n;
;         u32x4 o; o.x = pk2(s[0 * 65] * k0v[0], s[1 * 65] * k0v[1]); o.y = pk2(s[2 * 65] * k0v[2], s[3 * 65] * k0v[3]); o.z = pk2(s[4 * 65] * k1v[0], s[5 * 65] * k1v[1]); o.w = pk2(s[6 * 65] * k1v[2], s[7 * 65] * k1v[3]);
;         const int nn = n0 + n; const int row = gate < 0 ? nn : (256 * (nn >> 7) + 128 * gate + (nn & 127));
;         *(u32x4*)(WT + (size_t)row * K + k0 + 8 * c) = o; }
	ds_write2_b32 v30, v4, v5 offset1:1
	ds_write2_b32 v30, v6, v7 offset0:2 offset1:3
	s_waitcnt vmcnt(14)
	ds_write2_b32 v39, v8, v9 offset1:1
	ds_write2_b32 v122, v10, v11 offset1:1
	s_waitcnt vmcnt(13)
	ds_write2_b32 v123, v12, v13 offset1:1
	ds_write2_b32 v124, v14, v15 offset1:1
	s_waitcnt vmcnt(12)
	ds_write2_b32 v125, v16, v17 offset1:1
	ds_write2_b32 v126, v18, v19 offset1:1
	s_waitcnt vmcnt(11)
	ds_write2_b32 v127, v40, v41 offset1:1
	ds_write2_b32 v128, v42, v43 offset1:1
	s_waitcnt vmcnt(10)
	ds_write2_b32 v129, v44, v45 offset1:1
	ds_write2_b32 v130, v46, v47 offset1:1
	s_waitcnt vmcnt(9)
	ds_write2_b32 v131, v48, v49 offset1:1
	ds_write2_b32 v132, v50, v51 offset1:1
	s_waitcnt vmcnt(8)
	ds_write2_b32 v133, v52, v53 offset1:1
	ds_write2_b32 v134, v54, v55 offset1:1
	s_waitcnt vmcnt(7)
	ds_write2_b32 v135, v56, v57 offset1:1
	ds_write2_b32 v136, v58, v59 offset1:1
	s_waitcnt vmcnt(6)
	ds_write2_b32 v137, v60, v61 offset1:1
	ds_write2_b32 v138, v62, v63 offset1:1
	s_waitcnt vmcnt(5)
	ds_write2_b32 v139, v64, v65 offset1:1
	ds_write2_b32 v140, v66, v67 offset1:1
	s_waitcnt vmcnt(4)
	ds_write2_b32 v141, v68, v69 offset1:1
	ds_write2_b32 v142, v70, v71 offset1:1
	s_waitcnt vmcnt(3)
	ds_write2_b32 v143, v72, v73 offset1:1
	ds_write2_b32 v144, v74, v75 offset1:1
	s_waitcnt vmcnt(2)
	ds_write2_b32 v145, v76, v77 offset1:1
	ds_write2_b32 v146, v78, v79 offset1:1
	s_waitcnt vmcnt(1)
	ds_write2_b32 v147, v80, v81 offset1:1
	ds_write2_b32 v148, v82, v83 offset1:1
	s_waitcnt vmcnt(0)
	ds_write2_b32 v149, v84, v85 offset1:1
	ds_write2_b32 v150, v86, v87 offset1:1
	s_waitcnt lgkmcnt(0)
	v_add_u32_e32 v151, 0x400, v31
	v_add_u32_e32 v152, 0x400, v32
	v_add_u32_e32 v153, 0x400, v33
	v_add_u32_e32 v154, 0x400, v34
	v_add_u32_e32 v155, 0x400, v35
	v_add_u32_e32 v156, 0x400, v36
	v_add_u32_e32 v157, 0x400, v37
	v_add_u32_e32 v158, 0x400, v38
	ds_read2_b32 v[4:5], v31 offset1:65
	ds_read2_b32 v[6:7], v31 offset0:130 offset1:195
	ds_read2_b32 v[8:9], v151 offset0:4 offset1:69
	ds_read2_b32 v[10:11], v151 offset0:134 offset1:199
	ds_read2_b32 v[12:13], v32 offset1:65
	ds_read2_b32 v[14:15], v32 offset0:130 offset1:195
	ds_read2_b32 v[16:17], v152 offset0:4 offset1:69
	ds_read2_b32 v[18:19], v152 offset0:134 offset1:199
	ds_read2_b32 v[40:41], v33 offset1:65
	ds_read2_b32 v[42:43], v33 offset0:130 offset1:195
	ds_read2_b32 v[44:45], v153 offset0:4 offset1:69
	ds_read2_b32 v[46:47], v153 offset0:134 offset1:199
	ds_read2_b32 v[48:49], v34 offset1:65
	ds_read2_b32 v[50:51], v34 offset0:130 offset1:195
	ds_read2_b32 v[52:53], v154 offset0:4 offset1:69
	ds_read2_b32 v[54:55], v154 offset0:134 offset1:199
	ds_read2_b32 v[56:57], v35 offset1:65
	ds_read2_b32 v[58:59], v35 offset0:130 offset1:195
	ds_read2_b32 v[60:61], v155 offset0:4 offset1:69
	ds_read2_b32 v[62:63], v155 offset0:134 offset1:199
	ds_read2_b32 v[64:65], v36 offset1:65
	ds_read2_b32 v[66:67], v36 offset0:130 offset1:195
	ds_read2_b32 v[68:69], v156 offset0:4 offset1:69
	ds_read2_b32 v[70:71], v156 offset0:134 offset1:199
	ds_read2_b32 v[72:73], v37 offset1:65
	ds_read2_b32 v[74:75], v37 offset0:130 offset1:195
	ds_read2_b32 v[76:77], v157 offset0:4 offset1:69
	ds_read2_b32 v[78:79], v157 offset0:134 offset1:199
	ds_read2_b32 v[80:81], v38 offset1:65
	ds_read2_b32 v[82:83], v38 offset0:130 offset1:195
	ds_read2_b32 v[84:85], v158 offset0:4 offset1:69
	ds_read2_b32 v[86:87], v158 offset0:134 offset1:199
	s_waitcnt lgkmcnt(14)
	v_cvt_pk_bf16_f32 v4, v4, v5
	v_cvt_pk_bf16_f32 v5, v6, v7
	v_cvt_pk_bf16_f32 v6, v8, v9
	v_cvt_pk_bf16_f32 v7, v10, v11
	v_cvt_pk_bf16_f32 v8, v12, v13
	v_cvt_pk_bf16_f32 v9, v14, v15
	v_cvt_pk_bf16_f32 v10, v16, v17
	v_cvt_pk_bf16_f32 v11, v18, v19
	v_cvt_pk_bf16_f32 v12, v40, v41
	v_cvt_pk_bf16_f32 v13, v42, v43
	v_cvt_pk_bf16_f32 v14, v44, v45
	v_cvt_pk_bf16_f32 v15, v46, v47
	v_cvt_pk_bf16_f32 v16, v48, v49
	v_cvt_pk_bf16_f32 v17, v50, v51
	v_cvt_pk_bf16_f32 v18, v52, v53
	v_cvt_pk_bf16_f32 v19, v54, v55
	v_cvt_pk_bf16_f32 v40, v56, v57
	v_cvt_pk_bf16_f32 v41, v58, v59
	s_waitcnt lgkmcnt(13)
	v_cvt_pk_bf16_f32 v42, v60, v61
	s_waitcnt lgkmcnt(12)
	v_cvt_pk_bf16_f32 v43, v62, v63
	s_waitcnt lgkmcnt(11)
	v_cvt_pk_bf16_f32 v44, v64, v65
	s_waitcnt lgkmcnt(10)
	v_cvt_pk_bf16_f32 v45, v66, v67
	s_waitcnt lgkmcnt(9)
	v_cvt_pk_bf16_f32 v46, v68, v69
	s_waitcnt lgkmcnt(8)
	v_cvt_pk_bf16_f32 v47, v70, v71
	s_waitcnt lgkmcnt(7)
	v_cvt_pk_bf16_f32 v48, v72, v73
	s_waitcnt lgkmcnt(6)
	v_cvt_pk_bf16_f32 v49, v74, v75
	s_waitcnt lgkmcnt(5)
	v_cvt_pk_bf16_f32 v50, v76, v77
	s_waitcnt lgkmcnt(4)
	v_cvt_pk_bf16_f32 v51, v78, v79
	s_waitcnt lgkmcnt(3)
	v_cvt_pk_bf16_f32 v52, v80, v81
	s_waitcnt lgkmcnt(2)
	v_cvt_pk_bf16_f32 v53, v82, v83
	s_waitcnt lgkmcnt(1)
	v_cvt_pk_bf16_f32 v54, v84, v85
	s_waitcnt lgkmcnt(0)
	v_cvt_pk_bf16_f32 v55, v86, v87
	global_store_dwordx4 v[106:107], v[4:7], off nt
	global_store_dwordx4 v[108:109], v[8:11], off nt
	global_store_dwordx4 v[110:111], v[12:15], off nt
	global_store_dwordx4 v[112:113], v[16:19], off nt
	global_store_dwordx4 v[114:115], v[40:43], off nt
	global_store_dwordx4 v[116:117], v[44:47], off nt
	global_store_dwordx4 v[118:119], v[48:51], off nt
	global_store_dwordx4 v[120:121], v[52:55], off nt
	s_waitcnt lgkmcnt(0)
	s_add_i32 s0, s0, s92
	s_add_i32 s3, s3, s38
	s_cmpk_lt_i32 s0, 0x1000
	s_cbranch_scc1 .LBB0_43

; __device__ __forceinline__ float bflo(unsigned w) { return __uint_as_float(w << 16); }
; __device__ __forceinline__ float bfhi(unsigned w) { return __uint_as_float(w & 0xffff0000u); }
; __global__ void __launch_bounds__(512, 2) mega(Params p, int ph_lo, int ph_hi) {
;     ...
;         for (int idx = gt; idx < NTOK * 128; idx += NGT) {
;             const int t = idx >> 7, c8 = (idx & 127) * 8, pos = t & (SEQ - 1);
;             float a[8];
;             { const f32x4 b0 = *(const f32x4*)(p.conv_b + c8), b1 = *(const f32x4*)(p.conv_b + c8 + 4); a[0] = b0[0]; a[1] = b0[1]; a[2] = b0[2]; a[3] = b0[3]; a[4] = b1[0]; a[5] = b1[1]; a[6] = b1[2]; a[7] = b1[3]; }
; #pragma unroll
;             for (int j = 0; j < 4; ++j) {
;                 if (pos - 3 + j >= 0) {
;                     const u32x4 xw = *(const u32x4*)(BIG + (size_t)(t - 3 + j) * INC + c8);
;                     const f32x4 w0 = *(const f32x4*)(p.conv_w + j * 1024 + c8), w1 = *(const f32x4*)(p.conv_w + j * 1024 + c8 + 4);
;                     a[0] += w0[0] * bflo(xw.x); a[1] += w0[1] * bfhi(xw.x); a[2] += w0[2] * bflo(xw.y); a[3] += w0[3] * bfhi(xw.y);
;                     a[4] += w1[0] * bflo(xw.z); a[5] += w1[1] * bfhi(xw.z); a[6] += w1[2] * bflo(xw.w); a[7] += w1[3] * bfhi(xw.w);
;                 }
;             }
;             u32x4 o; o.x = pk2(a[0], a[1]); o.y = pk2(a[2], a[3]); o.z = pk2(a[4], a[5]); o.w = pk2(a[6], a[7]);
;             *(u32x4*)(XN + (size_t)t * 1024 + c8) = o;
;         }
.Lcv_A:
	v_add_u32_e32 v25, s38, v9
	v_ashrrev_i32_e32 v26, 7, v25
	v_add_u32_e32 v27, -3, v26
	v_mad_i64_i32 v[28:29], s[12:13], v27, s18, v[168:169]
	v_lshl_add_u64 v[30:31], v[28:29], 0, s[98:99]
	v_lshl_add_u64 v[32:33], v[30:31], 0, s[98:99]
	v_lshl_add_u64 v[34:35], v[32:33], 0, s[98:99]
	global_load_dwordx4 v[152:155], v[28:29], off
	global_load_dwordx4 v[156:159], v[30:31], off
	global_load_dwordx4 v[160:163], v[32:33], off
	global_load_dwordx4 v[164:167], v[34:35], off
	v_and_b32_e32 v15, 0x1fff, v14
	v_cmp_lt_u32_e64 s[6:7], 2, v15
	v_cmp_lt_u32_e64 s[8:9], 1, v15
	v_cmp_ne_u32_e64 s[10:11], 0, v15
	v_ashrrev_i32_e32 v15, 31, v14
	v_lshlrev_b64 v[16:17], 11, v[14:15]
	v_lshl_add_u64 v[16:17], v[170:171], 0, v[16:17]
	s_waitcnt vmcnt(4)
	v_mov_b64_e32 v[4:5], v[96:97]
	v_mov_b64_e32 v[6:7], v[98:99]
	v_mov_b64_e32 v[0:1], v[100:101]
	v_mov_b64_e32 v[2:3], v[102:103]
	v_cndmask_b32_e64 v36, 0, v136, s[6:7]
	v_cndmask_b32_e64 v37, 0, v137, s[6:7]
	v_cndmask_b32_e64 v38, 0, v138, s[6:7]
	v_cndmask_b32_e64 v39, 0, v139, s[6:7]
	v_lshlrev_b32_e32 v40, 16, v36
	v_and_b32_e32 v41, 0xffff0000, v36
	v_lshlrev_b32_e32 v42, 16, v37
	v_and_b32_e32 v43, 0xffff0000, v37
	v_lshlrev_b32_e32 v44, 16, v38
	v_and_b32_e32 v45, 0xffff0000, v38
	v_lshlrev_b32_e32 v46, 16, v39
	v_and_b32_e32 v47, 0xffff0000, v39
	v_pk_fma_f32 v[4:5], v[104:105], v[40:41], v[4:5]
	v_pk_fma_f32 v[6:7], v[106:107], v[42:43], v[6:7]
	v_pk_fma_f32 v[0:1], v[108:109], v[44:45], v[0:1]
	v_pk_fma_f32 v[2:3], v[110:111], v[46:47], v[2:3]
	v_cndmask_b32_e64 v36, 0, v140, s[8:9]
	v_cndmask_b32_e64 v37, 0, v141, s[8:9]
	v_cndmask_b32_e64 v38, 0, v142, s[8:9]
	v_cndmask_b32_e64 v39, 0, v143, s[8:9]
	v_lshlrev_b32_e32 v40, 16, v36
	v_and_b32_e32 v41, 0xffff0000, v36
	v_lshlrev_b32_e32 v42, 16, v37
	v_and_b32_e32 v43, 0xffff0000, v37
	v_lshlrev_b32_e32 v44, 16, v38
	v_and_b32_e32 v45, 0xffff0000, v38
	v_lshlrev_b32_e32 v46, 16, v39
	v_and_b32_e32 v47, 0xffff0000, v39
	v_pk_fma_f32 v[4:5], v[112:113], v[40:41], v[4:5]
	v_pk_fma_f32 v[6:7], v[114:115], v[42:43], v[6:7]
	v_pk_fma_f32 v[0:1], v[116:117], v[44:45], v[0:1]
	v_pk_fma_f32 v[2:3], v[118:119], v[46:47], v[2:3]
	v_cndmask_b32_e64 v36, 0, v144, s[10:11]
	v_cndmask_b32_e64 v37, 0, v145, s[10:11]
	v_cndmask_b32_e64 v38, 0, v146, s[10:11]
	v_cndmask_b32_e64 v39, 0, v147, s[10:11]
	v_lshlrev_b32_e32 v40, 16, v36
	v_and_b32_e32 v41, 0xffff0000, v36
	v_lshlrev_b32_e32 v42, 16, v37
	v_and_b32_e32 v43, 0xffff0000, v37
	v_lshlrev_b32_e32 v44, 16, v38
	v_and_b32_e32 v45, 0xffff0000, v38
	v_lshlrev_b32_e32 v46, 16, v39
	v_and_b32_e32 v47, 0xffff0000, v39
	v_pk_fma_f32 v[4:5], v[120:121], v[40:41], v[4:5]
	v_pk_fma_f32 v[6:7], v[122:123], v[42:43], v[6:7]
	v_pk_fma_f32 v[0:1], v[124:125], v[44:45], v[0:1]
	v_pk_fma_f32 v[2:3], v[126:127], v[46:47], v[2:3]
	v_lshlrev_b32_e32 v40, 16, v148
	v_and_b32_e32 v41, 0xffff0000, v148
	v_lshlrev_b32_e32 v42, 16, v149
	v_and_b32_e32 v43, 0xffff0000, v149
	v_lshlrev_b32_e32 v44, 16, v150
	v_and_b32_e32 v45, 0xffff0000, v150
	v_lshlrev_b32_e32 v46, 16, v151
	v_and_b32_e32 v47, 0xffff0000, v151
	v_pk_fma_f32 v[4:5], v[128:129], v[40:41], v[4:5]
	v_pk_fma_f32 v[6:7], v[130:131], v[42:43], v[6:7]
	v_pk_fma_f32 v[0:1], v[132:133], v[44:45], v[0:1]
	v_pk_fma_f32 v[2:3], v[134:135], v[46:47], v[2:3]
	v_cvt_pk_bf16_f32 v36, v4, v5
	v_cvt_pk_bf16_f32 v37, v6, v7
	v_cvt_pk_bf16_f32 v38, v0, v1
	v_cvt_pk_bf16_f32 v39, v2, v3
	global_store_dwordx4 v[16:17], v[36:39], off nt
	v_mov_b32_e32 v9, v25
	v_mov_b32_e32 v14, v26
	v_cmp_lt_i32_e32 vcc, s19, v9
	s_or_b64 s[4:5], vcc, s[4:5]
	s_andn2_b64 exec, exec, s[4:5]
	s_cbranch_execz .LBB0_92
; __device__ __forceinline__ float bflo(unsigned w) { return __uint_as_float(w << 16); }
; __device__ __forceinline__ float bfhi(unsigned w) { return __uint_as_float(w & 0xffff0000u); }
; __global__ void __launch_bounds__(512, 2) mega(Params p, int ph_lo, int ph_hi) {
;     ...
;         for (int idx = gt; idx < NTOK * 128; idx += NGT) {
;             const int t = idx >> 7, c8 = (idx & 127) * 8, pos = t & (SEQ - 1);
;             float a[8];
;             { const f32x4 b0 = *(const f32x4*)(p.conv_b + c8), b1 = *(const f32x4*)(p.conv_b + c8 + 4); a[0] = b0[0]; a[1] = b0[1]; a[2] = b0[2]; a[3] = b0[3]; a[4] = b1[0]; a[5] = b1[1]; a[6] = b1[2]; a[7] = b1[3]; }
; #pragma unroll
;             for (int j = 0; j < 4; ++j) {
;                 if (pos - 3 + j >= 0) {
;                     const u32x4 xw = *(const u32x4*)(BIG + (size_t)(t - 3 + j) * INC + c8);
;                     const f32x4 w0 = *(const f32x4*)(p.conv_w + j * 1024 + c8), w1 = *(const f32x4*)(p.conv_w + j * 1024 + c8 + 4);
;                     a[0] += w0[0] * bflo(xw.x); a[1] += w0[1] * bfhi(xw.x); a[2] += w0[2] * bflo(xw.y); a[3] += w0[3] * bfhi(xw.y);
;                     a[4] += w1[0] * bflo(xw.z); a[5] += w1[1] * bfhi(xw.z); a[6] += w1[2] * bflo(xw.w); a[7] += w1[3] * bfhi(xw.w);
;                 }
;             }
;             u32x4 o; o.x = pk2(a[0], a[1]); o.y = pk2(a[2], a[3]); o.z = pk2(a[4], a[5]); o.w = pk2(a[6], a[7]);
;             *(u32x4*)(XN + (size_t)t * 1024 + c8) = o;
;         }
.Lcv_B:
	v_add_u32_e32 v25, s38, v9
	v_ashrrev_i32_e32 v26, 7, v25
	v_add_u32_e32 v27, -3, v26
	v_mad_i64_i32 v[28:29], s[12:13], v27, s18, v[168:169]
	v_lshl_add_u64 v[30:31], v[28:29], 0, s[98:99]
	v_lshl_add_u64 v[32:33], v[30:31], 0, s[98:99]
	v_lshl_add_u64 v[34:35], v[32:33], 0, s[98:99]
	global_load_dwordx4 v[136:139], v[28:29], off
	global_load_dwordx4 v[140:143], v[30:31], off
	global_load_dwordx4 v[144:147], v[32:33], off
	global_load_dwordx4 v[148:151], v[34:35], off
	v_and_b32_e32 v15, 0x1fff, v14
	v_cmp_lt_u32_e64 s[6:7], 2, v15
	v_cmp_lt_u32_e64 s[8:9], 1, v15
	v_cmp_ne_u32_e64 s[10:11], 0, v15
	v_ashrrev_i32_e32 v15, 31, v14
	v_lshlrev_b64 v[16:17], 11, v[14:15]
	v_lshl_add_u64 v[16:17], v[170:171], 0, v[16:17]
	s_waitcnt vmcnt(4)
	v_mov_b64_e32 v[4:5], v[96:97]
	v_mov_b64_e32 v[6:7], v[98:99]
	v_mov_b64_e32 v[0:1], v[100:101]
	v_mov_b64_e32 v[2:3], v[102:103]
	v_cndmask_b32_e64 v36, 0, v152, s[6:7]
	v_cndmask_b32_e64 v37, 0, v153, s[6:7]
	v_cndmask_b32_e64 v38, 0, v154, s[6:7]
	v_cndmask_b32_e64 v39, 0, v155, s[6:7]
	v_lshlrev_b32_e32 v40, 16, v36
	v_and_b32_e32 v41, 0xffff0000, v36
	v_lshlrev_b32_e32 v42, 16, v37
	v_and_b32_e32 v43, 0xffff0000, v37
	v_lshlrev_b32_e32 v44, 16, v38
	v_and_b32_e32 v45, 0xffff0000, v38
	v_lshlrev_b32_e32 v46, 16, v39
	v_and_b32_e32 v47, 0xffff0000, v39
	v_pk_fma_f32 v[4:5], v[104:105], v[40:41], v[4:5]
	v_pk_fma_f32 v[6:7], v[106:107], v[42:43], v[6:7]
	v_pk_fma_f32 v[0:1], v[108:109], v[44:45], v[0:1]
	v_pk_fma_f32 v[2:3], v[110:111], v[46:47], v[2:3]
	v_cndmask_b32_e64 v36, 0, v156, s[8:9]
	v_cndmask_b32_e64 v37, 0, v157, s[8:9]
	v_cndmask_b32_e64 v38, 0, v158, s[8:9]
	v_cndmask_b32_e64 v39, 0, v159, s[8:9]
	v_lshlrev_b32_e32 v40, 16, v36
	v_and_b32_e32 v41, 0xffff0000, v36
	v_lshlrev_b32_e32 v42, 16, v37
	v_and_b32_e32 v43, 0xffff0000, v37
	v_lshlrev_b32_e32 v44, 16, v38
	v_and_b32_e32 v45, 0xffff0000, v38
	v_lshlrev_b32_e32 v46, 16, v39
	v_and_b32_e32 v47, 0xffff0000, v39
	v_pk_fma_f32 v[4:5], v[112:113], v[40:41], v[4:5]
	v_pk_fma_f32 v[6:7], v[114:115], v[42:43], v[6:7]
	v_pk_fma_f32 v[0:1], v[116:117], v[44:45], v[0:1]
	v_pk_fma_f32 v[2:3], v[118:119], v[46:47], v[2:3]
	v_cndmask_b32_e64 v36, 0, v160, s[10:11]
	v_cndmask_b32_e64 v37, 0, v161, s[10:11]
	v_cndmask_b32_e64 v38, 0, v162, s[10:11]
	v_cndmask_b32_e64 v39, 0, v163, s[10:11]
	v_lshlrev_b32_e32 v40, 16, v36
	v_and_b32_e32 v41, 0xffff0000, v36
	v_lshlrev_b32_e32 v42, 16, v37
	v_and_b32_e32 v43, 0xffff0000, v37
	v_lshlrev_b32_e32 v44, 16, v38
	v_and_b32_e32 v45, 0xffff0000, v38
	v_lshlrev_b32_e32 v46, 16, v39
	v_and_b32_e32 v47, 0xffff0000, v39
	v_pk_fma_f32 v[4:5], v[120:121], v[40:41], v[4:5]
	v_pk_fma_f32 v[6:7], v[122:123], v[42:43], v[6:7]
	v_pk_fma_f32 v[0:1], v[124:125], v[44:45], v[0:1]
	v_pk_fma_f32 v[2:3], v[126:127], v[46:47], v[2:3]
	v_lshlrev_b32_e32 v40, 16, v164
	v_and_b32_e32 v41, 0xffff0000, v164
	v_lshlrev_b32_e32 v42, 16, v165
	v_and_b32_e32 v43, 0xffff0000, v165
	v_lshlrev_b32_e32 v44, 16, v166
	v_and_b32_e32 v45, 0xffff0000, v166
	v_lshlrev_b32_e32 v46, 16, v167
	v_and_b32_e32 v47, 0xffff0000, v167
	v_pk_fma_f32 v[4:5], v[128:129], v[40:41], v[4:5]
	v_pk_fma_f32 v[6:7], v[130:131], v[42:43], v[6:7]
	v_pk_fma_f32 v[0:1], v[132:133], v[44:45], v[0:1]
	v_pk_fma_f32 v[2:3], v[134:135], v[46:47], v[2:3]
	v_cvt_pk_bf16_f32 v36, v4, v5
	v_cvt_pk_bf16_f32 v37, v6, v7
	v_cvt_pk_bf16_f32 v38, v0, v1
	v_cvt_pk_bf16_f32 v39, v2, v3
	global_store_dwordx4 v[16:17], v[36:39], off nt
	v_mov_b32_e32 v9, v25
	v_mov_b32_e32 v14, v26
	v_cmp_lt_i32_e32 vcc, s19, v9
	s_or_b64 s[4:5], vcc, s[4:5]
	s_andn2_b64 exec, exec, s[4:5]
	s_cbranch_execz .LBB0_92
	s_branch .Lcv_A

; #define LAS __attribute__((address_space(3)))
; __device__ __forceinline__ void lds_wait() { asm volatile("s_waitcnt lgkmcnt(0)" ::: "memory"); }
; __device__ __forceinline__ void transpose_item(const float* W, int K, int N, bf16_t* WT, int gate, const float* kscale, LAS float* scr, int item, int lane) {
;     const int nblk = N / 64, kb = item / nblk, nb = item % nblk, k0 = 64 * kb, n0 = 64 * nb;
;     const int c4 = (lane & 15) * 4, kr = lane >> 4;
;     f32x4 v[16];
; #pragma unroll
;     for (int i = 0; i < 16; ++i) v[i] = __builtin_nontemporal_load((const f32x4*)(W + (size_t)(k0 + 4 * i + kr) * N + n0 + c4));
; #pragma unroll
;     for (int i = 0; i < 16; ++i) { LAS float* d = scr + (4 * i + kr) * 65 + c4; d[0] = v[i][0]; d[1] = v[i][1]; d[2] = v[i][2]; d[3] = v[i][3]; }
;     lds_wait();
.LBB0_562:
	s_mul_hi_i32 s4, s3, 0x2aaaaaab
	s_lshr_b32 s5, s4, 31
	s_ashr_i32 s4, s4, 4
	s_add_i32 s5, s4, s5
	s_lshl_b32 s4, s5, 6
	s_mulk_i32 s5, 0xe800
	s_add_i32 s6, s0, s5
	v_add_u32_e32 v43, s4, v8
	s_ashr_i32 s7, s6, 31
	s_ashr_i32 s5, s4, 31
	v_add_u32_e32 v48, 4, v43
	v_add_u32_e32 v49, 8, v43
	v_add_u32_e32 v50, 12, v43
	v_add_u32_e32 v51, 16, v43
	v_add_u32_e32 v52, 20, v43
	v_add_u32_e32 v53, 24, v43
	v_add_u32_e32 v54, 28, v43
	v_add_u32_e32 v55, 32, v43
	v_add_u32_e32 v56, 36, v43
	v_add_u32_e32 v57, 40, v43
	v_add_u32_e32 v58, 44, v43
	v_add_u32_e32 v59, 48, v43
	v_add_u32_e32 v60, 52, v43
	v_add_u32_e32 v61, 56, v43
	v_add_u32_e32 v62, 60, v43
	v_add_u32_e32 v44, s6, v9
	v_lshl_add_u64 v[46:47], s[6:7], 2, v[2:3]
	v_lshl_add_u64 v[108:109], s[4:5], 2, v[4:5]
	v_lshl_add_u64 v[110:111], s[4:5], 1, v[6:7]
	v_ashrrev_i32_e32 v45, 31, v44
	v_mad_i64_i32 v[76:77], s[4:5], v43, s1, v[46:47]
	v_mad_i64_i32 v[78:79], s[4:5], v48, s1, v[46:47]
	v_mad_i64_i32 v[80:81], s[4:5], v49, s1, v[46:47]
	v_mad_i64_i32 v[82:83], s[4:5], v50, s1, v[46:47]
	v_mad_i64_i32 v[84:85], s[4:5], v51, s1, v[46:47]
	v_mad_i64_i32 v[86:87], s[4:5], v52, s1, v[46:47]
	v_mad_i64_i32 v[88:89], s[4:5], v53, s1, v[46:47]
	v_mad_i64_i32 v[90:91], s[4:5], v54, s1, v[46:47]
	v_mad_i64_i32 v[92:93], s[4:5], v55, s1, v[46:47]
	v_mad_i64_i32 v[94:95], s[4:5], v56, s1, v[46:47]
	v_mad_i64_i32 v[96:97], s[4:5], v57, s1, v[46:47]
	v_mad_i64_i32 v[98:99], s[4:5], v58, s1, v[46:47]
	v_mad_i64_i32 v[100:101], s[4:5], v59, s1, v[46:47]
	v_mad_i64_i32 v[102:103], s[4:5], v60, s1, v[46:47]
	v_mad_i64_i32 v[104:105], s[4:5], v61, s1, v[46:47]
	v_mad_i64_i32 v[106:107], s[4:5], v62, s1, v[46:47]
	v_add_u32_e32 v112, 8, v44
	v_add_u32_e32 v114, 16, v44
	v_add_u32_e32 v116, 24, v44
	v_add_u32_e32 v118, 32, v44
	v_add_u32_e32 v120, 40, v44
	v_add_u32_e32 v122, 48, v44
	v_add_u32_e32 v124, 56, v44
	v_lshlrev_b64 v[126:127], 12, v[44:45]
	global_load_dwordx4 v[44:47], v[76:77], off nt
	global_load_dwordx4 v[48:51], v[78:79], off nt
	global_load_dwordx4 v[52:55], v[80:81], off nt
	global_load_dwordx4 v[56:59], v[82:83], off nt
	global_load_dwordx4 v[60:63], v[84:85], off nt
	global_load_dwordx4 v[64:67], v[86:87], off nt
	global_load_dwordx4 v[68:71], v[88:89], off nt
	global_load_dwordx4 v[72:75], v[90:91], off nt
	global_load_dwordx4 v[76:79], v[92:93], off nt
	global_load_dwordx4 v[80:83], v[94:95], off nt
	s_nop 0
	global_load_dwordx4 v[84:87], v[96:97], off nt
	global_load_dwordx4 v[88:91], v[98:99], off nt
	global_load_dwordx4 v[92:95], v[100:101], off nt
	s_nop 0
	global_load_dwordx4 v[96:99], v[102:103], off nt
	s_nop 0
	global_load_dwordx4 v[100:103], v[104:105], off nt
	s_nop 0
	global_load_dwordx4 v[104:107], v[106:107], off nt
	v_ashrrev_i32_e32 v113, 31, v112
	v_ashrrev_i32_e32 v115, 31, v114
	v_ashrrev_i32_e32 v117, 31, v116
	v_ashrrev_i32_e32 v119, 31, v118
	v_ashrrev_i32_e32 v121, 31, v120
	v_ashrrev_i32_e32 v123, 31, v122
	v_ashrrev_i32_e32 v125, 31, v124
	v_lshlrev_b64 v[112:113], 12, v[112:113]
	v_lshlrev_b64 v[114:115], 12, v[114:115]
	v_lshlrev_b64 v[116:117], 12, v[116:117]
	v_lshlrev_b64 v[118:119], 12, v[118:119]
	v_lshlrev_b64 v[120:121], 12, v[120:121]
	v_lshlrev_b64 v[122:123], 12, v[122:123]
	v_lshlrev_b64 v[124:125], 12, v[124:125]
	v_lshl_add_u64 v[126:127], v[110:111], 0, v[126:127]
	v_lshl_add_u64 v[112:113], v[110:111], 0, v[112:113]
	v_lshl_add_u64 v[114:115], v[110:111], 0, v[114:115]
	s_waitcnt vmcnt(15)
	ds_write2_b32 v11, v44, v45 offset1:1
	ds_write2_b32 v11, v46, v47 offset0:2 offset1:3
	s_waitcnt vmcnt(14)
	ds_write2_b32 v12, v48, v49 offset1:1
	ds_write2_b32 v13, v50, v51 offset1:1
	s_waitcnt vmcnt(13)
	ds_write2_b32 v14, v52, v53 offset1:1
	ds_write2_b32 v15, v54, v55 offset1:1
	s_waitcnt vmcnt(12)
	ds_write2_b32 v16, v56, v57 offset1:1
	ds_write2_b32 v17, v58, v59 offset1:1
	s_waitcnt vmcnt(11)
	ds_write2_b32 v18, v60, v61 offset1:1
	ds_write2_b32 v19, v62, v63 offset1:1
	s_waitcnt vmcnt(10)
	ds_write2_b32 v20, v64, v65 offset1:1
	ds_write2_b32 v21, v66, v67 offset1:1
	s_waitcnt vmcnt(9)
	ds_write2_b32 v22, v68, v69 offset1:1
	ds_write2_b32 v23, v70, v71 offset1:1
	s_waitcnt vmcnt(8)
	ds_write2_b32 v24, v72, v73 offset1:1
	ds_write2_b32 v25, v74, v75 offset1:1
	s_waitcnt vmcnt(7)
	ds_write2_b32 v26, v76, v77 offset1:1
	ds_write2_b32 v27, v78, v79 offset1:1
	s_waitcnt vmcnt(6)
	ds_write2_b32 v28, v80, v81 offset1:1
	ds_write2_b32 v29, v82, v83 offset1:1
	s_waitcnt vmcnt(5)
	ds_write2_b32 v30, v84, v85 offset1:1
	ds_write2_b32 v31, v86, v87 offset1:1
	s_waitcnt vmcnt(4)
	ds_write2_b32 v32, v88, v89 offset1:1
	ds_write2_b32 v33, v90, v91 offset1:1
	s_waitcnt vmcnt(3)
	ds_write2_b32 v34, v92, v93 offset1:1
	ds_write2_b32 v35, v94, v95 offset1:1
	s_waitcnt vmcnt(2)
	ds_write2_b32 v36, v96, v97 offset1:1
	ds_write2_b32 v37, v98, v99 offset1:1
	s_waitcnt vmcnt(1)
	ds_write2_b32 v38, v100, v101 offset1:1
	ds_write2_b32 v39, v102, v103 offset1:1
	s_waitcnt vmcnt(0)
	ds_write2_b32 v40, v104, v105 offset1:1
	ds_write2_b32 v41, v106, v107 offset1:1
	s_waitcnt lgkmcnt(0)
; #define LAS __attribute__((address_space(3)))
; __device__ __forceinline__ void transpose_item(const float* W, int K, int N, bf16_t* WT, int gate, const float* kscale, LAS float* scr, int item, int lane) {
;     ...
;     const int c = lane & 7;
;     f32x4 k0v = {1.f, 1.f, 1.f, 1.f}, k1v = k0v;
;     if (kscale) { k0v = *(const f32x4*)(kscale + k0 + 8 * c); k1v = *(const f32x4*)(kscale + k0 + 8 * c + 4); }
; #pragma unroll
;     for (int j = 0; j < 8; ++j) { const int n = (lane >> 3) + 8 * j; const LAS float* s = scr + (8 * c) * 65 + n;
;         u32x4 o; o.x = pk2(s[0 * 65] * k0v[0], s[1 * 65] * k0v[1]); o.y = pk2(s[2 * 65] * k0v[2], s[3 * 65] * k0v[3]); o.z = pk2(s[4 * 65] * k1v[0], s[5 * 65] * k1v[1]); o.w = pk2(s[6 * 65] * k1v[2], s[7 * 65] * k1v[3]);
;         const int nn = n0 + n; const int row = gate < 0 ? nn : (256 * (nn >> 7) + 128 * gate + (nn & 127));
;         *(u32x4*)(WT + (size_t)row * K + k0 + 8 * c) = o; }
	global_load_dwordx4 v[44:47], v[108:109], off
	global_load_dwordx4 v[48:51], v[108:109], off offset:16
	v_lshl_add_u64 v[116:117], v[110:111], 0, v[116:117]
	v_lshl_add_u64 v[118:119], v[110:111], 0, v[118:119]
	v_lshl_add_u64 v[120:121], v[110:111], 0, v[120:121]
	v_lshl_add_u64 v[122:123], v[110:111], 0, v[122:123]
	v_lshl_add_u64 v[110:111], v[110:111], 0, v[124:125]
	ds_read2_b32 v[52:53], v10 offset1:8
	ds_read2_b32 v[54:55], v10 offset0:65 offset1:73
	ds_read2_b32 v[56:57], v10 offset0:130 offset1:138
	ds_read2_b32 v[58:59], v10 offset0:195 offset1:203
	ds_read2_b32 v[60:61], v42 offset0:4 offset1:12
	ds_read2_b32 v[62:63], v42 offset0:69 offset1:77
	ds_read2_b32 v[64:65], v42 offset0:134 offset1:142
	ds_read2_b32 v[66:67], v42 offset0:199 offset1:207
	ds_read2_b32 v[68:69], v10 offset0:16 offset1:24
	ds_read2_b32 v[70:71], v10 offset0:81 offset1:89
	ds_read2_b32 v[72:73], v10 offset0:146 offset1:154
	ds_read2_b32 v[74:75], v10 offset0:211 offset1:219
	ds_read2_b32 v[76:77], v42 offset0:20 offset1:28
	ds_read2_b32 v[78:79], v42 offset0:85 offset1:93
	ds_read2_b32 v[80:81], v42 offset0:150 offset1:158
	ds_read2_b32 v[82:83], v42 offset0:215 offset1:223
	ds_read2_b32 v[84:85], v10 offset0:32 offset1:40
	ds_read2_b32 v[86:87], v10 offset0:97 offset1:105
	ds_read2_b32 v[88:89], v10 offset0:162 offset1:170
	ds_read2_b32 v[90:91], v10 offset0:227 offset1:235
	ds_read2_b32 v[92:93], v42 offset0:36 offset1:44
	ds_read2_b32 v[94:95], v42 offset0:101 offset1:109
	ds_read2_b32 v[96:97], v42 offset0:166 offset1:174
	ds_read2_b32 v[98:99], v42 offset0:231 offset1:239
	ds_read2_b32 v[100:101], v10 offset0:48 offset1:56
	ds_read2_b32 v[102:103], v10 offset0:113 offset1:121
	ds_read2_b32 v[104:105], v10 offset0:178 offset1:186
	ds_read2_b32 v[106:107], v10 offset0:243 offset1:251
	ds_read2_b32 v[108:109], v42 offset0:52 offset1:60
	ds_read2_b32 v[124:125], v42 offset0:117 offset1:125
	ds_read2_b32 v[128:129], v42 offset0:182 offset1:190
	ds_read2_b32 v[130:131], v42 offset0:247 offset1:255
	s_add_i32 s3, s3, s92
	s_add_i32 s0, s0, s38
	s_cmpk_lt_i32 s3, 0xc00
	s_waitcnt vmcnt(1) lgkmcnt(14)
	v_mul_f32_e32 v43, v44, v52
	v_mul_f32_e32 v52, v45, v54
	v_mul_f32_e32 v54, v46, v56
	v_mul_f32_e32 v56, v47, v58
	s_waitcnt vmcnt(0)
	v_mul_f32_e32 v58, v48, v60
	v_mul_f32_e32 v60, v49, v62
	v_mul_f32_e32 v62, v50, v64
	v_mul_f32_e32 v64, v51, v66
	v_mul_f32_e32 v53, v44, v53
	v_mul_f32_e32 v55, v45, v55
	v_mul_f32_e32 v57, v46, v57
	v_mul_f32_e32 v59, v47, v59
	v_mul_f32_e32 v61, v48, v61
	v_mul_f32_e32 v63, v49, v63
	v_mul_f32_e32 v65, v50, v65
	v_mul_f32_e32 v66, v51, v67
	v_mul_f32_e32 v67, v44, v68
	v_mul_f32_e32 v68, v45, v70
	v_mul_f32_e32 v70, v46, v72
	v_mul_f32_e32 v72, v47, v74
	v_mul_f32_e32 v74, v48, v76
	v_mul_f32_e32 v76, v49, v78
	v_mul_f32_e32 v78, v50, v80
	v_mul_f32_e32 v80, v51, v82
	v_mul_f32_e32 v69, v44, v69
	v_mul_f32_e32 v71, v45, v71
	v_mul_f32_e32 v73, v46, v73
	v_mul_f32_e32 v75, v47, v75
	v_mul_f32_e32 v77, v48, v77
	v_mul_f32_e32 v79, v49, v79
	v_mul_f32_e32 v81, v50, v81
	v_mul_f32_e32 v82, v51, v83
	v_mul_f32_e32 v83, v44, v84
	v_mul_f32_e32 v84, v45, v86
	s_waitcnt lgkmcnt(13)
	v_mul_f32_e32 v86, v46, v88
	s_waitcnt lgkmcnt(12)
	v_mul_f32_e32 v88, v47, v90
	s_waitcnt lgkmcnt(11)
	v_mul_f32_e32 v90, v48, v92
	s_waitcnt lgkmcnt(10)
	v_mul_f32_e32 v92, v49, v94
	s_waitcnt lgkmcnt(9)
	v_mul_f32_e32 v94, v50, v96
	s_waitcnt lgkmcnt(8)
	v_mul_f32_e32 v96, v51, v98
	v_mul_f32_e32 v85, v44, v85
	v_mul_f32_e32 v87, v45, v87
	v_mul_f32_e32 v89, v46, v89
	v_mul_f32_e32 v91, v47, v91
	v_mul_f32_e32 v93, v48, v93
	v_mul_f32_e32 v95, v49, v95
	v_mul_f32_e32 v97, v50, v97
	v_mul_f32_e32 v98, v51, v99
	s_waitcnt lgkmcnt(7)
	v_mul_f32_e32 v99, v44, v100
	s_waitcnt lgkmcnt(6)
	v_mul_f32_e32 v100, v45, v102
	s_waitcnt lgkmcnt(5)
	v_mul_f32_e32 v102, v46, v104
	s_waitcnt lgkmcnt(4)
	v_mul_f32_e32 v104, v47, v106
	s_waitcnt lgkmcnt(3)
	v_mul_f32_e32 v106, v48, v108
	s_waitcnt lgkmcnt(2)
	v_mul_f32_e32 v108, v49, v124
	s_waitcnt lgkmcnt(1)
	v_mul_f32_e32 v124, v50, v128
	s_waitcnt lgkmcnt(0)
	v_mul_f32_e32 v128, v51, v130
	v_mul_f32_e32 v101, v44, v101
	v_mul_f32_e32 v103, v45, v103
	v_mul_f32_e32 v105, v46, v105
	v_mul_f32_e32 v107, v47, v107
	v_mul_f32_e32 v109, v48, v109
	v_mul_f32_e32 v125, v49, v125
	v_mul_f32_e32 v129, v50, v129
	v_mul_f32_e32 v130, v51, v131
	v_cvt_pk_bf16_f32 v44, v43, v52
	v_cvt_pk_bf16_f32 v45, v54, v56
	v_cvt_pk_bf16_f32 v46, v58, v60
	v_cvt_pk_bf16_f32 v47, v62, v64
	v_cvt_pk_bf16_f32 v48, v53, v55
	v_cvt_pk_bf16_f32 v49, v57, v59
	v_cvt_pk_bf16_f32 v50, v61, v63
	v_cvt_pk_bf16_f32 v51, v65, v66
	v_cvt_pk_bf16_f32 v52, v67, v68
	v_cvt_pk_bf16_f32 v53, v70, v72
	v_cvt_pk_bf16_f32 v54, v74, v76
	v_cvt_pk_bf16_f32 v55, v78, v80
	v_cvt_pk_bf16_f32 v56, v69, v71
	v_cvt_pk_bf16_f32 v57, v73, v75
	v_cvt_pk_bf16_f32 v58, v77, v79
	v_cvt_pk_bf16_f32 v59, v81, v82
	v_cvt_pk_bf16_f32 v60, v83, v84
	v_cvt_pk_bf16_f32 v61, v86, v88
	v_cvt_pk_bf16_f32 v62, v90, v92
	v_cvt_pk_bf16_f32 v63, v94, v96
	v_cvt_pk_bf16_f32 v64, v85, v87
	v_cvt_pk_bf16_f32 v65, v89, v91
	v_cvt_pk_bf16_f32 v66, v93, v95
	v_cvt_pk_bf16_f32 v67, v97, v98
	v_cvt_pk_bf16_f32 v68, v99, v100
	v_cvt_pk_bf16_f32 v69, v102, v104
	v_cvt_pk_bf16_f32 v70, v106, v108
	v_cvt_pk_bf16_f32 v71, v124, v128
	v_cvt_pk_bf16_f32 v72, v101, v103
	v_cvt_pk_bf16_f32 v73, v105, v107
	v_cvt_pk_bf16_f32 v74, v109, v125
	v_cvt_pk_bf16_f32 v75, v129, v130
	global_store_dwordx4 v[126:127], v[44:47], off nt
	global_store_dwordx4 v[112:113], v[48:51], off nt
	global_store_dwordx4 v[114:115], v[52:55], off nt
	global_store_dwordx4 v[116:117], v[56:59], off nt
	global_store_dwordx4 v[118:119], v[60:63], off nt
	global_store_dwordx4 v[120:121], v[64:67], off nt
	global_store_dwordx4 v[122:123], v[68:71], off nt
	global_store_dwordx4 v[110:111], v[72:75], off nt
	s_waitcnt lgkmcnt(0)
	s_cbranch_scc1 .LBB0_562

; #define LAS __attribute__((address_space(3)))
; __device__ __forceinline__ void transpose_item(const float* W, int K, int N, bf16_t* WT, int gate, const float* kscale, LAS float* scr, int item, int lane) {
;     const int nblk = N / 64, kb = item / nblk, nb = item % nblk, k0 = 64 * kb, n0 = 64 * nb;
;     const int c4 = (lane & 15) * 4, kr = lane >> 4;
;     f32x4 v[16];
; #pragma unroll
;     for (int i = 0; i < 16; ++i) v[i] = __builtin_nontemporal_load((const f32x4*)(W + (size_t)(k0 + 4 * i + kr) * N + n0 + c4));
; #pragma unroll
;     for (int i = 0; i < 16; ++i) { LAS float* d = scr + (4 * i + kr) * 65 + c4; d[0] = v[i][0]; d[1] = v[i][1]; d[2] = v[i][2]; d[3] = v[i][3]; }
.LBB0_814:
	s_ashr_i32 s4, s1, 31
	s_lshr_b32 s4, s4, 27
	s_add_i32 s4, s1, s4
	s_ashr_i32 s5, s4, 5
	s_lshl_b32 s4, s5, 6
	s_lshl_b32 s5, s5, 11
	v_add_u32_e32 v42, s4, v10
	s_sub_i32 s6, s0, s5
	v_add_u32_e32 v44, 4, v42
	v_add_u32_e32 v46, 8, v42
	v_add_u32_e32 v48, 12, v42
	v_add_u32_e32 v50, 16, v42
	v_add_u32_e32 v52, 20, v42
	v_add_u32_e32 v54, 24, v42
	v_add_u32_e32 v56, 28, v42
	s_ashr_i32 s7, s6, 31
	v_ashrrev_i32_e32 v43, 31, v42
	v_add_u32_e32 v58, 32, v42
	v_add_u32_e32 v60, 36, v42
	v_add_u32_e32 v62, 40, v42
	v_add_u32_e32 v64, 44, v42
	v_add_u32_e32 v66, 48, v42
	v_add_u32_e32 v68, 52, v42
	v_add_u32_e32 v70, 56, v42
	v_add_u32_e32 v72, 60, v42
	v_add_u32_e32 v74, s6, v11
	v_ashrrev_i32_e32 v45, 31, v44
	v_ashrrev_i32_e32 v47, 31, v46
	v_ashrrev_i32_e32 v49, 31, v48
	v_ashrrev_i32_e32 v51, 31, v50
	v_ashrrev_i32_e32 v53, 31, v52
	v_ashrrev_i32_e32 v55, 31, v54
	v_ashrrev_i32_e32 v57, 31, v56
	s_ashr_i32 s5, s4, 31
	v_lshl_add_u64 v[76:77], s[6:7], 2, v[0:1]
	v_lshlrev_b64 v[42:43], 13, v[42:43]
	v_ashrrev_i32_e32 v59, 31, v58
	v_ashrrev_i32_e32 v61, 31, v60
	v_ashrrev_i32_e32 v63, 31, v62
	v_ashrrev_i32_e32 v65, 31, v64
	v_ashrrev_i32_e32 v67, 31, v66
	v_ashrrev_i32_e32 v69, 31, v68
	v_ashrrev_i32_e32 v71, 31, v70
	v_ashrrev_i32_e32 v73, 31, v72
	v_ashrrev_i32_e32 v75, 31, v74
	v_add_u32_e32 v78, 8, v74
	v_add_u32_e32 v80, 16, v74
	v_add_u32_e32 v82, 24, v74
	v_add_u32_e32 v84, 32, v74
	v_add_u32_e32 v86, 40, v74
	v_add_u32_e32 v88, 48, v74
	v_add_u32_e32 v90, 56, v74
	v_lshlrev_b64 v[92:93], 13, v[44:45]
	v_lshlrev_b64 v[46:47], 13, v[46:47]
	v_lshlrev_b64 v[48:49], 13, v[48:49]
	v_lshlrev_b64 v[50:51], 13, v[50:51]
	v_lshlrev_b64 v[52:53], 13, v[52:53]
	v_lshlrev_b64 v[54:55], 13, v[54:55]
	v_lshlrev_b64 v[56:57], 13, v[56:57]
	v_lshl_add_u64 v[106:107], s[4:5], 1, v[2:3]
	v_lshl_add_u64 v[42:43], v[76:77], 0, v[42:43]
	v_lshlrev_b64 v[58:59], 13, v[58:59]
	v_lshlrev_b64 v[60:61], 13, v[60:61]
	v_lshlrev_b64 v[62:63], 13, v[62:63]
	v_lshlrev_b64 v[64:65], 13, v[64:65]
	v_lshlrev_b64 v[66:67], 13, v[66:67]
	v_lshlrev_b64 v[68:69], 13, v[68:69]
	v_lshlrev_b64 v[70:71], 13, v[70:71]
	v_lshlrev_b64 v[72:73], 13, v[72:73]
	v_lshlrev_b64 v[74:75], 12, v[74:75]
	v_ashrrev_i32_e32 v79, 31, v78
	v_ashrrev_i32_e32 v81, 31, v80
	v_ashrrev_i32_e32 v83, 31, v82
	v_ashrrev_i32_e32 v85, 31, v84
	v_ashrrev_i32_e32 v87, 31, v86
	v_ashrrev_i32_e32 v89, 31, v88
	v_ashrrev_i32_e32 v91, 31, v90
	v_lshl_add_u64 v[92:93], v[76:77], 0, v[92:93]
	v_lshl_add_u64 v[94:95], v[76:77], 0, v[46:47]
	v_lshl_add_u64 v[96:97], v[76:77], 0, v[48:49]
	v_lshl_add_u64 v[98:99], v[76:77], 0, v[50:51]
	v_lshl_add_u64 v[100:101], v[76:77], 0, v[52:53]
	v_lshl_add_u64 v[102:103], v[76:77], 0, v[54:55]
	v_lshl_add_u64 v[104:105], v[76:77], 0, v[56:57]
	global_load_dwordx4 v[42:45], v[42:43], off nt
	v_lshl_add_u64 v[108:109], v[76:77], 0, v[58:59]
	v_lshl_add_u64 v[110:111], v[76:77], 0, v[60:61]
	v_lshl_add_u64 v[112:113], v[76:77], 0, v[62:63]
	v_lshl_add_u64 v[114:115], v[76:77], 0, v[64:65]
	v_lshl_add_u64 v[116:117], v[76:77], 0, v[66:67]
	v_lshl_add_u64 v[118:119], v[76:77], 0, v[68:69]
	v_lshl_add_u64 v[120:121], v[76:77], 0, v[70:71]
	v_lshl_add_u64 v[122:123], v[76:77], 0, v[72:73]
	v_lshl_add_u64 v[124:125], v[106:107], 0, v[74:75]
	v_lshlrev_b64 v[126:127], 12, v[78:79]
	v_lshlrev_b64 v[128:129], 12, v[80:81]
	v_lshlrev_b64 v[130:131], 12, v[82:83]
	v_lshlrev_b64 v[132:133], 12, v[84:85]
	v_lshlrev_b64 v[134:135], 12, v[86:87]
	v_lshlrev_b64 v[136:137], 12, v[88:89]
	v_lshlrev_b64 v[138:139], 12, v[90:91]
	global_load_dwordx4 v[46:49], v[92:93], off nt
	global_load_dwordx4 v[50:53], v[94:95], off nt
	global_load_dwordx4 v[54:57], v[96:97], off nt
	global_load_dwordx4 v[58:61], v[98:99], off nt
	global_load_dwordx4 v[62:65], v[100:101], off nt
	global_load_dwordx4 v[66:69], v[102:103], off nt
	global_load_dwordx4 v[70:73], v[104:105], off nt
	global_load_dwordx4 v[74:77], v[108:109], off nt
	global_load_dwordx4 v[78:81], v[110:111], off nt
	global_load_dwordx4 v[82:85], v[112:113], off nt
	global_load_dwordx4 v[86:89], v[114:115], off nt
	global_load_dwordx4 v[90:93], v[116:117], off nt
	global_load_dwordx4 v[94:97], v[118:119], off nt
	global_load_dwordx4 v[98:101], v[120:121], off nt
	global_load_dwordx4 v[102:105], v[122:123], off nt
	s_waitcnt vmcnt(15)
	ds_write2_b32 v6, v42, v43 offset1:1
	ds_write2_b32 v6, v44, v45 offset0:2 offset1:3
	s_waitcnt vmcnt(14)
	ds_write2_b32 v7, v46, v47 offset1:1
	ds_write2_b32 v9, v48, v49 offset1:1
	s_waitcnt vmcnt(13)
	ds_write2_b32 v12, v50, v51 offset1:1
	ds_write2_b32 v13, v52, v53 offset1:1
	s_waitcnt vmcnt(12)
	ds_write2_b32 v14, v54, v55 offset1:1
	ds_write2_b32 v15, v56, v57 offset1:1
	s_waitcnt vmcnt(11)
	ds_write2_b32 v16, v58, v59 offset1:1
	ds_write2_b32 v17, v60, v61 offset1:1
	s_waitcnt vmcnt(10)
; #define LAS __attribute__((address_space(3)))
; __device__ __forceinline__ void lds_wait() { asm volatile("s_waitcnt lgkmcnt(0)" ::: "memory"); }
; __device__ __forceinline__ void transpose_item(const float* W, int K, int N, bf16_t* WT, int gate, const float* kscale, LAS float* scr, int item, int lane) {
;     ...
;     for (int i = 0; i < 16; ++i) { LAS float* d = scr + (4 * i + kr) * 65 + c4; d[0] = v[i][0]; d[1] = v[i][1]; d[2] = v[i][2]; d[3] = v[i][3]; }
;     lds_wait();
;     const int c = lane & 7;
;     f32x4 k0v = {1.f, 1.f, 1.f, 1.f}, k1v = k0v;
;     if (kscale) { k0v = *(const f32x4*)(kscale + k0 + 8 * c); k1v = *(const f32x4*)(kscale + k0 + 8 * c + 4); }
; #pragma unroll
;     for (int j = 0; j < 8; ++j) { const int n = (lane >> 3) + 8 * j; const LAS float* s = scr + (8 * c) * 65 + n;
;         u32x4 o; o.x = pk2(s[0 * 65] * k0v[0], s[1 * 65] * k0v[1]); o.y = pk2(s[2 * 65] * k0v[2], s[3 * 65] * k0v[3]); o.z = pk2(s[4 * 65] * k1v[0], s[5 * 65] * k1v[1]); o.w = pk2(s[6 * 65] * k1v[2], s[7 * 65] * k1v[3]);
;         const int nn = n0 + n; const int row = gate < 0 ? nn : (256 * (nn >> 7) + 128 * gate + (nn & 127));
;         *(u32x4*)(WT + (size_t)row * K + k0 + 8 * c) = o; }
;     lds_wait();
	ds_write2_b32 v18, v62, v63 offset1:1
	ds_write2_b32 v19, v64, v65 offset1:1
	s_waitcnt vmcnt(9)
	ds_write2_b32 v20, v66, v67 offset1:1
	ds_write2_b32 v21, v68, v69 offset1:1
	s_waitcnt vmcnt(8)
	ds_write2_b32 v22, v70, v71 offset1:1
	ds_write2_b32 v23, v72, v73 offset1:1
	s_waitcnt vmcnt(7)
	ds_write2_b32 v24, v74, v75 offset1:1
	ds_write2_b32 v25, v76, v77 offset1:1
	s_waitcnt vmcnt(6)
	ds_write2_b32 v26, v78, v79 offset1:1
	ds_write2_b32 v27, v80, v81 offset1:1
	s_waitcnt vmcnt(5)
	ds_write2_b32 v28, v82, v83 offset1:1
	ds_write2_b32 v29, v84, v85 offset1:1
	s_waitcnt vmcnt(4)
	ds_write2_b32 v30, v86, v87 offset1:1
	ds_write2_b32 v31, v88, v89 offset1:1
	s_waitcnt vmcnt(3)
	ds_write2_b32 v32, v90, v91 offset1:1
	ds_write2_b32 v33, v92, v93 offset1:1
	s_waitcnt vmcnt(2)
	ds_write2_b32 v34, v94, v95 offset1:1
	ds_write2_b32 v35, v96, v97 offset1:1
	s_waitcnt vmcnt(1)
	ds_write2_b32 v36, v98, v99 offset1:1
	ds_write2_b32 v37, v100, v101 offset1:1
	s_waitcnt vmcnt(0)
	ds_write2_b32 v38, v102, v103 offset1:1
	ds_write2_b32 v39, v104, v105 offset1:1
	s_waitcnt lgkmcnt(0)
	ds_read2_b32 v[46:47], v5 offset0:65 offset1:73
	ds_read2_b32 v[48:49], v5 offset1:8
	ds_read2_b32 v[50:51], v5 offset0:130 offset1:138
	ds_read2_b32 v[52:53], v5 offset0:195 offset1:203
	ds_read2_b32 v[54:55], v40 offset0:4 offset1:12
	ds_read2_b32 v[56:57], v40 offset0:69 offset1:77
	ds_read2_b32 v[58:59], v40 offset0:134 offset1:142
	ds_read2_b32 v[60:61], v40 offset0:199 offset1:207
	ds_read2_b32 v[62:63], v5 offset0:81 offset1:89
	ds_read2_b32 v[64:65], v5 offset0:16 offset1:24
	ds_read2_b32 v[66:67], v5 offset0:146 offset1:154
	ds_read2_b32 v[68:69], v5 offset0:211 offset1:219
	ds_read2_b32 v[70:71], v40 offset0:20 offset1:28
	ds_read2_b32 v[72:73], v40 offset0:85 offset1:93
	ds_read2_b32 v[74:75], v40 offset0:150 offset1:158
	ds_read2_b32 v[76:77], v40 offset0:215 offset1:223
	ds_read2_b32 v[78:79], v5 offset0:32 offset1:40
	ds_read2_b32 v[80:81], v5 offset0:97 offset1:105
	ds_read2_b32 v[82:83], v5 offset0:162 offset1:170
	ds_read2_b32 v[84:85], v5 offset0:227 offset1:235
	ds_read2_b32 v[86:87], v40 offset0:36 offset1:44
	ds_read2_b32 v[88:89], v40 offset0:101 offset1:109
	ds_read2_b32 v[90:91], v40 offset0:166 offset1:174
	ds_read2_b32 v[92:93], v40 offset0:231 offset1:239
	ds_read2_b32 v[94:95], v5 offset0:48 offset1:56
	ds_read2_b32 v[96:97], v5 offset0:113 offset1:121
	ds_read2_b32 v[98:99], v5 offset0:178 offset1:186
	ds_read2_b32 v[100:101], v5 offset0:243 offset1:251
	ds_read2_b32 v[102:103], v40 offset0:52 offset1:60
	ds_read2_b32 v[104:105], v40 offset0:117 offset1:125
	ds_read2_b32 v[120:121], v40 offset0:182 offset1:190
	ds_read2_b32 v[122:123], v40 offset0:247 offset1:255
	s_waitcnt lgkmcnt(14)
	v_cvt_pk_bf16_f32 v42, v48, v46
	v_cvt_pk_bf16_f32 v43, v50, v52
	v_cvt_pk_bf16_f32 v44, v54, v56
	v_cvt_pk_bf16_f32 v45, v58, v60
	v_lshl_add_u64 v[108:109], v[106:107], 0, v[126:127]
	v_lshl_add_u64 v[110:111], v[106:107], 0, v[128:129]
	v_lshl_add_u64 v[112:113], v[106:107], 0, v[130:131]
	v_lshl_add_u64 v[114:115], v[106:107], 0, v[132:133]
	v_lshl_add_u64 v[116:117], v[106:107], 0, v[134:135]
	v_lshl_add_u64 v[118:119], v[106:107], 0, v[136:137]
	v_lshl_add_u64 v[106:107], v[106:107], 0, v[138:139]
	v_cvt_pk_bf16_f32 v46, v49, v47
	v_cvt_pk_bf16_f32 v47, v51, v53
	v_cvt_pk_bf16_f32 v48, v55, v57
	v_cvt_pk_bf16_f32 v49, v59, v61
	v_cvt_pk_bf16_f32 v50, v64, v62
	v_cvt_pk_bf16_f32 v51, v66, v68
	v_cvt_pk_bf16_f32 v52, v70, v72
	v_cvt_pk_bf16_f32 v53, v74, v76
	v_cvt_pk_bf16_f32 v54, v65, v63
	v_cvt_pk_bf16_f32 v55, v67, v69
	v_cvt_pk_bf16_f32 v56, v71, v73
	v_cvt_pk_bf16_f32 v57, v75, v77
	v_cvt_pk_bf16_f32 v58, v78, v80
	s_waitcnt lgkmcnt(12)
	v_cvt_pk_bf16_f32 v59, v82, v84
	s_waitcnt lgkmcnt(10)
	v_cvt_pk_bf16_f32 v60, v86, v88
	s_waitcnt lgkmcnt(8)
	v_cvt_pk_bf16_f32 v61, v90, v92
	v_cvt_pk_bf16_f32 v62, v79, v81
	v_cvt_pk_bf16_f32 v63, v83, v85
	v_cvt_pk_bf16_f32 v64, v87, v89
	v_cvt_pk_bf16_f32 v65, v91, v93
	s_waitcnt lgkmcnt(6)
	v_cvt_pk_bf16_f32 v66, v94, v96
	s_waitcnt lgkmcnt(4)
	v_cvt_pk_bf16_f32 v67, v98, v100
	s_waitcnt lgkmcnt(2)
	v_cvt_pk_bf16_f32 v68, v102, v104
	s_waitcnt lgkmcnt(0)
	v_cvt_pk_bf16_f32 v69, v120, v122
	v_cvt_pk_bf16_f32 v70, v95, v97
	v_cvt_pk_bf16_f32 v71, v99, v101
	v_cvt_pk_bf16_f32 v72, v103, v105
	v_cvt_pk_bf16_f32 v73, v121, v123
	global_store_dwordx4 v[124:125], v[42:45], off nt
	global_store_dwordx4 v[108:109], v[46:49], off nt
	global_store_dwordx4 v[110:111], v[50:53], off nt
	global_store_dwordx4 v[112:113], v[54:57], off nt
	global_store_dwordx4 v[114:115], v[58:61], off nt
	global_store_dwordx4 v[116:117], v[62:65], off nt
	global_store_dwordx4 v[118:119], v[66:69], off nt
	global_store_dwordx4 v[106:107], v[70:73], off nt
	s_waitcnt lgkmcnt(0)
	s_add_i32 s1, s1, s92
	s_add_i32 s0, s0, s38
	s_cmpk_lt_i32 s1, 0x400
	s_cbranch_scc1 .LBB0_814

; #define LAS __attribute__((address_space(3)))
; __device__ __forceinline__ void transpose_item(const float* W, int K, int N, bf16_t* WT, int gate, const float* kscale, LAS float* scr, int item, int lane) {
;     const int nblk = N / 64, kb = item / nblk, nb = item % nblk, k0 = 64 * kb, n0 = 64 * nb;
;     const int c4 = (lane & 15) * 4, kr = lane >> 4;
;     f32x4 v[16];
; #pragma unroll
;     for (int i = 0; i < 16; ++i) v[i] = __builtin_nontemporal_load((const f32x4*)(W + (size_t)(k0 + 4 * i + kr) * N + n0 + c4));
; #pragma unroll
;     for (int i = 0; i < 16; ++i) { LAS float* d = scr + (4 * i + kr) * 65 + c4; d[0] = v[i][0]; d[1] = v[i][1]; d[2] = v[i][2]; d[3] = v[i][3]; }
.LBB0_817:
	s_ashr_i32 s19, s18, 31
	s_lshr_b32 s19, s19, 25
	s_add_i32 s19, s18, s19
	s_ashr_i32 s19, s19, 7
	s_lshl_b32 s20, s19, 6
	s_lshl_b32 s19, s19, 13
	s_sub_i32 s26, s17, s19
	v_add_u32_e32 v44, s20, v10
	s_ashr_i32 s27, s26, 31
	v_ashrrev_i32_e32 v45, 31, v44
	v_lshl_add_u64 v[48:49], s[26:27], 2, v[4:5]
	v_lshlrev_b64 v[44:45], 15, v[44:45]
	v_lshl_add_u64 v[48:49], v[48:49], 0, v[44:45]
	v_add_co_u32_e32 v66, vcc, s1, v48
	v_add_u32_e32 v46, s26, v11
	s_nop 0
	v_addc_co_u32_e32 v67, vcc, 0, v49, vcc
	v_add_co_u32_e32 v68, vcc, s3, v48
	s_ashr_i32 s21, s20, 31
	s_nop 0
	v_addc_co_u32_e32 v69, vcc, 0, v49, vcc
	v_add_co_u32_e32 v70, vcc, s4, v48
	v_ashrrev_i32_e32 v47, 31, v46
	s_nop 0
	v_addc_co_u32_e32 v71, vcc, 0, v49, vcc
	v_add_co_u32_e32 v72, vcc, s5, v48
	v_add_u32_e32 v50, 8, v46
	s_nop 0
	v_addc_co_u32_e32 v73, vcc, 0, v49, vcc
	v_add_co_u32_e32 v74, vcc, s6, v48
	v_add_u32_e32 v52, 16, v46
	s_nop 0
	v_addc_co_u32_e32 v75, vcc, 0, v49, vcc
	v_add_co_u32_e32 v76, vcc, s7, v48
	v_add_u32_e32 v54, 24, v46
	s_nop 0
	v_addc_co_u32_e32 v77, vcc, 0, v49, vcc
	v_add_co_u32_e32 v78, vcc, s8, v48
	v_add_u32_e32 v56, 32, v46
	s_nop 0
	v_addc_co_u32_e32 v79, vcc, 0, v49, vcc
	v_add_co_u32_e32 v80, vcc, s9, v48
	v_add_u32_e32 v58, 40, v46
	s_nop 0
	v_addc_co_u32_e32 v81, vcc, 0, v49, vcc
	v_add_co_u32_e32 v82, vcc, s10, v48
	v_add_u32_e32 v60, 48, v46
	s_nop 0
	v_addc_co_u32_e32 v83, vcc, 0, v49, vcc
	v_add_co_u32_e32 v84, vcc, s11, v48
	v_add_u32_e32 v62, 56, v46
	s_nop 0
	v_addc_co_u32_e32 v85, vcc, 0, v49, vcc
	v_add_co_u32_e32 v88, vcc, s12, v48
	v_lshl_add_u64 v[110:111], s[20:21], 1, v[8:9]
	s_nop 0
	v_addc_co_u32_e32 v89, vcc, 0, v49, vcc
	v_add_co_u32_e32 v92, vcc, s13, v48
	v_lshlrev_b64 v[64:65], 12, v[46:47]
	s_nop 0
	v_addc_co_u32_e32 v93, vcc, 0, v49, vcc
	v_add_co_u32_e32 v96, vcc, s14, v48
	v_ashrrev_i32_e32 v51, 31, v50
	s_nop 0
	v_addc_co_u32_e32 v97, vcc, 0, v49, vcc
	v_add_co_u32_e32 v100, vcc, s15, v48
	v_ashrrev_i32_e32 v53, 31, v52
	s_nop 0
	v_addc_co_u32_e32 v101, vcc, 0, v49, vcc
	v_add_co_u32_e32 v104, vcc, s16, v48
	v_ashrrev_i32_e32 v55, 31, v54
	v_ashrrev_i32_e32 v57, 31, v56
	v_ashrrev_i32_e32 v59, 31, v58
	v_ashrrev_i32_e32 v61, 31, v60
	v_ashrrev_i32_e32 v63, 31, v62
	v_addc_co_u32_e32 v105, vcc, 0, v49, vcc
	global_load_dwordx4 v[44:47], v[48:49], off nt
	v_lshl_add_u64 v[112:113], v[110:111], 0, v[64:65]
	v_lshlrev_b64 v[114:115], 12, v[50:51]
	v_lshlrev_b64 v[116:117], 12, v[52:53]
	v_lshlrev_b64 v[118:119], 12, v[54:55]
	v_lshlrev_b64 v[120:121], 12, v[56:57]
	v_lshlrev_b64 v[122:123], 12, v[58:59]
	v_lshlrev_b64 v[124:125], 12, v[60:61]
	v_lshlrev_b64 v[126:127], 12, v[62:63]
	global_load_dwordx4 v[48:51], v[66:67], off nt
	global_load_dwordx4 v[52:55], v[68:69], off nt
	global_load_dwordx4 v[56:59], v[70:71], off nt
	global_load_dwordx4 v[60:63], v[72:73], off nt
	s_nop 0
	global_load_dwordx4 v[64:67], v[74:75], off nt
	global_load_dwordx4 v[68:71], v[76:77], off nt
	s_nop 0
	global_load_dwordx4 v[72:75], v[78:79], off nt
	s_nop 0
	global_load_dwordx4 v[76:79], v[80:81], off nt
	s_nop 0
	global_load_dwordx4 v[80:83], v[82:83], off nt
	s_nop 0
	global_load_dwordx4 v[84:87], v[84:85], off nt
	s_nop 0
	global_load_dwordx4 v[88:91], v[88:89], off nt
	s_nop 0
	global_load_dwordx4 v[92:95], v[92:93], off nt
	s_nop 0
	global_load_dwordx4 v[96:99], v[96:97], off nt
	s_nop 0
	global_load_dwordx4 v[100:103], v[100:101], off nt
	s_nop 0
	global_load_dwordx4 v[104:107], v[104:105], off nt
	v_lshl_add_u64 v[108:109], s[20:21], 2, v[6:7]
	v_lshl_add_u64 v[114:115], v[110:111], 0, v[114:115]
	v_lshl_add_u64 v[116:117], v[110:111], 0, v[116:117]
	v_lshl_add_u64 v[118:119], v[110:111], 0, v[118:119]
	v_lshl_add_u64 v[120:121], v[110:111], 0, v[120:121]
	v_lshl_add_u64 v[122:123], v[110:111], 0, v[122:123]
	v_lshl_add_u64 v[124:125], v[110:111], 0, v[124:125]
	v_lshl_add_u64 v[110:111], v[110:111], 0, v[126:127]
	s_add_i32 s18, s18, s92
	s_add_i32 s17, s17, s38
	s_cmpk_lt_i32 s18, 0x1000
	s_waitcnt vmcnt(15)
	ds_write2_b32 v13, v44, v45 offset1:1
	ds_write2_b32 v13, v46, v47 offset0:2 offset1:3
	s_waitcnt vmcnt(14)
	ds_write2_b32 v1, v48, v49 offset1:1
	ds_write2_b32 v3, v50, v51 offset1:1
	s_waitcnt vmcnt(13)
	ds_write2_b32 v14, v52, v53 offset1:1
	ds_write2_b32 v15, v54, v55 offset1:1
	s_waitcnt vmcnt(12)
	ds_write2_b32 v16, v56, v57 offset1:1
	ds_write2_b32 v17, v58, v59 offset1:1
	s_waitcnt vmcnt(11)
	ds_write2_b32 v18, v60, v61 offset1:1
	ds_write2_b32 v19, v62, v63 offset1:1
	s_waitcnt vmcnt(10)
	ds_write2_b32 v20, v64, v65 offset1:1
	ds_write2_b32 v21, v66, v67 offset1:1
	s_waitcnt vmcnt(9)
	ds_write2_b32 v22, v68, v69 offset1:1
	ds_write2_b32 v23, v70, v71 offset1:1
	s_waitcnt vmcnt(8)
	ds_write2_b32 v24, v72, v73 offset1:1
	ds_write2_b32 v25, v74, v75 offset1:1
	s_waitcnt vmcnt(7)
	ds_write2_b32 v26, v76, v77 offset1:1
	ds_write2_b32 v27, v78, v79 offset1:1
	s_waitcnt vmcnt(6)
	ds_write2_b32 v28, v80, v81 offset1:1
	ds_write2_b32 v29, v82, v83 offset1:1
	s_waitcnt vmcnt(5)
	ds_write2_b32 v30, v84, v85 offset1:1
	ds_write2_b32 v31, v86, v87 offset1:1
	s_waitcnt vmcnt(4)
	ds_write2_b32 v32, v88, v89 offset1:1
	ds_write2_b32 v33, v90, v91 offset1:1
	s_waitcnt vmcnt(3)
	ds_write2_b32 v34, v92, v93 offset1:1
	ds_write2_b32 v35, v94, v95 offset1:1
	s_waitcnt vmcnt(2)
	ds_write2_b32 v36, v96, v97 offset1:1
	ds_write2_b32 v37, v98, v99 offset1:1
	s_waitcnt vmcnt(1)
	ds_write2_b32 v38, v100, v101 offset1:1
	ds_write2_b32 v39, v102, v103 offset1:1
	s_waitcnt vmcnt(0)
	ds_write2_b32 v40, v104, v105 offset1:1
	ds_write2_b32 v41, v106, v107 offset1:1
	s_waitcnt lgkmcnt(0)
; #define LAS __attribute__((address_space(3)))
; __device__ __forceinline__ void lds_wait() { asm volatile("s_waitcnt lgkmcnt(0)" ::: "memory"); }
; __device__ __forceinline__ void transpose_item(const float* W, int K, int N, bf16_t* WT, int gate, const float* kscale, LAS float* scr, int item, int lane) {
;     ...
;     const int c = lane & 7;
;     f32x4 k0v = {1.f, 1.f, 1.f, 1.f}, k1v = k0v;
;     if (kscale) { k0v = *(const f32x4*)(kscale + k0 + 8 * c); k1v = *(const f32x4*)(kscale + k0 + 8 * c + 4); }
; #pragma unroll
;     for (int j = 0; j < 8; ++j) { const int n = (lane >> 3) + 8 * j; const LAS float* s = scr + (8 * c) * 65 + n;
;         u32x4 o; o.x = pk2(s[0 * 65] * k0v[0], s[1 * 65] * k0v[1]); o.y = pk2(s[2 * 65] * k0v[2], s[3 * 65] * k0v[3]); o.z = pk2(s[4 * 65] * k1v[0], s[5 * 65] * k1v[1]); o.w = pk2(s[6 * 65] * k1v[2], s[7 * 65] * k1v[3]);
;         const int nn = n0 + n; const int row = gate < 0 ? nn : (256 * (nn >> 7) + 128 * gate + (nn & 127));
;         *(u32x4*)(WT + (size_t)row * K + k0 + 8 * c) = o; }
;     lds_wait();
	global_load_dwordx4 v[44:47], v[108:109], off
	global_load_dwordx4 v[48:51], v[108:109], off offset:16
	ds_read2_b32 v[52:53], v12 offset1:8
	ds_read2_b32 v[54:55], v12 offset0:65 offset1:73
	ds_read2_b32 v[56:57], v12 offset0:130 offset1:138
	ds_read2_b32 v[58:59], v12 offset0:195 offset1:203
	ds_read2_b32 v[60:61], v42 offset0:4 offset1:12
	ds_read2_b32 v[62:63], v42 offset0:69 offset1:77
	ds_read2_b32 v[64:65], v42 offset0:134 offset1:142
	ds_read2_b32 v[66:67], v42 offset0:199 offset1:207
	ds_read2_b32 v[68:69], v12 offset0:16 offset1:24
	ds_read2_b32 v[70:71], v12 offset0:81 offset1:89
	ds_read2_b32 v[72:73], v12 offset0:146 offset1:154
	ds_read2_b32 v[74:75], v12 offset0:211 offset1:219
	ds_read2_b32 v[76:77], v42 offset0:20 offset1:28
	ds_read2_b32 v[78:79], v42 offset0:85 offset1:93
	ds_read2_b32 v[80:81], v42 offset0:150 offset1:158
	ds_read2_b32 v[82:83], v42 offset0:215 offset1:223
	ds_read2_b32 v[84:85], v12 offset0:32 offset1:40
	ds_read2_b32 v[86:87], v12 offset0:97 offset1:105
	ds_read2_b32 v[88:89], v12 offset0:162 offset1:170
	ds_read2_b32 v[90:91], v12 offset0:227 offset1:235
	ds_read2_b32 v[92:93], v42 offset0:36 offset1:44
	ds_read2_b32 v[94:95], v42 offset0:101 offset1:109
	ds_read2_b32 v[96:97], v42 offset0:166 offset1:174
	ds_read2_b32 v[98:99], v42 offset0:231 offset1:239
	ds_read2_b32 v[100:101], v12 offset0:48 offset1:56
	ds_read2_b32 v[102:103], v12 offset0:113 offset1:121
	ds_read2_b32 v[104:105], v12 offset0:178 offset1:186
	ds_read2_b32 v[106:107], v12 offset0:243 offset1:251
	ds_read2_b32 v[108:109], v42 offset0:52 offset1:60
	ds_read2_b32 v[126:127], v42 offset0:117 offset1:125
	ds_read2_b32 v[128:129], v42 offset0:182 offset1:190
	ds_read2_b32 v[130:131], v42 offset0:247 offset1:255
	s_waitcnt vmcnt(1) lgkmcnt(14)
	v_mul_f32_e32 v43, v44, v52
	v_mul_f32_e32 v52, v45, v54
	v_mul_f32_e32 v54, v46, v56
	v_mul_f32_e32 v56, v47, v58
	s_waitcnt vmcnt(0)
	v_mul_f32_e32 v58, v48, v60
	v_mul_f32_e32 v60, v49, v62
	v_mul_f32_e32 v62, v50, v64
	v_mul_f32_e32 v64, v51, v66
	v_mul_f32_e32 v53, v44, v53
	v_mul_f32_e32 v55, v45, v55
	v_mul_f32_e32 v57, v46, v57
	v_mul_f32_e32 v59, v47, v59
	v_mul_f32_e32 v61, v48, v61
	v_mul_f32_e32 v63, v49, v63
	v_mul_f32_e32 v65, v50, v65
	v_mul_f32_e32 v66, v51, v67
	v_mul_f32_e32 v67, v44, v68
	v_mul_f32_e32 v68, v45, v70
	v_mul_f32_e32 v70, v46, v72
	v_mul_f32_e32 v72, v47, v74
	v_mul_f32_e32 v74, v48, v76
	v_mul_f32_e32 v76, v49, v78
	v_mul_f32_e32 v78, v50, v80
	v_mul_f32_e32 v80, v51, v82
	v_mul_f32_e32 v69, v44, v69
	v_mul_f32_e32 v71, v45, v71
	v_mul_f32_e32 v73, v46, v73
	v_mul_f32_e32 v75, v47, v75
	v_mul_f32_e32 v77, v48, v77
	v_mul_f32_e32 v79, v49, v79
	v_mul_f32_e32 v81, v50, v81
	v_mul_f32_e32 v82, v51, v83
	v_mul_f32_e32 v83, v44, v84
	v_mul_f32_e32 v84, v45, v86
	s_waitcnt lgkmcnt(13)
	v_mul_f32_e32 v86, v46, v88
	s_waitcnt lgkmcnt(12)
	v_mul_f32_e32 v88, v47, v90
	s_waitcnt lgkmcnt(11)
	v_mul_f32_e32 v90, v48, v92
	s_waitcnt lgkmcnt(10)
	v_mul_f32_e32 v92, v49, v94
	s_waitcnt lgkmcnt(9)
	v_mul_f32_e32 v94, v50, v96
	s_waitcnt lgkmcnt(8)
	v_mul_f32_e32 v96, v51, v98
	v_mul_f32_e32 v85, v44, v85
	v_mul_f32_e32 v87, v45, v87
	v_mul_f32_e32 v89, v46, v89
	v_mul_f32_e32 v91, v47, v91
	v_mul_f32_e32 v93, v48, v93
	v_mul_f32_e32 v95, v49, v95
	v_mul_f32_e32 v97, v50, v97
	v_mul_f32_e32 v98, v51, v99
	s_waitcnt lgkmcnt(7)
	v_mul_f32_e32 v99, v44, v100
	s_waitcnt lgkmcnt(6)
	v_mul_f32_e32 v100, v45, v102
	s_waitcnt lgkmcnt(5)
	v_mul_f32_e32 v102, v46, v104
	s_waitcnt lgkmcnt(4)
	v_mul_f32_e32 v104, v47, v106
	s_waitcnt lgkmcnt(3)
	v_mul_f32_e32 v106, v48, v108
	s_waitcnt lgkmcnt(2)
	v_mul_f32_e32 v108, v49, v126
	s_waitcnt lgkmcnt(1)
	v_mul_f32_e32 v126, v50, v128
	s_waitcnt lgkmcnt(0)
	v_mul_f32_e32 v128, v51, v130
	v_mul_f32_e32 v101, v44, v101
	v_mul_f32_e32 v103, v45, v103
	v_mul_f32_e32 v105, v46, v105
	v_mul_f32_e32 v107, v47, v107
	v_mul_f32_e32 v109, v48, v109
	v_mul_f32_e32 v127, v49, v127
	v_mul_f32_e32 v129, v50, v129
	v_mul_f32_e32 v130, v51, v131
	v_cvt_pk_bf16_f32 v44, v43, v52
	v_cvt_pk_bf16_f32 v45, v54, v56
	v_cvt_pk_bf16_f32 v46, v58, v60
	v_cvt_pk_bf16_f32 v47, v62, v64
	v_cvt_pk_bf16_f32 v48, v53, v55
	v_cvt_pk_bf16_f32 v49, v57, v59
	v_cvt_pk_bf16_f32 v50, v61, v63
	v_cvt_pk_bf16_f32 v51, v65, v66
	v_cvt_pk_bf16_f32 v52, v67, v68
	v_cvt_pk_bf16_f32 v53, v70, v72
	v_cvt_pk_bf16_f32 v54, v74, v76
	v_cvt_pk_bf16_f32 v55, v78, v80
	v_cvt_pk_bf16_f32 v56, v69, v71
	v_cvt_pk_bf16_f32 v57, v73, v75
	v_cvt_pk_bf16_f32 v58, v77, v79
	v_cvt_pk_bf16_f32 v59, v81, v82
	v_cvt_pk_bf16_f32 v60, v83, v84
	v_cvt_pk_bf16_f32 v61, v86, v88
	v_cvt_pk_bf16_f32 v62, v90, v92
	v_cvt_pk_bf16_f32 v63, v94, v96
	v_cvt_pk_bf16_f32 v64, v85, v87
	v_cvt_pk_bf16_f32 v65, v89, v91
	v_cvt_pk_bf16_f32 v66, v93, v95
	v_cvt_pk_bf16_f32 v67, v97, v98
	v_cvt_pk_bf16_f32 v68, v99, v100
	v_cvt_pk_bf16_f32 v69, v102, v104
	v_cvt_pk_bf16_f32 v70, v106, v108
	v_cvt_pk_bf16_f32 v71, v126, v128
	v_cvt_pk_bf16_f32 v72, v101, v103
	v_cvt_pk_bf16_f32 v73, v105, v107
	v_cvt_pk_bf16_f32 v74, v109, v127
	v_cvt_pk_bf16_f32 v75, v129, v130
	global_store_dwordx4 v[112:113], v[44:47], off nt
	global_store_dwordx4 v[114:115], v[48:51], off nt
	global_store_dwordx4 v[116:117], v[52:55], off nt
	global_store_dwordx4 v[118:119], v[56:59], off nt
	global_store_dwordx4 v[120:121], v[60:63], off nt
	global_store_dwordx4 v[122:123], v[64:67], off nt
	global_store_dwordx4 v[124:125], v[68:71], off nt
	global_store_dwordx4 v[110:111], v[72:75], off nt
	s_waitcnt lgkmcnt(0)
	s_cbranch_scc1 .LBB0_817
	v_readlane_b32 s4, v253, 0
	v_lshlrev_b32_e32 v4, 2, v0
	v_mov_b32_e32 v5, 0
	v_readlane_b32 s5, v253, 1
	v_readlane_b32 s10, v253, 6
	v_readlane_b32 s11, v253, 7
	s_mov_b64 s[4:5], 0x4000000
	v_readlane_b32 s60, v253, 12
	v_lshl_add_u64 v[0:1], s[10:11], 0, v[4:5]
	v_lshl_add_u64 v[0:1], v[0:1], 0, s[4:5]
	v_readlane_b32 s4, v253, 10
	v_lshlrev_b32_e32 v4, 1, v2
	v_readlane_b32 s5, v253, 11
	v_readlane_b32 s62, v253, 15
	s_mov_b32 s1, s54
	v_lshl_add_u64 v[2:3], s[4:5], 0, v[4:5]
	v_readlane_b32 s61, v253, 13
	v_readlane_b32 s63, v253, 16
	v_readlane_b32 s6, v253, 2
	v_readlane_b32 s7, v253, 3
	v_readlane_b32 s8, v253, 4
	v_readlane_b32 s9, v253, 5
; #define LAS __attribute__((address_space(3)))
; __device__ __forceinline__ void transpose_item(const float* W, int K, int N, bf16_t* WT, int gate, const float* kscale, LAS float* scr, int item, int lane) {
;     const int nblk = N / 64, kb = item / nblk, nb = item % nblk, k0 = 64 * kb, n0 = 64 * nb;
;     const int c4 = (lane & 15) * 4, kr = lane >> 4;
;     f32x4 v[16];
; #pragma unroll
;     for (int i = 0; i < 16; ++i) v[i] = __builtin_nontemporal_load((const f32x4*)(W + (size_t)(k0 + 4 * i + kr) * N + n0 + c4));
; #pragma unroll
;     for (int i = 0; i < 16; ++i) { LAS float* d = scr + (4 * i + kr) * 65 + c4; d[0] = v[i][0]; d[1] = v[i][1]; d[2] = v[i][2]; d[3] = v[i][3]; }
.LBB0_819:
	s_ashr_i32 s3, s1, 31
	s_lshr_b32 s3, s3, 27
	s_add_i32 s3, s1, s3
	s_ashr_i32 s3, s3, 5
	s_lshl_b32 s4, s3, 6
	s_lshl_b32 s3, s3, 11
	v_add_u32_e32 v4, s4, v10
	s_sub_i32 s6, s0, s3
	v_add_u32_e32 v6, 4, v4
	v_add_u32_e32 v14, 12, v4
	v_add_u32_e32 v16, 16, v4
	v_add_u32_e32 v18, 20, v4
	v_add_u32_e32 v20, 24, v4
	v_add_u32_e32 v22, 28, v4
	v_add_u32_e32 v24, 32, v4
	v_add_u32_e32 v26, 36, v4
	s_ashr_i32 s7, s6, 31
	v_ashrrev_i32_e32 v5, 31, v4
	v_add_u32_e32 v8, 8, v4
	v_add_u32_e32 v28, 40, v4
	v_add_u32_e32 v30, 44, v4
	v_add_u32_e32 v32, 48, v4
	v_add_u32_e32 v34, 52, v4
	v_add_u32_e32 v36, 56, v4
	v_add_u32_e32 v38, 60, v4
	v_add_u32_e32 v40, s6, v11
	v_ashrrev_i32_e32 v7, 31, v6
	v_ashrrev_i32_e32 v15, 31, v14
	v_ashrrev_i32_e32 v17, 31, v16
	v_ashrrev_i32_e32 v19, 31, v18
	v_ashrrev_i32_e32 v21, 31, v20
	v_ashrrev_i32_e32 v23, 31, v22
	v_ashrrev_i32_e32 v25, 31, v24
	v_ashrrev_i32_e32 v27, 31, v26
	s_ashr_i32 s5, s4, 31
	v_lshl_add_u64 v[42:43], s[6:7], 2, v[0:1]
	v_lshlrev_b64 v[4:5], 13, v[4:5]
	v_ashrrev_i32_e32 v9, 31, v8
	v_ashrrev_i32_e32 v29, 31, v28
	v_ashrrev_i32_e32 v31, 31, v30
	v_ashrrev_i32_e32 v33, 31, v32
	v_ashrrev_i32_e32 v35, 31, v34
	v_ashrrev_i32_e32 v37, 31, v36
	v_ashrrev_i32_e32 v39, 31, v38
	v_ashrrev_i32_e32 v41, 31, v40
	v_add_u32_e32 v44, 8, v40
	v_add_u32_e32 v46, 16, v40
	v_add_u32_e32 v48, 24, v40
	v_add_u32_e32 v50, 32, v40
	v_add_u32_e32 v52, 40, v40
	v_add_u32_e32 v54, 48, v40
	v_add_u32_e32 v56, 56, v40
	v_lshlrev_b64 v[58:59], 13, v[6:7]
	v_lshlrev_b64 v[14:15], 13, v[14:15]
	v_lshlrev_b64 v[16:17], 13, v[16:17]
	v_lshlrev_b64 v[18:19], 13, v[18:19]
	v_lshlrev_b64 v[20:21], 13, v[20:21]
	v_lshlrev_b64 v[22:23], 13, v[22:23]
	v_lshlrev_b64 v[24:25], 13, v[24:25]
	v_lshlrev_b64 v[26:27], 13, v[26:27]
	v_lshl_add_u64 v[74:75], s[4:5], 1, v[2:3]
	v_lshl_add_u64 v[4:5], v[42:43], 0, v[4:5]
	v_lshlrev_b64 v[8:9], 13, v[8:9]
	v_lshlrev_b64 v[28:29], 13, v[28:29]
	v_lshlrev_b64 v[30:31], 13, v[30:31]
	v_lshlrev_b64 v[32:33], 13, v[32:33]
	v_lshlrev_b64 v[34:35], 13, v[34:35]
	v_lshlrev_b64 v[36:37], 13, v[36:37]
	v_lshlrev_b64 v[38:39], 13, v[38:39]
	v_lshlrev_b64 v[40:41], 14, v[40:41]
	v_ashrrev_i32_e32 v45, 31, v44
	v_ashrrev_i32_e32 v47, 31, v46
	v_ashrrev_i32_e32 v49, 31, v48
	v_ashrrev_i32_e32 v51, 31, v50
	v_ashrrev_i32_e32 v53, 31, v52
	v_ashrrev_i32_e32 v55, 31, v54
	v_ashrrev_i32_e32 v57, 31, v56
	v_lshl_add_u64 v[58:59], v[42:43], 0, v[58:59]
	v_lshl_add_u64 v[60:61], v[42:43], 0, v[14:15]
	v_lshl_add_u64 v[62:63], v[42:43], 0, v[16:17]
	v_lshl_add_u64 v[64:65], v[42:43], 0, v[18:19]
	v_lshl_add_u64 v[66:67], v[42:43], 0, v[20:21]
	v_lshl_add_u64 v[68:69], v[42:43], 0, v[22:23]
	v_lshl_add_u64 v[70:71], v[42:43], 0, v[24:25]
	v_lshl_add_u64 v[72:73], v[42:43], 0, v[26:27]
	global_load_dwordx4 v[4:7], v[4:5], off nt
	v_lshl_add_u64 v[8:9], v[42:43], 0, v[8:9]
	v_lshl_add_u64 v[76:77], v[42:43], 0, v[28:29]
	v_lshl_add_u64 v[78:79], v[42:43], 0, v[30:31]
	v_lshl_add_u64 v[80:81], v[42:43], 0, v[32:33]
	v_lshl_add_u64 v[82:83], v[42:43], 0, v[34:35]
	v_lshl_add_u64 v[84:85], v[42:43], 0, v[36:37]
	v_lshl_add_u64 v[86:87], v[42:43], 0, v[38:39]
	v_lshl_add_u64 v[88:89], v[74:75], 0, v[40:41]
	v_lshlrev_b64 v[90:91], 14, v[44:45]
	v_lshlrev_b64 v[92:93], 14, v[46:47]
	v_lshlrev_b64 v[94:95], 14, v[48:49]
	v_lshlrev_b64 v[96:97], 14, v[50:51]
	v_lshlrev_b64 v[98:99], 14, v[52:53]
	v_lshlrev_b64 v[100:101], 14, v[54:55]
	v_lshlrev_b64 v[102:103], 14, v[56:57]
	global_load_dwordx4 v[14:17], v[58:59], off nt
	global_load_dwordx4 v[18:21], v[8:9], off nt
	global_load_dwordx4 v[22:25], v[60:61], off nt
	global_load_dwordx4 v[26:29], v[62:63], off nt
	global_load_dwordx4 v[30:33], v[64:65], off nt
	global_load_dwordx4 v[34:37], v[66:67], off nt
	global_load_dwordx4 v[38:41], v[68:69], off nt
	global_load_dwordx4 v[42:45], v[70:71], off nt
	global_load_dwordx4 v[46:49], v[72:73], off nt
	global_load_dwordx4 v[50:53], v[76:77], off nt
	global_load_dwordx4 v[54:57], v[78:79], off nt
	global_load_dwordx4 v[58:61], v[80:81], off nt
	global_load_dwordx4 v[62:65], v[82:83], off nt
	global_load_dwordx4 v[66:69], v[84:85], off nt
	global_load_dwordx4 v[70:73], v[86:87], off nt
	v_add_u32_e32 v104, 0x410, v13
	v_add_u32_e32 v105, 0x418, v13
	v_add_u32_e32 v106, 0x820, v13
	v_add_u32_e32 v107, 0x828, v13
	v_add_u32_e32 v108, 0xc30, v13
	v_add_u32_e32 v109, 0xc38, v13
	v_add_u32_e32 v110, 0x1040, v13
	v_add_u32_e32 v111, 0x1048, v13
	v_add_u32_e32 v112, 0x1450, v13
	v_add_u32_e32 v113, 0x1458, v13
	v_add_u32_e32 v114, 0x1860, v13
	v_add_u32_e32 v115, 0x1868, v13
	v_add_u32_e32 v116, 0x1c70, v13
	v_add_u32_e32 v117, 0x1c78, v13
	v_add_u32_e32 v118, 0x2080, v13
	v_add_u32_e32 v119, 0x2088, v13
	v_add_u32_e32 v120, 0x2490, v13
	v_add_u32_e32 v121, 0x2498, v13
	v_add_u32_e32 v122, 0x28a0, v13
	v_add_u32_e32 v123, 0x28a8, v13
	v_add_u32_e32 v124, 0x2cb0, v13
	v_add_u32_e32 v125, 0x2cb8, v13
	v_add_u32_e32 v126, 0x30c0, v13
	v_add_u32_e32 v127, 0x30c8, v13
	v_add_u32_e32 v128, 0x34d0, v13
	v_add_u32_e32 v129, 0x34d8, v13
	v_add_u32_e32 v130, 0x38e0, v13
	v_add_u32_e32 v131, 0x38e8, v13
	v_add_u32_e32 v132, 0x3cf0, v13
	v_add_u32_e32 v133, 0x3cf8, v13
	s_waitcnt vmcnt(15)
	ds_write2_b32 v13, v4, v5 offset1:1
	ds_write2_b32 v13, v6, v7 offset0:2 offset1:3
	s_waitcnt vmcnt(14)
; #define LAS __attribute__((address_space(3)))
; __device__ __forceinline__ void lds_wait() { asm volatile("s_waitcnt lgkmcnt(0)" ::: "memory"); }
; __device__ __forceinline__ void transpose_item(const float* W, int K, int N, bf16_t* WT, int gate, const float* kscale, LAS float* scr, int item, int lane) {
;     ...
;     for (int i = 0; i < 16; ++i) { LAS float* d = scr + (4 * i + kr) * 65 + c4; d[0] = v[i][0]; d[1] = v[i][1]; d[2] = v[i][2]; d[3] = v[i][3]; }
;     lds_wait();
;     const int c = lane & 7;
;     f32x4 k0v = {1.f, 1.f, 1.f, 1.f}, k1v = k0v;
;     if (kscale) { k0v = *(const f32x4*)(kscale + k0 + 8 * c); k1v = *(const f32x4*)(kscale + k0 + 8 * c + 4); }
; #pragma unroll
;     for (int j = 0; j < 8; ++j) { const int n = (lane >> 3) + 8 * j; const LAS float* s = scr + (8 * c) * 65 + n;
;         u32x4 o; o.x = pk2(s[0 * 65] * k0v[0], s[1 * 65] * k0v[1]); o.y = pk2(s[2 * 65] * k0v[2], s[3 * 65] * k0v[3]); o.z = pk2(s[4 * 65] * k1v[0], s[5 * 65] * k1v[1]); o.w = pk2(s[6 * 65] * k1v[2], s[7 * 65] * k1v[3]);
;         const int nn = n0 + n; const int row = gate < 0 ? nn : (256 * (nn >> 7) + 128 * gate + (nn & 127));
;         *(u32x4*)(WT + (size_t)row * K + k0 + 8 * c) = o; }
;     lds_wait();
	ds_write2_b32 v104, v14, v15 offset1:1
	ds_write2_b32 v105, v16, v17 offset1:1
	s_waitcnt vmcnt(13)
	ds_write2_b32 v106, v18, v19 offset1:1
	ds_write2_b32 v107, v20, v21 offset1:1
	s_waitcnt vmcnt(12)
	ds_write2_b32 v108, v22, v23 offset1:1
	ds_write2_b32 v109, v24, v25 offset1:1
	s_waitcnt vmcnt(11)
	ds_write2_b32 v110, v26, v27 offset1:1
	ds_write2_b32 v111, v28, v29 offset1:1
	s_waitcnt vmcnt(10)
	ds_write2_b32 v112, v30, v31 offset1:1
	ds_write2_b32 v113, v32, v33 offset1:1
	s_waitcnt vmcnt(9)
	ds_write2_b32 v114, v34, v35 offset1:1
	ds_write2_b32 v115, v36, v37 offset1:1
	s_waitcnt vmcnt(8)
	ds_write2_b32 v116, v38, v39 offset1:1
	ds_write2_b32 v117, v40, v41 offset1:1
	s_waitcnt vmcnt(7)
	ds_write2_b32 v118, v42, v43 offset1:1
	ds_write2_b32 v119, v44, v45 offset1:1
	s_waitcnt vmcnt(6)
	ds_write2_b32 v120, v46, v47 offset1:1
	ds_write2_b32 v121, v48, v49 offset1:1
	s_waitcnt vmcnt(5)
	ds_write2_b32 v122, v50, v51 offset1:1
	ds_write2_b32 v123, v52, v53 offset1:1
	s_waitcnt vmcnt(4)
	ds_write2_b32 v124, v54, v55 offset1:1
	ds_write2_b32 v125, v56, v57 offset1:1
	s_waitcnt vmcnt(3)
	ds_write2_b32 v126, v58, v59 offset1:1
	ds_write2_b32 v127, v60, v61 offset1:1
	s_waitcnt vmcnt(2)
	ds_write2_b32 v128, v62, v63 offset1:1
	ds_write2_b32 v129, v64, v65 offset1:1
	s_waitcnt vmcnt(1)
	ds_write2_b32 v130, v66, v67 offset1:1
	ds_write2_b32 v131, v68, v69 offset1:1
	s_waitcnt vmcnt(0)
	ds_write2_b32 v132, v70, v71 offset1:1
	ds_write2_b32 v133, v72, v73 offset1:1
	s_waitcnt lgkmcnt(0)
	v_add_u32_e32 v134, 0x400, v12
	v_lshl_add_u64 v[8:9], v[74:75], 0, v[90:91]
	ds_read2_b32 v[14:15], v12 offset0:65 offset1:73
	ds_read2_b32 v[16:17], v12 offset1:8
	ds_read2_b32 v[18:19], v12 offset0:130 offset1:138
	ds_read2_b32 v[20:21], v12 offset0:195 offset1:203
	ds_read2_b32 v[22:23], v134 offset0:4 offset1:12
	ds_read2_b32 v[24:25], v134 offset0:69 offset1:77
	ds_read2_b32 v[26:27], v134 offset0:134 offset1:142
	ds_read2_b32 v[28:29], v134 offset0:199 offset1:207
	ds_read2_b32 v[30:31], v12 offset0:81 offset1:89
	ds_read2_b32 v[32:33], v12 offset0:16 offset1:24
	ds_read2_b32 v[34:35], v12 offset0:146 offset1:154
	ds_read2_b32 v[36:37], v12 offset0:211 offset1:219
	ds_read2_b32 v[38:39], v134 offset0:20 offset1:28
	ds_read2_b32 v[40:41], v134 offset0:85 offset1:93
	ds_read2_b32 v[42:43], v134 offset0:150 offset1:158
	ds_read2_b32 v[44:45], v134 offset0:215 offset1:223
	ds_read2_b32 v[46:47], v12 offset0:32 offset1:40
	ds_read2_b32 v[48:49], v12 offset0:97 offset1:105
	ds_read2_b32 v[50:51], v12 offset0:162 offset1:170
	ds_read2_b32 v[52:53], v12 offset0:227 offset1:235
	ds_read2_b32 v[54:55], v134 offset0:36 offset1:44
	ds_read2_b32 v[56:57], v134 offset0:101 offset1:109
	ds_read2_b32 v[58:59], v134 offset0:166 offset1:174
	ds_read2_b32 v[60:61], v134 offset0:231 offset1:239
	ds_read2_b32 v[62:63], v12 offset0:48 offset1:56
	ds_read2_b32 v[64:65], v12 offset0:113 offset1:121
	ds_read2_b32 v[66:67], v12 offset0:178 offset1:186
	ds_read2_b32 v[68:69], v12 offset0:243 offset1:251
	ds_read2_b32 v[70:71], v134 offset0:52 offset1:60
	ds_read2_b32 v[72:73], v134 offset0:117 offset1:125
	ds_read2_b32 v[86:87], v134 offset0:182 offset1:190
	ds_read2_b32 v[90:91], v134 offset0:247 offset1:255
	s_waitcnt lgkmcnt(14)
	v_cvt_pk_bf16_f32 v4, v16, v14
	v_cvt_pk_bf16_f32 v5, v18, v20
	v_cvt_pk_bf16_f32 v6, v22, v24
	v_cvt_pk_bf16_f32 v7, v26, v28
	v_lshl_add_u64 v[76:77], v[74:75], 0, v[92:93]
	v_lshl_add_u64 v[78:79], v[74:75], 0, v[94:95]
	v_lshl_add_u64 v[80:81], v[74:75], 0, v[96:97]
	v_lshl_add_u64 v[82:83], v[74:75], 0, v[98:99]
	v_lshl_add_u64 v[84:85], v[74:75], 0, v[100:101]
	v_lshl_add_u64 v[74:75], v[74:75], 0, v[102:103]
	v_cvt_pk_bf16_f32 v14, v17, v15
	v_cvt_pk_bf16_f32 v15, v19, v21
	v_cvt_pk_bf16_f32 v16, v23, v25
	v_cvt_pk_bf16_f32 v17, v27, v29
	v_cvt_pk_bf16_f32 v18, v32, v30
	v_cvt_pk_bf16_f32 v19, v34, v36
	v_cvt_pk_bf16_f32 v20, v38, v40
	v_cvt_pk_bf16_f32 v21, v42, v44
	v_cvt_pk_bf16_f32 v22, v33, v31
	v_cvt_pk_bf16_f32 v23, v35, v37
	v_cvt_pk_bf16_f32 v24, v39, v41
	v_cvt_pk_bf16_f32 v25, v43, v45
	v_cvt_pk_bf16_f32 v26, v46, v48
	s_waitcnt lgkmcnt(12)
	v_cvt_pk_bf16_f32 v27, v50, v52
	s_waitcnt lgkmcnt(10)
	v_cvt_pk_bf16_f32 v28, v54, v56
	s_waitcnt lgkmcnt(8)
	v_cvt_pk_bf16_f32 v29, v58, v60
	v_cvt_pk_bf16_f32 v30, v47, v49
	v_cvt_pk_bf16_f32 v31, v51, v53
	v_cvt_pk_bf16_f32 v32, v55, v57
	v_cvt_pk_bf16_f32 v33, v59, v61
	s_waitcnt lgkmcnt(6)
	v_cvt_pk_bf16_f32 v34, v62, v64
	s_waitcnt lgkmcnt(4)
	v_cvt_pk_bf16_f32 v35, v66, v68
	s_waitcnt lgkmcnt(2)
	v_cvt_pk_bf16_f32 v36, v70, v72
	s_waitcnt lgkmcnt(0)
	v_cvt_pk_bf16_f32 v37, v86, v90
	v_cvt_pk_bf16_f32 v38, v63, v65
	v_cvt_pk_bf16_f32 v39, v67, v69
	v_cvt_pk_bf16_f32 v40, v71, v73
	v_cvt_pk_bf16_f32 v41, v87, v91
	global_store_dwordx4 v[88:89], v[4:7], off nt
	global_store_dwordx4 v[8:9], v[14:17], off nt
	global_store_dwordx4 v[76:77], v[18:21], off nt
	global_store_dwordx4 v[78:79], v[22:25], off nt
	global_store_dwordx4 v[80:81], v[26:29], off nt
	global_store_dwordx4 v[82:83], v[30:33], off nt
	global_store_dwordx4 v[84:85], v[34:37], off nt
	global_store_dwordx4 v[74:75], v[38:41], off nt
	s_waitcnt lgkmcnt(0)
	s_add_i32 s1, s1, s92
	s_add_i32 s0, s0, s38
	s_cmpk_lt_i32 s1, 0x1000
	s_cbranch_scc1 .LBB0_819
	s_branch .LBB0_821
